# attention phase: one static s_setprio 1 for waves 4-7, the 88 per-burst priority toggles deleted
# speedup vs baseline: 1.0055x; 1.0055x over previous
; __global__ void __launch_bounds__(512, 2) fwd_kernel(Args a) {
;     ...
;     if (IN(2)) {
;         AttnP P; P.QA = (const bf16_t*)(ws + WS_QA); P.KA = (const bf16_t*)(ws + WS_KA); P.VAT = (const bf16_t*)(ws + WS_VAT); P.ZA = (const bf16_t*)(ws + WS_ZA);
;         P.QB = (const bf16_t*)(ws + WS_QB); P.KB = (const bf16_t*)(ws + WS_KB); P.VBT = (const bf16_t*)(ws + WS_VBT); P.ZB = (const bf16_t*)(ws + WS_ZB);
;         P.Y = (bf16_t*)(ws + WS_Y); P.sink = a.in[9]; P.rpb = a.in[6];
;         float shiftA, shiftB; bool fast;
;         { float mqa = fabsf(a.in[4][lane]), mka = fabsf(a.in[5][lane]), mqb = fabsf(a.in[7][lane]), mkb = fabsf(a.in[8][lane]), msk = fabsf(a.in[9][lane & 7]), mr = 0.f;
;           for (int i = tid; i < 8 * 465; i += 512) mr = fmaxf(mr, fabsf(a.in[6][i]));
.LBB0_266:
	s_cmp_lt_i32 s66, 3
	s_cselect_b64 s[4:5], -1, 0
	s_and_b64 s[72:73], s[4:5], s[0:1]
	s_andn2_b64 vcc, exec, s[72:73]
	s_cbranch_vccnz .LBB0_427
	v_readfirstlane_b32 s100, v190
	s_nop 0
	s_cmp_lt_u32 s100, 0x100
	s_cbranch_scc1 .Lpbprio_lo
	s_setprio 1
.Lpbprio_lo:
	s_load_dwordx8 s[4:11], s[74:75], 0x40
	s_waitcnt vmcnt(0)
	v_lshlrev_b32_e32 v0, 2, v191
	s_waitcnt lgkmcnt(0)
	global_load_dword v6, v0, s[84:85]
	global_load_dword v5, v0, s[86:87]
	global_load_dword v3, v0, s[90:91]
	v_lshlrev_b32_e32 v152, 2, v190
	v_mov_b32_e32 v153, 0
	global_load_dword v2, v0, s[4:5]
	v_and_b32_e32 v0, 7, v190
	v_lshlrev_b32_e32 v0, 2, v0
	global_load_dword v4, v0, s[6:7]
	v_add_u32_e32 v7, 0xfffffe00, v190
	v_lshl_add_u64 v[0:1], s[88:89], 0, v[152:153]
	s_mov_b64 s[0:1], 0
	s_mov_b64 s[4:5], 0x800
	s_movk_i32 s6, 0xc87

; #define LAS __attribute__((address_space(3)))
; template <bool SWA, bool FAST>
; __device__ __forceinline__ void att_tile(const AttnP& P, LAS unsigned char* lds, int lane, int tb, int qpos0, int hq, int kloc0, int r, int ct, int kr0, int kc0, const AttQZ& qz, float shift) {
;     ...
;     const int krow0 = (SWA ? kloc0 : kc0) + li, ksw = (krow0 >> 1) & 7;
;     const LAS unsigned char* kb0 = lds + krow0 * 128 + ((fq ^ ksw) << 4);
;     const LAS unsigned char* kb1 = lds + krow0 * 128 + (((fq + 4) ^ ksw) << 4);
; #pragma unroll
;     for (int s0 = 0; s0 < NSEG; s0 += GS) {
;         bf16x8 kf[GS][2][2];
; #pragma unroll
;         for (int g = 0; g < GS; ++g)
; #pragma unroll
;             for (int kt = 0; kt < 2; ++kt) { const int s = s0 + g;
;                 const int segoff = SWA ? (32 * s + 16 * kt) * 128 : (((kr0 + s) % 9) * 64 + 16 * kt) * 128;
;                 kf[g][kt][0] = *(const LAS bf16x8*)(kb0 + segoff); kf[g][kt][1] = *(const LAS bf16x8*)(kb1 + segoff); }
;         __builtin_amdgcn_sched_barrier(0);
;         __builtin_amdgcn_s_setprio(1);
; #pragma unroll
;         for (int g = 0; g < GS; ++g)
; #pragma unroll
;             for (int kt = 0; kt < 2; ++kt) {
;                 f32x4 z = FAST ? (f32x4){-shift, -shift, -shift, -shift} : (f32x4){0.f, 0.f, 0.f, 0.f};
;                 z = __builtin_amdgcn_mfma_f32_16x16x32_bf16(kf[g][kt][0], bq0, z, 0, 0, 0);
;                 z = __builtin_amdgcn_mfma_f32_16x16x32_bf16(kf[g][kt][1], bq1, z, 0, 0, 0);
;                 sc[s0 + g][kt] = z; }
;         __builtin_amdgcn_s_setprio(0);
;         __builtin_amdgcn_sched_barrier(0);
.LBB0_315:
	s_add_i32 s60, s60, s33
	s_max_i32 s0, s60, 4
	s_add_i32 s0, s0, -4
	s_min_u32 s61, s0, 56
	s_mul_i32 s68, s61, 57
	s_lshr_b32 s0, s68, 9
	s_mul_i32 s0, s0, 9
	s_sub_i32 s0, s61, s0
	s_and_b32 s0, s0, 0xff
	s_lshl_b32 s58, s0, 13
	s_add_i32 s0, s68, 57
	s_bfe_u32 s0, s0, 0x40009
	s_mul_i32 s0, s0, 9
	s_sub_i32 s0, s61, s0
	s_add_i32 s0, s0, 1
	s_and_b32 s0, s0, 0xff
	s_lshl_b32 s57, s0, 13
	s_add_i32 s0, s68, 0x72
	v_add_u16_e32 v109, s59, v168
	s_bfe_u32 s0, s0, 0x40009
	v_add_u32_e32 v108, s59, v168
	v_lshrrev_b16_e32 v109, 1, v109
	s_mul_i32 s0, s0, 9
	v_lshl_add_u32 v108, v108, 7, 0
	v_bitop3_b32 v110, v109, v183, 7 bitop3:0x6c
	s_sub_i32 s0, s61, s0
	v_lshl_add_u32 v163, v110, 4, v108
	v_bitop3_b32 v109, v109, v170, 7 bitop3:0x6c
	s_add_i32 s0, s0, 2
	v_lshl_add_u32 v161, v109, 4, v108
	v_add_u32_e32 v108, s58, v163
	s_and_b32 s0, s0, 0xff
	v_add_u32_e32 v109, s58, v161
	ds_read_b128 v[112:115], v108
	ds_read_b128 v[116:119], v108 offset:2048
	ds_read_b128 v[124:127], v109
	ds_read_b128 v[120:123], v109 offset:2048
	v_add_u32_e32 v108, s57, v163
	s_lshl_b32 s56, s0, 13
	s_add_i32 s0, s68, 0xab
	v_add_u32_e32 v109, s57, v161
	ds_read_b128 v[128:131], v108
	ds_read_b128 v[132:135], v108 offset:2048
	ds_read_b128 v[140:143], v109
	ds_read_b128 v[136:139], v109 offset:2048
	s_bfe_u32 s0, s0, 0x40009
	s_mul_i32 s0, s0, 9
	s_sub_i32 s0, s61, s0
	s_add_i32 s0, s0, 3
	s_and_b32 s0, s0, 0xff
	s_lshl_b32 s55, s0, 13
	v_add_u32_e32 v156, s59, v173
	s_and_b32 s53, s12, 0xfffff000
	s_lshl_b32 s54, s60, 6
	v_add_u32_e32 v194, s56, v163
	v_add_u32_e32 v193, s56, v161
	v_add_u32_e32 v151, s55, v163
	v_add_u32_e32 v150, s55, v161
	v_sub_u32_e32 v192, v156, v171
	s_mov_b64 s[0:1], exec
	v_readlane_b32 s10, v249, 9
	v_readlane_b32 s11, v249, 10
	s_and_b64 s[10:11], s[0:1], s[10:11]
	s_xor_b64 s[40:41], s[10:11], s[0:1]
	s_mov_b64 exec, s[10:11]
	s_cbranch_execz .LBB0_317
	s_waitcnt vmcnt(7) lgkmcnt(7)
	v_mfma_f32_16x16x32_bf16 v[108:111], v[112:115], v[104:107], 0
	s_waitcnt vmcnt(6) lgkmcnt(5)
	v_mfma_f32_16x16x32_bf16 v[196:199], v[124:127], v[100:103], v[108:111]
	v_mfma_f32_16x16x32_bf16 v[108:111], v[116:119], v[104:107], 0
	s_waitcnt lgkmcnt(4)
	v_mfma_f32_16x16x32_bf16 v[200:203], v[120:123], v[100:103], v[108:111]
	s_waitcnt lgkmcnt(3)
	v_mfma_f32_16x16x32_bf16 v[108:111], v[128:131], v[104:107], 0
	s_waitcnt lgkmcnt(1)
	v_mfma_f32_16x16x32_bf16 v[204:207], v[140:143], v[100:103], v[108:111]
	v_mfma_f32_16x16x32_bf16 v[108:111], v[132:135], v[104:107], 0
	s_waitcnt lgkmcnt(0)
	v_mfma_f32_16x16x32_bf16 v[208:211], v[136:139], v[100:103], v[108:111]
	s_nop 4
	ds_read_b128 v[108:111], v194
	ds_read_b128 v[112:115], v194 offset:2048
	ds_read_b128 v[116:119], v193
	ds_read_b128 v[120:123], v193 offset:2048
	ds_read_b128 v[124:127], v151
	ds_read_b128 v[128:131], v151 offset:2048
	ds_read_b128 v[132:135], v150
	ds_read_b128 v[136:139], v150 offset:2048
	s_waitcnt lgkmcnt(7)
	v_mfma_f32_16x16x32_bf16 v[108:111], v[108:111], v[104:107], 0
	s_waitcnt lgkmcnt(5)
	v_mfma_f32_16x16x32_bf16 v[148:151], v[116:119], v[100:103], v[108:111]
	v_mfma_f32_16x16x32_bf16 v[108:111], v[112:115], v[104:107], 0
	s_waitcnt lgkmcnt(4)
	v_mfma_f32_16x16x32_bf16 v[144:147], v[120:123], v[100:103], v[108:111]
	s_waitcnt lgkmcnt(3)
	v_mfma_f32_16x16x32_bf16 v[108:111], v[124:127], v[104:107], 0
	s_waitcnt lgkmcnt(1)
	v_mfma_f32_16x16x32_bf16 v[140:143], v[132:135], v[100:103], v[108:111]
	v_mfma_f32_16x16x32_bf16 v[108:111], v[128:131], v[104:107], 0
	s_waitcnt lgkmcnt(0)
	v_mfma_f32_16x16x32_bf16 v[132:135], v[136:139], v[100:103], v[108:111]
	s_add_i32 s0, s68, 0xe4
	s_bfe_u32 s0, s0, 0x40009
	s_mul_i32 s0, s0, 9
	s_sub_i32 s0, s61, s0
	s_add_i32 s0, s0, 4
	s_and_b32 s0, s0, 0xff
	s_lshl_b32 s71, s0, 13
	s_add_i32 s0, s68, 0x11d
	s_bfe_u32 s0, s0, 0x40009
	s_mul_i32 s0, s0, 9
	s_sub_i32 s0, s61, s0
	s_add_i32 s0, s0, 5
	s_and_b32 s0, s0, 0xff
	s_lshl_b32 s70, s0, 13
	v_add_u32_e32 v112, s71, v163
	v_add_u32_e32 v120, s71, v161
	v_add_u32_e32 v128, s70, v163
	ds_read_b128 v[108:111], v112
	ds_read_b128 v[112:115], v112 offset:2048
	ds_read_b128 v[116:119], v120
	ds_read_b128 v[120:123], v120 offset:2048
	v_add_u32_e32 v129, s70, v161
	ds_read_b128 v[124:127], v128
	ds_read_b128 v[212:215], v128 offset:2048
	ds_read_b128 v[216:219], v129
	ds_read_b128 v[220:223], v129 offset:2048
	s_waitcnt lgkmcnt(7)
	v_mfma_f32_16x16x32_bf16 v[108:111], v[108:111], v[104:107], 0
	s_waitcnt lgkmcnt(5)
	v_mfma_f32_16x16x32_bf16 v[136:139], v[116:119], v[100:103], v[108:111]
	v_mfma_f32_16x16x32_bf16 v[108:111], v[112:115], v[104:107], 0
	s_waitcnt lgkmcnt(4)
	v_mfma_f32_16x16x32_bf16 v[128:131], v[120:123], v[100:103], v[108:111]
	s_waitcnt lgkmcnt(3)
	v_mfma_f32_16x16x32_bf16 v[108:111], v[124:127], v[104:107], 0
	s_waitcnt lgkmcnt(1)
	v_mfma_f32_16x16x32_bf16 v[124:127], v[216:219], v[100:103], v[108:111]
	v_mfma_f32_16x16x32_bf16 v[108:111], v[212:215], v[104:107], 0
	s_waitcnt lgkmcnt(0)
	v_mfma_f32_16x16x32_bf16 v[116:119], v[220:223], v[100:103], v[108:111]
	s_add_i32 s0, s68, 0x156
	s_bfe_u32 s0, s0, 0x40009
	s_mul_i32 s0, s0, 9
	s_sub_i32 s0, s61, s0
	s_add_i32 s0, s0, 6
	s_and_b32 s0, s0, 0xff
	s_lshl_b32 s69, s0, 13
	s_add_i32 s0, s68, 0x18f
	s_bfe_u32 s0, s0, 0x40009
	s_mul_i32 s0, s0, 9
	s_sub_i32 s0, s61, s0
	s_add_i32 s0, s0, 7
	s_and_b32 s0, s0, 0xff
	s_lshl_b32 s38, s0, 13
	v_add_u32_e32 v112, s69, v163
	v_add_u32_e32 v163, s38, v163
	v_add_u32_e32 v193, s69, v161
	ds_read_b128 v[108:111], v112
	ds_read_b128 v[112:115], v112 offset:2048
	ds_read_b128 v[120:123], v193
	ds_read_b128 v[212:215], v193 offset:2048
	v_add_u32_e32 v161, s38, v161
	ds_read_b128 v[216:219], v163
	ds_read_b128 v[220:223], v163 offset:2048
	ds_read_b128 v[224:227], v161
	ds_read_b128 v[228:231], v161 offset:2048
	s_waitcnt lgkmcnt(7)
; #define LAS __attribute__((address_space(3)))
; template <bool SWA, bool FAST>
; __device__ __forceinline__ void att_tile(const AttnP& P, LAS unsigned char* lds, int lane, int tb, int qpos0, int hq, int kloc0, int r, int ct, int kr0, int kc0, const AttQZ& qz, float shift) {
;     ...
;                 z = __builtin_amdgcn_mfma_f32_16x16x32_bf16(kf[g][kt][0], bq0, z, 0, 0, 0);
;                 z = __builtin_amdgcn_mfma_f32_16x16x32_bf16(kf[g][kt][1], bq1, z, 0, 0, 0);
;                 sc[s0 + g][kt] = z; }
;         __builtin_amdgcn_s_setprio(0);
;         __builtin_amdgcn_sched_barrier(0);
;     ...
;         const int c = 16 * ct + li, cs = min(max(c - 8, 0), 48);
;         const LAS float* rp = (const LAS float*)(lds + ATT_RPB) + (kr0 - r + 7) * 64 + (kc0 + 4 * fq - c + 31);
; #pragma unroll
;         for (int s = 0; s < NSEG; ++s) {
;             float bias[2][4];
; #pragma unroll
;             for (int kt = 0; kt < 2; ++kt)
; #pragma unroll
;                 for (int j = 0; j < 4; ++j) bias[kt][j] = rp[s * 64 + 16 * kt + j];
; #pragma unroll
;             for (int kt = 0; kt < 2; ++kt)
; #pragma unroll
;                 for (int j = 0; j < 4; ++j) { const int kc = kc0 + 16 * kt + 4 * fq + j; const bool ok = (kc >= cs) && (kc < cs + 16);
;                     float t = sc[s][kt][j] + bias[kt][j]; asm volatile("" : "+v"(t));
;                     const float v = ok ? t : -1e30f; sc[s][kt][j] = v; if (!FAST) mx = fmaxf(mx, v); }
;         }
	v_mfma_f32_16x16x32_bf16 v[108:111], v[108:111], v[104:107], 0
	s_waitcnt lgkmcnt(5)
	v_mfma_f32_16x16x32_bf16 v[120:123], v[120:123], v[100:103], v[108:111]
	v_mfma_f32_16x16x32_bf16 v[108:111], v[112:115], v[104:107], 0
	s_waitcnt lgkmcnt(4)
	v_mfma_f32_16x16x32_bf16 v[112:115], v[212:215], v[100:103], v[108:111]
	s_waitcnt lgkmcnt(3)
	v_mfma_f32_16x16x32_bf16 v[108:111], v[216:219], v[104:107], 0
	s_waitcnt lgkmcnt(2)
	v_mfma_f32_16x16x32_bf16 v[104:107], v[220:223], v[104:107], 0
	s_waitcnt lgkmcnt(1)
	v_mfma_f32_16x16x32_bf16 v[108:111], v[224:227], v[100:103], v[108:111]
	s_waitcnt lgkmcnt(0)
	v_mfma_f32_16x16x32_bf16 v[100:103], v[228:231], v[100:103], v[104:107]
	s_sub_i32 s0, s61, s60
	s_lshl_b32 s0, s0, 8
	s_add_i32 s0, s0, 0
	s_add_i32 s0, s0, 0x24000
	v_lshl_add_u32 v161, v192, 2, s0
	v_add_u32_e32 v104, 0x77c, v161
	v_add_u32_e32 v105, 16, v156
	v_add_u32_e32 v106, 0x784, v161
	v_add_u32_e32 v194, 0x7c4, v161
	v_cmp_ge_u32_e64 s[12:13], v105, v172
	v_add_u32_e32 v163, 0x7bc, v161
	ds_read2_b32 v[104:105], v104 offset1:1
	ds_read2_b32 v[106:107], v106 offset1:1
	ds_read2_b32 v[192:193], v163 offset1:1
	ds_read2_b32 v[194:195], v194 offset1:1
	v_cmp_ge_u32_e32 vcc, v156, v172
	v_cmp_lt_u32_e64 s[0:1], v156, v174
	s_waitcnt lgkmcnt(3)
	v_add_f32_e32 v104, v196, v104
	s_and_b64 vcc, vcc, s[0:1]
	v_cndmask_b32_e32 v163, v187, v104, vcc
	v_or_b32_e32 v104, 1, v156
	v_cmp_ge_u32_e64 s[0:1], v104, v172
	v_cmp_lt_u32_e64 s[10:11], v104, v174
	v_add_f32_e32 v104, v197, v105
	v_or_b32_e32 v105, 2, v156
	s_and_b64 s[0:1], s[0:1], s[10:11]
	v_cmp_ge_u32_e64 s[10:11], v105, v172
	v_cmp_lt_u32_e64 s[16:17], v105, v174
	s_waitcnt lgkmcnt(2)
	v_add_f32_e32 v105, v198, v106
	s_and_b64 s[20:21], s[10:11], s[16:17]
	v_cndmask_b32_e64 v197, v187, v105, s[20:21]
	v_or_b32_e32 v105, 3, v156
	v_cmp_ge_u32_e64 s[10:11], v105, v172
	v_cmp_lt_u32_e64 s[16:17], v105, v174
	v_add_f32_e32 v105, v199, v107
	s_and_b64 s[10:11], s[10:11], s[16:17]
	v_cmp_lt_u32_e64 s[14:15], v156, v172
	v_cndmask_b32_e64 v198, v187, v105, s[10:11]
	s_waitcnt lgkmcnt(1)
	v_add_f32_e32 v105, v200, v192
	s_and_b64 s[12:13], s[12:13], s[14:15]
	v_cndmask_b32_e64 v199, v187, v105, s[12:13]
	v_add_u32_e32 v105, 17, v156
	v_cmp_ge_u32_e64 s[14:15], v105, v172
	v_cmp_lt_u32_e64 s[16:17], v105, v174
	v_add_f32_e32 v105, v201, v193
	s_and_b64 s[14:15], s[14:15], s[16:17]
	v_cndmask_b32_e64 v200, v187, v105, s[14:15]
	v_add_u32_e32 v105, 18, v156
	v_cmp_ge_u32_e64 s[16:17], v105, v172
	v_cmp_lt_u32_e64 s[18:19], v105, v174
	s_waitcnt lgkmcnt(0)
	v_add_f32_e32 v105, v202, v194
	s_and_b64 s[16:17], s[16:17], s[18:19]
	v_cndmask_b32_e64 v196, v187, v104, s[0:1]
	v_cndmask_b32_e64 v201, v187, v105, s[16:17]
	v_add_u32_e32 v105, 19, v156
	v_max3_f32 v104, v163, s49, v196
	v_cmp_ge_u32_e64 s[18:19], v105, v172
	v_cmp_lt_u32_e64 s[22:23], v105, v174
	v_max3_f32 v104, v104, v197, v198
	v_add_f32_e32 v105, v203, v195
	s_and_b64 s[18:19], s[18:19], s[22:23]
	v_max3_f32 v104, v104, v199, v200
	v_add_u32_e32 v106, 0x884, v161
	v_cndmask_b32_e64 v202, v187, v105, s[18:19]
	v_max3_f32 v203, v104, v201, v202
	v_add_u32_e32 v104, 0x87c, v161
	ds_read2_b32 v[104:105], v104 offset1:1
	v_add_u32_e32 v192, 0x8bc, v161
	v_add_u32_e32 v194, 0x8c4, v161
	ds_read2_b32 v[106:107], v106 offset1:1
	ds_read2_b32 v[192:193], v192 offset1:1
	ds_read2_b32 v[194:195], v194 offset1:1
	s_waitcnt lgkmcnt(3)
	v_add_f32_e32 v104, v204, v104
	s_nop 0
	v_cndmask_b32_e32 v204, v187, v104, vcc
	v_add_f32_e32 v104, v205, v105
	s_waitcnt lgkmcnt(2)
	v_add_f32_e32 v105, v206, v106
	v_add_u32_e32 v106, 0x984, v161
	v_cndmask_b32_e64 v205, v187, v104, s[0:1]
	v_max3_f32 v104, v203, v204, v205
	v_cndmask_b32_e64 v203, v187, v105, s[20:21]
	v_add_f32_e32 v105, v207, v107
	s_nop 0
	v_cndmask_b32_e64 v206, v187, v105, s[10:11]
	s_waitcnt lgkmcnt(1)
	v_add_f32_e32 v105, v208, v192
	v_max3_f32 v104, v104, v203, v206
	v_cndmask_b32_e64 v207, v187, v105, s[12:13]
	v_add_f32_e32 v105, v209, v193
	v_add_u32_e32 v192, 0x9bc, v161
	v_cndmask_b32_e64 v208, v187, v105, s[14:15]
	s_waitcnt lgkmcnt(0)
	v_add_f32_e32 v105, v210, v194
	v_max3_f32 v104, v104, v207, v208
	v_cndmask_b32_e64 v209, v187, v105, s[16:17]
	v_add_f32_e32 v105, v211, v195
	v_add_u32_e32 v194, 0x9c4, v161
	v_cndmask_b32_e64 v210, v187, v105, s[18:19]
	v_max3_f32 v211, v104, v209, v210
	v_add_u32_e32 v104, 0x97c, v161
	ds_read2_b32 v[104:105], v104 offset1:1
	ds_read2_b32 v[106:107], v106 offset1:1
	ds_read2_b32 v[192:193], v192 offset1:1
	ds_read2_b32 v[194:195], v194 offset1:1
	s_waitcnt lgkmcnt(3)
	v_add_f32_e32 v104, v148, v104
	s_nop 0
	v_cndmask_b32_e32 v148, v187, v104, vcc
	v_add_f32_e32 v104, v149, v105
	s_waitcnt lgkmcnt(2)
	v_add_f32_e32 v105, v150, v106
	v_add_u32_e32 v106, 0xa84, v161
	v_cndmask_b32_e64 v150, v187, v105, s[20:21]
	v_add_f32_e32 v105, v151, v107
	v_cndmask_b32_e64 v149, v187, v104, s[0:1]
	v_cndmask_b32_e64 v151, v187, v105, s[10:11]
	s_waitcnt lgkmcnt(1)
	v_add_f32_e32 v105, v144, v192
	v_max3_f32 v104, v211, v148, v149
	v_cndmask_b32_e64 v192, v187, v105, s[12:13]
	v_add_f32_e32 v105, v145, v193
	v_max3_f32 v104, v104, v150, v151
	v_cndmask_b32_e64 v193, v187, v105, s[14:15]
	s_waitcnt lgkmcnt(0)
	v_add_f32_e32 v105, v146, v194
	v_max3_f32 v104, v104, v192, v193
	v_cndmask_b32_e64 v194, v187, v105, s[16:17]
	v_add_f32_e32 v105, v147, v195
	v_add_u32_e32 v144, 0xabc, v161
	v_cndmask_b32_e64 v195, v187, v105, s[18:19]
	v_max3_f32 v211, v104, v194, v195
	v_add_u32_e32 v104, 0xa7c, v161
	ds_read2_b32 v[104:105], v104 offset1:1
	v_add_u32_e32 v146, 0xac4, v161
	ds_read2_b32 v[106:107], v106 offset1:1
	ds_read2_b32 v[144:145], v144 offset1:1
	ds_read2_b32 v[146:147], v146 offset1:1
	s_waitcnt lgkmcnt(3)
; #define LAS __attribute__((address_space(3)))
; template <bool SWA, bool FAST>
; __device__ __forceinline__ void att_tile(const AttnP& P, LAS unsigned char* lds, int lane, int tb, int qpos0, int hq, int kloc0, int r, int ct, int kr0, int kc0, const AttQZ& qz, float shift) {
;     ...
;     } else if (!FAST) {
;         const int c = 16 * ct + li, cs = min(max(c - 8, 0), 48);
;         const LAS float* rp = (const LAS float*)(lds + ATT_RPB) + (kr0 - r + 7) * 64 + (kc0 + 4 * fq - c + 31);
; #pragma unroll
;         for (int s = 0; s < NSEG; ++s) {
;             float bias[2][4];
; #pragma unroll
;             for (int kt = 0; kt < 2; ++kt)
; #pragma unroll
;                 for (int j = 0; j < 4; ++j) bias[kt][j] = rp[s * 64 + 16 * kt + j];
; #pragma unroll
;             for (int kt = 0; kt < 2; ++kt)
; #pragma unroll
;                 for (int j = 0; j < 4; ++j) { const int kc = kc0 + 16 * kt + 4 * fq + j; const bool ok = (kc >= cs) && (kc < cs + 16);
;                     float t = sc[s][kt][j] + bias[kt][j]; asm volatile("" : "+v"(t));
;                     const float v = ok ? t : -1e30f; sc[s][kt][j] = v; if (!FAST) mx = fmaxf(mx, v); }
;         }
;     }
;     if (!FAST) { mx = fmaxf(mx, __shfl_xor(mx, 16)); mx = fmaxf(mx, __shfl_xor(mx, 32)); }
	v_add_f32_e32 v104, v140, v104
	s_nop 0
	v_cndmask_b32_e32 v140, v187, v104, vcc
	v_add_f32_e32 v104, v141, v105
	s_waitcnt lgkmcnt(2)
	v_add_f32_e32 v105, v142, v106
	v_add_u32_e32 v106, 0xb84, v161
	v_cndmask_b32_e64 v142, v187, v105, s[20:21]
	v_add_f32_e32 v105, v143, v107
	v_cndmask_b32_e64 v141, v187, v104, s[0:1]
	v_cndmask_b32_e64 v143, v187, v105, s[10:11]
	s_waitcnt lgkmcnt(1)
	v_add_f32_e32 v105, v132, v144
	v_max3_f32 v104, v211, v140, v141
	v_cndmask_b32_e64 v144, v187, v105, s[12:13]
	v_add_f32_e32 v105, v133, v145
	v_max3_f32 v104, v104, v142, v143
	v_cndmask_b32_e64 v145, v187, v105, s[14:15]
	s_waitcnt lgkmcnt(0)
	v_add_f32_e32 v105, v134, v146
	v_max3_f32 v104, v104, v144, v145
	v_cndmask_b32_e64 v146, v187, v105, s[16:17]
	v_add_f32_e32 v105, v135, v147
	v_add_u32_e32 v132, 0xbbc, v161
	v_cndmask_b32_e64 v147, v187, v105, s[18:19]
	v_max3_f32 v211, v104, v146, v147
	v_add_u32_e32 v104, 0xb7c, v161
	ds_read2_b32 v[104:105], v104 offset1:1
	v_add_u32_e32 v134, 0xbc4, v161
	ds_read2_b32 v[106:107], v106 offset1:1
	ds_read2_b32 v[132:133], v132 offset1:1
	ds_read2_b32 v[134:135], v134 offset1:1
	s_waitcnt lgkmcnt(3)
	v_add_f32_e32 v104, v136, v104
	s_nop 0
	v_cndmask_b32_e32 v136, v187, v104, vcc
	v_add_f32_e32 v104, v137, v105
	s_waitcnt lgkmcnt(2)
	v_add_f32_e32 v105, v138, v106
	v_add_u32_e32 v106, 0xc84, v161
	v_cndmask_b32_e64 v138, v187, v105, s[20:21]
	v_add_f32_e32 v105, v139, v107
	v_cndmask_b32_e64 v137, v187, v104, s[0:1]
	v_cndmask_b32_e64 v139, v187, v105, s[10:11]
	s_waitcnt lgkmcnt(1)
	v_add_f32_e32 v105, v128, v132
	v_max3_f32 v104, v211, v136, v137
	v_cndmask_b32_e64 v132, v187, v105, s[12:13]
	v_add_f32_e32 v105, v129, v133
	v_max3_f32 v104, v104, v138, v139
	v_cndmask_b32_e64 v133, v187, v105, s[14:15]
	s_waitcnt lgkmcnt(0)
	v_add_f32_e32 v105, v130, v134
	v_max3_f32 v104, v104, v132, v133
	v_cndmask_b32_e64 v134, v187, v105, s[16:17]
	v_add_f32_e32 v105, v131, v135
	v_add_u32_e32 v128, 0xcbc, v161
	v_cndmask_b32_e64 v135, v187, v105, s[18:19]
	v_max3_f32 v211, v104, v134, v135
	v_add_u32_e32 v104, 0xc7c, v161
	ds_read2_b32 v[104:105], v104 offset1:1
	v_add_u32_e32 v130, 0xcc4, v161
	ds_read2_b32 v[106:107], v106 offset1:1
	ds_read2_b32 v[128:129], v128 offset1:1
	ds_read2_b32 v[130:131], v130 offset1:1
	s_waitcnt lgkmcnt(3)
	v_add_f32_e32 v104, v124, v104
	s_nop 0
	v_cndmask_b32_e32 v212, v187, v104, vcc
	v_add_f32_e32 v104, v125, v105
	s_waitcnt lgkmcnt(2)
	v_add_f32_e32 v105, v126, v106
	v_add_u32_e32 v106, 0xd84, v161
	v_cndmask_b32_e64 v213, v187, v104, s[0:1]
	v_max3_f32 v104, v211, v212, v213
	v_cndmask_b32_e64 v211, v187, v105, s[20:21]
	v_add_f32_e32 v105, v127, v107
	s_nop 0
	v_cndmask_b32_e64 v214, v187, v105, s[10:11]
	s_waitcnt lgkmcnt(1)
	v_add_f32_e32 v105, v116, v128
	v_max3_f32 v104, v104, v211, v214
	v_cndmask_b32_e64 v128, v187, v105, s[12:13]
	v_add_f32_e32 v105, v117, v129
	v_add_u32_e32 v116, 0xdbc, v161
	v_cndmask_b32_e64 v129, v187, v105, s[14:15]
	s_waitcnt lgkmcnt(0)
	v_add_f32_e32 v105, v118, v130
	v_max3_f32 v104, v104, v128, v129
	v_cndmask_b32_e64 v130, v187, v105, s[16:17]
	v_add_f32_e32 v105, v119, v131
	v_add_u32_e32 v118, 0xdc4, v161
	v_cndmask_b32_e64 v131, v187, v105, s[18:19]
	v_max3_f32 v124, v104, v130, v131
	v_add_u32_e32 v104, 0xd7c, v161
	ds_read2_b32 v[104:105], v104 offset1:1
	ds_read2_b32 v[106:107], v106 offset1:1
	ds_read2_b32 v[116:117], v116 offset1:1
	ds_read2_b32 v[118:119], v118 offset1:1
	s_waitcnt lgkmcnt(3)
	v_add_f32_e32 v104, v120, v104
	s_nop 0
	v_cndmask_b32_e32 v215, v187, v104, vcc
	v_add_f32_e32 v104, v121, v105
	s_waitcnt lgkmcnt(2)
	v_add_f32_e32 v105, v122, v106
	v_add_u32_e32 v106, 0xe84, v161
	v_cndmask_b32_e64 v217, v187, v105, s[20:21]
	v_add_f32_e32 v105, v123, v107
	v_cndmask_b32_e64 v216, v187, v104, s[0:1]
	v_cndmask_b32_e64 v218, v187, v105, s[10:11]
	s_waitcnt lgkmcnt(1)
	v_add_f32_e32 v105, v112, v116
	v_max3_f32 v104, v124, v215, v216
	v_cndmask_b32_e64 v219, v187, v105, s[12:13]
	v_add_f32_e32 v105, v113, v117
	v_max3_f32 v104, v104, v217, v218
	v_cndmask_b32_e64 v220, v187, v105, s[14:15]
	s_waitcnt lgkmcnt(0)
	v_add_f32_e32 v105, v114, v118
	v_max3_f32 v104, v104, v219, v220
	v_cndmask_b32_e64 v221, v187, v105, s[16:17]
	v_add_f32_e32 v105, v115, v119
	v_add_u32_e32 v112, 0xebc, v161
	v_cndmask_b32_e64 v222, v187, v105, s[18:19]
	v_max3_f32 v116, v104, v221, v222
	v_add_u32_e32 v104, 0xe7c, v161
	ds_read2_b32 v[104:105], v104 offset1:1
	v_add_u32_e32 v114, 0xec4, v161
	ds_read2_b32 v[106:107], v106 offset1:1
	ds_read2_b32 v[112:113], v112 offset1:1
	ds_read2_b32 v[114:115], v114 offset1:1
	s_waitcnt lgkmcnt(3)
	v_add_f32_e32 v104, v108, v104
	s_waitcnt lgkmcnt(1)
	v_add_f32_e32 v100, v100, v112
	v_cndmask_b32_e32 v161, v187, v104, vcc
	v_add_f32_e32 v104, v109, v105
	v_add_f32_e32 v105, v110, v106
	s_nop 0
	v_cndmask_b32_e64 v224, v187, v105, s[20:21]
	v_add_f32_e32 v105, v111, v107
	v_cndmask_b32_e64 v223, v187, v104, s[0:1]
	v_cndmask_b32_e64 v226, v187, v100, s[12:13]
	v_add_f32_e32 v100, v101, v113
	s_waitcnt lgkmcnt(0)
	v_add_f32_e32 v101, v102, v114
	v_max3_f32 v104, v116, v161, v223
	v_cndmask_b32_e64 v225, v187, v105, s[10:11]
	v_max3_f32 v104, v104, v224, v225
	v_cndmask_b32_e64 v227, v187, v100, s[14:15]
	v_cndmask_b32_e64 v228, v187, v101, s[16:17]
	v_add_f32_e32 v101, v103, v115
	v_max3_f32 v100, v104, v226, v227
	s_nop 0
	v_cndmask_b32_e64 v229, v187, v101, s[18:19]
	v_max3_f32 v100, v100, v228, v229
	ds_bpermute_b32 v101, v180, v100
	s_waitcnt lgkmcnt(0)
	v_max_f32_e32 v101, v101, v101
	v_max_f32_e32 v100, v100, v101
	ds_bpermute_b32 v101, v181, v100
	s_waitcnt lgkmcnt(0)
; __device__ __forceinline__ unsigned cvt_pk_bf16(float lo, float hi) { const f32x2_t v = {lo, hi}; const bf16x2_t r = __builtin_convertvector(v, bf16x2_t); return __builtin_bit_cast(unsigned, r); }
; template <bool SWA, bool FAST>
; __device__ __forceinline__ void att_tile(const AttnP& P, LAS unsigned char* lds, int lane, int tb, int qpos0, int hq, int kloc0, int r, int ct, int kr0, int kc0, const AttQZ& qz, float shift) {
;     ...
; #pragma unroll
;     for (int s = 0; s < NSEG; ++s) {
;         float p[8];
; #pragma unroll
;         for (int kt = 0; kt < 2; ++kt)
; #pragma unroll
;             for (int j = 0; j < 4; ++j) p[4 * kt + j] = __builtin_amdgcn_exp2f(FAST ? sc[s][kt][j] : sc[s][kt][j] - mx);
; #pragma unroll
;         for (int e = 0; e < 8; e += 2) l2 += (f32x2_t){p[e], p[e + 1]};
;         u32x4 w; w.x = cvt_pk_bf16(p[0], p[1]); w.y = cvt_pk_bf16(p[2], p[3]); w.z = cvt_pk_bf16(p[4], p[5]); w.w = cvt_pk_bf16(p[6], p[7]);
;         pb[s] = __builtin_bit_cast(bf16x8, w);
;     }
;     l += l2[0] + l2[1];
;     l += __shfl_xor(l, 16); l += __shfl_xor(l, 32);
	v_max_f32_e32 v101, v101, v101
	v_max_f32_e32 v230, v100, v101
	v_sub_f32_e32 v100, v163, v230
	v_sub_f32_e32 v101, v196, v230
	v_exp_f32_e32 v100, v100
	v_exp_f32_e32 v101, v101
	v_sub_f32_e32 v102, v197, v230
	v_sub_f32_e32 v103, v198, v230
	v_exp_f32_e32 v102, v102
	v_exp_f32_e32 v103, v103
	v_sub_f32_e32 v104, v199, v230
	v_sub_f32_e32 v105, v200, v230
	v_exp_f32_e32 v104, v104
	v_exp_f32_e32 v105, v105
	v_sub_f32_e32 v106, v201, v230
	v_sub_f32_e32 v107, v202, v230
	v_exp_f32_e32 v106, v106
	v_exp_f32_e32 v107, v107
	v_pk_add_f32 v[108:109], v[100:101], 0 op_sel_hi:[1,0]
	v_cvt_pk_bf16_f32 v110, v104, v105
	v_pk_add_f32 v[108:109], v[102:103], v[108:109]
	v_cvt_pk_bf16_f32 v111, v106, v107
	v_pk_add_f32 v[108:109], v[104:105], v[108:109]
	v_sub_f32_e32 v104, v207, v230
	v_pk_add_f32 v[112:113], v[106:107], v[108:109]
	v_cvt_pk_bf16_f32 v108, v100, v101
	v_sub_f32_e32 v100, v204, v230
	v_sub_f32_e32 v101, v205, v230
	v_cvt_pk_bf16_f32 v109, v102, v103
	v_exp_f32_e32 v100, v100
	v_exp_f32_e32 v101, v101
	v_sub_f32_e32 v102, v203, v230
	v_sub_f32_e32 v103, v206, v230
	v_exp_f32_e32 v102, v102
	v_exp_f32_e32 v103, v103
	v_sub_f32_e32 v105, v208, v230
	v_exp_f32_e32 v104, v104
	v_exp_f32_e32 v105, v105
	v_sub_f32_e32 v106, v209, v230
	v_sub_f32_e32 v107, v210, v230
	v_exp_f32_e32 v106, v106
	v_exp_f32_e32 v107, v107
	v_pk_add_f32 v[112:113], v[100:101], v[112:113]
	v_cvt_pk_bf16_f32 v124, v100, v101
	v_pk_add_f32 v[112:113], v[102:103], v[112:113]
	v_cvt_pk_bf16_f32 v126, v104, v105
	v_pk_add_f32 v[112:113], v[104:105], v[112:113]
	v_sub_f32_e32 v100, v148, v230
	v_sub_f32_e32 v101, v149, v230
	v_sub_f32_e32 v104, v192, v230
	v_pk_add_f32 v[112:113], v[106:107], v[112:113]
	v_cvt_pk_bf16_f32 v125, v102, v103
	v_cvt_pk_bf16_f32 v127, v106, v107
	v_exp_f32_e32 v100, v100
	v_exp_f32_e32 v101, v101
	v_sub_f32_e32 v102, v150, v230
	v_sub_f32_e32 v103, v151, v230
	v_exp_f32_e32 v106, v104
	v_sub_f32_e32 v104, v193, v230
	v_exp_f32_e32 v102, v102
	v_exp_f32_e32 v103, v103
	v_exp_f32_e32 v107, v104
	v_sub_f32_e32 v104, v194, v230
	v_exp_f32_e32 v114, v104
	v_sub_f32_e32 v104, v195, v230
	v_exp_f32_e32 v115, v104
	v_pk_add_f32 v[104:105], v[100:101], v[112:113]
	v_sub_f32_e32 v116, v146, v230
	v_pk_add_f32 v[104:105], v[102:103], v[104:105]
	v_exp_f32_e32 v120, v116
	v_pk_add_f32 v[104:105], v[106:107], v[104:105]
	v_cvt_pk_bf16_f32 v106, v106, v107
	v_pk_add_f32 v[112:113], v[114:115], v[104:105]
	v_cvt_pk_bf16_f32 v104, v100, v101
	v_sub_f32_e32 v100, v140, v230
	v_sub_f32_e32 v101, v141, v230
	v_cvt_pk_bf16_f32 v105, v102, v103
	v_exp_f32_e32 v100, v100
	v_exp_f32_e32 v101, v101
	v_sub_f32_e32 v102, v142, v230
	v_sub_f32_e32 v103, v143, v230
	v_cvt_pk_bf16_f32 v107, v114, v115
	v_exp_f32_e32 v102, v102
	v_exp_f32_e32 v103, v103
	v_sub_f32_e32 v114, v144, v230
	v_sub_f32_e32 v115, v145, v230
	v_exp_f32_e32 v114, v114
	v_exp_f32_e32 v115, v115
	v_sub_f32_e32 v116, v147, v230
	v_exp_f32_e32 v121, v116
	v_pk_add_f32 v[112:113], v[100:101], v[112:113]
	v_cvt_pk_bf16_f32 v116, v100, v101
	v_sub_f32_e32 v100, v136, v230
	v_sub_f32_e32 v101, v137, v230
	v_pk_add_f32 v[112:113], v[102:103], v[112:113]
	v_cvt_pk_bf16_f32 v117, v102, v103
	v_exp_f32_e32 v100, v100
	v_exp_f32_e32 v101, v101
	v_sub_f32_e32 v102, v138, v230
	v_sub_f32_e32 v103, v139, v230
	v_pk_add_f32 v[112:113], v[114:115], v[112:113]
	v_cvt_pk_bf16_f32 v118, v114, v115
	v_exp_f32_e32 v102, v102
	v_exp_f32_e32 v103, v103
	v_sub_f32_e32 v114, v132, v230
	v_sub_f32_e32 v115, v133, v230
	v_pk_add_f32 v[112:113], v[120:121], v[112:113]
	v_cvt_pk_bf16_f32 v119, v120, v121
	v_exp_f32_e32 v114, v114
	v_exp_f32_e32 v115, v115
	v_sub_f32_e32 v120, v134, v230
	v_sub_f32_e32 v121, v135, v230
	v_exp_f32_e32 v120, v120
	v_exp_f32_e32 v121, v121
	v_pk_add_f32 v[112:113], v[100:101], v[112:113]
	v_cvt_pk_bf16_f32 v100, v100, v101
	v_pk_add_f32 v[112:113], v[102:103], v[112:113]
	v_cvt_pk_bf16_f32 v101, v102, v103
	v_pk_add_f32 v[112:113], v[114:115], v[112:113]
	v_cvt_pk_bf16_f32 v102, v114, v115
	v_sub_f32_e32 v114, v212, v230
	v_sub_f32_e32 v115, v213, v230
	v_pk_add_f32 v[112:113], v[120:121], v[112:113]
	v_cvt_pk_bf16_f32 v103, v120, v121
	v_exp_f32_e32 v114, v114
	v_exp_f32_e32 v115, v115
	v_sub_f32_e32 v120, v211, v230
	v_sub_f32_e32 v121, v214, v230
	v_exp_f32_e32 v120, v120
	v_exp_f32_e32 v121, v121
	v_sub_f32_e32 v122, v128, v230
	v_sub_f32_e32 v123, v129, v230
	v_exp_f32_e32 v122, v122
	v_exp_f32_e32 v123, v123
	v_sub_f32_e32 v128, v130, v230
	v_sub_f32_e32 v129, v131, v230
	v_exp_f32_e32 v128, v128
	v_exp_f32_e32 v129, v129
	v_pk_add_f32 v[112:113], v[114:115], v[112:113]
	s_nop 0
	v_pk_add_f32 v[112:113], v[120:121], v[112:113]
	s_nop 0
	v_pk_add_f32 v[112:113], v[122:123], v[112:113]
	s_nop 0
	v_pk_add_f32 v[130:131], v[128:129], v[112:113]
	v_cvt_pk_bf16_f32 v113, v120, v121
	v_sub_f32_e32 v120, v215, v230
	v_sub_f32_e32 v121, v216, v230
	v_cvt_pk_bf16_f32 v112, v114, v115
	v_cvt_pk_bf16_f32 v115, v128, v129
	v_exp_f32_e32 v120, v120
	v_exp_f32_e32 v121, v121
	v_sub_f32_e32 v128, v219, v230
	v_exp_f32_e32 v132, v128
	v_sub_f32_e32 v128, v220, v230
	v_exp_f32_e32 v133, v128
	v_sub_f32_e32 v128, v221, v230
	v_exp_f32_e32 v134, v128
	v_sub_f32_e32 v128, v222, v230
	v_exp_f32_e32 v135, v128
	v_pk_add_f32 v[128:129], v[120:121], v[130:131]
	v_sub_f32_e32 v130, v161, v230
	v_cvt_pk_bf16_f32 v114, v122, v123
	v_sub_f32_e32 v122, v217, v230
	v_sub_f32_e32 v123, v218, v230
	v_exp_f32_e32 v136, v130
	v_sub_f32_e32 v130, v223, v230
	v_exp_f32_e32 v122, v122
	v_exp_f32_e32 v123, v123
	v_exp_f32_e32 v137, v130
	v_sub_f32_e32 v130, v224, v230
	v_exp_f32_e32 v138, v130
	v_sub_f32_e32 v130, v225, v230
	v_exp_f32_e32 v139, v130
	v_sub_f32_e32 v130, v226, v230
	v_exp_f32_e32 v140, v130
	v_sub_f32_e32 v130, v227, v230
	v_pk_add_f32 v[128:129], v[122:123], v[128:129]
	v_exp_f32_e32 v141, v130
	v_sub_f32_e32 v130, v228, v230
	v_pk_add_f32 v[128:129], v[132:133], v[128:129]
	v_exp_f32_e32 v142, v130
	v_sub_f32_e32 v130, v229, v230
	v_pk_add_f32 v[128:129], v[134:135], v[128:129]
	v_exp_f32_e32 v143, v130
	v_pk_add_f32 v[128:129], v[136:137], v[128:129]
	v_cvt_pk_bf16_f32 v130, v132, v133
	v_pk_add_f32 v[128:129], v[138:139], v[128:129]
	v_cvt_pk_bf16_f32 v131, v134, v135
	v_pk_add_f32 v[128:129], v[140:141], v[128:129]
	s_nop 0
	v_pk_add_f32 v[128:129], v[142:143], v[128:129]
	s_nop 0
	v_add_f32_e32 v128, v128, v129
	v_add_f32_e32 v144, 0, v128
	ds_bpermute_b32 v145, v180, v144
	v_cvt_pk_bf16_f32 v128, v120, v121
	v_cvt_pk_bf16_f32 v120, v136, v137
	v_cvt_pk_bf16_f32 v121, v138, v139
	v_cvt_pk_bf16_f32 v129, v122, v123
	s_waitcnt lgkmcnt(0)
; #define LAS __attribute__((address_space(3)))
; template <bool SWA, bool FAST>
; __device__ __forceinline__ void att_tile(const AttnP& P, LAS unsigned char* lds, int lane, int tb, int qpos0, int hq, int kloc0, int r, int ct, int kr0, int kc0, const AttQZ& qz, float shift) {
;     ...
;     l += __shfl_xor(l, 16); l += __shfl_xor(l, 32);
;     if (SWA) l += __builtin_amdgcn_exp2f(FAST ? sk - shift : sk - mx);
;     const float rl = 1.0f / l;
;     f32x4 oacc[4];
; #pragma unroll
;     for (int dt = 0; dt < 4; ++dt) oacc[dt] = (f32x4){0.f, 0.f, 0.f, 0.f};
;     constexpr int GV = SWA ? 3 : 2;
;     const int g0l = (SWA ? kloc0 : kc0) + 4 * fq;
;     const LAS unsigned char* vb0 = lds + ATT_VOFF + (g0l >> 3) * 1024 + li * 16 + (g0l & 7) * 2;
; #pragma unroll
;     for (int s0 = 0; s0 < NSEG; s0 += GV) {
;         u32x2 vf[GV][4][2];
; #pragma unroll
;         for (int g = 0; g < GV; ++g) { const int s = s0 + g;
;             const int segv = SWA ? s * 4096 : ((kr0 + s) % 9) * 8192;
; #pragma unroll
;             for (int dt = 0; dt < 4; ++dt) {
;                 vf[g][dt][0] = *(const LAS u32x2*)(vb0 + segv + dt * 256); asm volatile("" ::: "memory");
;                 vf[g][dt][1] = *(const LAS u32x2*)(vb0 + segv + dt * 256 + 2048); asm volatile("" ::: "memory"); } }
;         __builtin_amdgcn_sched_barrier(0);
;         __builtin_amdgcn_s_setprio(1);
; #pragma unroll
;         for (int g = 0; g < GV; ++g)
; #pragma unroll
;             for (int dt = 0; dt < 4; ++dt) {
;                 u32x4 w; w.x = vf[g][dt][0].x; w.y = vf[g][dt][0].y; w.z = vf[g][dt][1].x; w.w = vf[g][dt][1].y;
;                 oacc[dt] = __builtin_amdgcn_mfma_f32_16x16x32_bf16(__builtin_bit_cast(bf16x8, w), pb[s0 + g], oacc[dt], 0, 0, 0); }
;         __builtin_amdgcn_s_setprio(0);
;         __builtin_amdgcn_sched_barrier(0);
;     }
	v_add_f32_e32 v132, v144, v145
	ds_bpermute_b32 v133, v181, v132
	v_cvt_pk_bf16_f32 v122, v140, v141
	v_cvt_pk_bf16_f32 v123, v142, v143
	s_waitcnt lgkmcnt(0)
	v_add_f32_e32 v161, v132, v133
	v_lshlrev_b32_e32 v132, 7, v156
	v_lshlrev_b32_e32 v133, 1, v156
	v_and_b32_e32 v132, 0x3c00, v132
	v_and_b32_e32 v133, 8, v133
	v_add3_u32 v156, v175, v132, v133
	v_add_u32_e32 v146, s58, v156
	ds_read_b64 v[132:133], v146
	ds_read_b64 v[134:135], v146 offset:2048
	ds_read_b64 v[136:137], v146 offset:256
	ds_read_b64 v[138:139], v146 offset:2304
	ds_read_b64 v[140:141], v146 offset:512
	ds_read_b64 v[142:143], v146 offset:2560
	ds_read_b64 v[144:145], v146 offset:768
	ds_read_b64 v[146:147], v146 offset:2816
	v_add_u32_e32 v163, s57, v156
	ds_read_b64 v[148:149], v163
	ds_read_b64 v[150:151], v163 offset:2048
	ds_read_b64 v[192:193], v163 offset:256
	ds_read_b64 v[194:195], v163 offset:2304
	ds_read_b64 v[196:197], v163 offset:512
	ds_read_b64 v[198:199], v163 offset:2560
	ds_read_b64 v[200:201], v163 offset:768
	ds_read_b64 v[202:203], v163 offset:2816
	s_waitcnt lgkmcnt(14)
	v_mfma_f32_16x16x32_bf16 v[132:135], v[132:135], v[108:111], 0
	s_waitcnt lgkmcnt(12)
	v_mfma_f32_16x16x32_bf16 v[136:139], v[136:139], v[108:111], 0
	s_waitcnt lgkmcnt(10)
	v_mfma_f32_16x16x32_bf16 v[140:143], v[140:143], v[108:111], 0
	s_waitcnt lgkmcnt(8)
	v_mfma_f32_16x16x32_bf16 v[108:111], v[144:147], v[108:111], 0
	s_waitcnt lgkmcnt(6)
	v_mfma_f32_16x16x32_bf16 v[132:135], v[148:151], v[124:127], v[132:135]
	s_waitcnt lgkmcnt(4)
	v_mfma_f32_16x16x32_bf16 v[136:139], v[192:195], v[124:127], v[136:139]
	s_waitcnt lgkmcnt(2)
	v_mfma_f32_16x16x32_bf16 v[140:143], v[196:199], v[124:127], v[140:143]
	s_waitcnt lgkmcnt(0)
	v_mfma_f32_16x16x32_bf16 v[108:111], v[200:203], v[124:127], v[108:111]
	v_add_u32_e32 v163, s56, v156
	ds_read_b64 v[124:125], v163
	ds_read_b64 v[126:127], v163 offset:2048
	ds_read_b64 v[144:145], v163 offset:256
	ds_read_b64 v[146:147], v163 offset:2304
	ds_read_b64 v[148:149], v163 offset:512
	ds_read_b64 v[150:151], v163 offset:2560
	ds_read_b64 v[192:193], v163 offset:768
	ds_read_b64 v[194:195], v163 offset:2816
	v_add_u32_e32 v163, s55, v156
	ds_read_b64 v[196:197], v163
	ds_read_b64 v[198:199], v163 offset:2048
	ds_read_b64 v[200:201], v163 offset:256
	ds_read_b64 v[202:203], v163 offset:2304
	ds_read_b64 v[204:205], v163 offset:512
	ds_read_b64 v[206:207], v163 offset:2560
	ds_read_b64 v[208:209], v163 offset:768
	ds_read_b64 v[210:211], v163 offset:2816
	s_waitcnt lgkmcnt(14)
	v_mfma_f32_16x16x32_bf16 v[124:127], v[124:127], v[104:107], v[132:135]
	s_waitcnt lgkmcnt(12)
	v_mfma_f32_16x16x32_bf16 v[132:135], v[144:147], v[104:107], v[136:139]
	s_waitcnt lgkmcnt(10)
	v_mfma_f32_16x16x32_bf16 v[136:139], v[148:151], v[104:107], v[140:143]
	s_waitcnt lgkmcnt(8)
	v_mfma_f32_16x16x32_bf16 v[104:107], v[192:195], v[104:107], v[108:111]
	s_waitcnt lgkmcnt(6)
	v_mfma_f32_16x16x32_bf16 v[108:111], v[196:199], v[116:119], v[124:127]
	s_waitcnt lgkmcnt(4)
	v_mfma_f32_16x16x32_bf16 v[124:127], v[200:203], v[116:119], v[132:135]
	s_waitcnt lgkmcnt(2)
	v_mfma_f32_16x16x32_bf16 v[132:135], v[204:207], v[116:119], v[136:139]
	s_waitcnt lgkmcnt(0)
	v_mfma_f32_16x16x32_bf16 v[104:107], v[208:211], v[116:119], v[104:107]
	v_add_u32_e32 v146, s71, v156
	ds_read_b64 v[116:117], v146
	ds_read_b64 v[118:119], v146 offset:2048
	ds_read_b64 v[136:137], v146 offset:256
	ds_read_b64 v[138:139], v146 offset:2304
	ds_read_b64 v[140:141], v146 offset:512
	ds_read_b64 v[142:143], v146 offset:2560
	ds_read_b64 v[144:145], v146 offset:768
	ds_read_b64 v[146:147], v146 offset:2816
	v_add_u32_e32 v163, s70, v156
	ds_read_b64 v[148:149], v163
	ds_read_b64 v[150:151], v163 offset:2048
	ds_read_b64 v[192:193], v163 offset:256
	ds_read_b64 v[194:195], v163 offset:2304
	ds_read_b64 v[196:197], v163 offset:512
	ds_read_b64 v[198:199], v163 offset:2560
	ds_read_b64 v[200:201], v163 offset:768
	ds_read_b64 v[202:203], v163 offset:2816
	s_waitcnt lgkmcnt(14)
	v_mfma_f32_16x16x32_bf16 v[108:111], v[116:119], v[100:103], v[108:111]
	s_waitcnt lgkmcnt(12)
	v_mfma_f32_16x16x32_bf16 v[116:119], v[136:139], v[100:103], v[124:127]
	s_waitcnt lgkmcnt(10)
	v_mfma_f32_16x16x32_bf16 v[124:127], v[140:143], v[100:103], v[132:135]
	s_waitcnt lgkmcnt(8)
	v_mfma_f32_16x16x32_bf16 v[100:103], v[144:147], v[100:103], v[104:107]
	s_waitcnt lgkmcnt(6)
	v_mfma_f32_16x16x32_bf16 v[104:107], v[148:151], v[112:115], v[108:111]
	s_waitcnt lgkmcnt(4)
	v_mfma_f32_16x16x32_bf16 v[108:111], v[192:195], v[112:115], v[116:119]
	s_waitcnt lgkmcnt(2)
	v_mfma_f32_16x16x32_bf16 v[116:119], v[196:199], v[112:115], v[124:127]
	s_waitcnt lgkmcnt(0)
	v_mfma_f32_16x16x32_bf16 v[100:103], v[200:203], v[112:115], v[100:103]
	v_add_u32_e32 v138, s69, v156
	ds_read_b64 v[112:113], v138
	ds_read_b64 v[114:115], v138 offset:2048
	ds_read_b64 v[124:125], v138 offset:256
	ds_read_b64 v[126:127], v138 offset:2304
	ds_read_b64 v[132:133], v138 offset:512
	ds_read_b64 v[134:135], v138 offset:2560
	ds_read_b64 v[136:137], v138 offset:768
	ds_read_b64 v[138:139], v138 offset:2816
	v_add_u32_e32 v156, s38, v156
	ds_read_b64 v[140:141], v156
	ds_read_b64 v[142:143], v156 offset:2048
	ds_read_b64 v[144:145], v156 offset:256
	ds_read_b64 v[146:147], v156 offset:2304
	ds_read_b64 v[148:149], v156 offset:512
	ds_read_b64 v[150:151], v156 offset:2560
	ds_read_b64 v[192:193], v156 offset:768
	ds_read_b64 v[194:195], v156 offset:2816
	s_waitcnt lgkmcnt(14)
	v_mfma_f32_16x16x32_bf16 v[104:107], v[112:115], v[128:131], v[104:107]
	s_waitcnt lgkmcnt(12)
	v_mfma_f32_16x16x32_bf16 v[108:111], v[124:127], v[128:131], v[108:111]
	s_waitcnt lgkmcnt(10)
; template <bool SWA, bool FAST>
; __device__ __forceinline__ void att_tile(const AttnP& P, LAS unsigned char* lds, int lane, int tb, int qpos0, int hq, int kloc0, int r, int ct, int kr0, int kc0, const AttQZ& qz, float shift) {
;     ...
;     const int krow0 = (SWA ? kloc0 : kc0) + li, ksw = (krow0 >> 1) & 7;
;     const LAS unsigned char* kb0 = lds + krow0 * 128 + ((fq ^ ksw) << 4);
;     const LAS unsigned char* kb1 = lds + krow0 * 128 + (((fq + 4) ^ ksw) << 4);
; #pragma unroll
;     for (int s0 = 0; s0 < NSEG; s0 += GS) {
;         bf16x8 kf[GS][2][2];
; #pragma unroll
;         for (int g = 0; g < GS; ++g)
; #pragma unroll
;             for (int kt = 0; kt < 2; ++kt) { const int s = s0 + g;
;                 const int segoff = SWA ? (32 * s + 16 * kt) * 128 : (((kr0 + s) % 9) * 64 + 16 * kt) * 128;
;                 kf[g][kt][0] = *(const LAS bf16x8*)(kb0 + segoff); kf[g][kt][1] = *(const LAS bf16x8*)(kb1 + segoff); }
;         __builtin_amdgcn_sched_barrier(0);
;         __builtin_amdgcn_s_setprio(1);
; #pragma unroll
;         for (int g = 0; g < GS; ++g)
; #pragma unroll
;             for (int kt = 0; kt < 2; ++kt) {
;                 f32x4 z = FAST ? (f32x4){-shift, -shift, -shift, -shift} : (f32x4){0.f, 0.f, 0.f, 0.f};
;                 z = __builtin_amdgcn_mfma_f32_16x16x32_bf16(kf[g][kt][0], bq0, z, 0, 0, 0);
;                 z = __builtin_amdgcn_mfma_f32_16x16x32_bf16(kf[g][kt][1], bq1, z, 0, 0, 0);
;                 sc[s0 + g][kt] = z; }
;         __builtin_amdgcn_s_setprio(0);
;         __builtin_amdgcn_sched_barrier(0);
;     }
;     ...
;                 oacc[dt] = __builtin_amdgcn_mfma_f32_16x16x32_bf16(__builtin_bit_cast(bf16x8, w), pb[s0 + g], oacc[dt], 0, 0, 0); }
;         __builtin_amdgcn_s_setprio(0);
;         __builtin_amdgcn_sched_barrier(0);
;     }
;     const size_t tq = (size_t)(tb + qpos0 + li);
; #pragma unroll
;     for (int hh = 0; hh < 2; ++hh) {
;         const u32x4 z = qz.z[hh]; const f32x4 a = oacc[2 * hh], b = oacc[2 * hh + 1];
;         u32x4 o; o.x = cvt_pk_bf16(a[0] * rl * bf_lo(z.x), a[1] * rl * bf_hi(z.x)); o.y = cvt_pk_bf16(a[2] * rl * bf_lo(z.y), a[3] * rl * bf_hi(z.y));
;         o.z = cvt_pk_bf16(b[0] * rl * bf_lo(z.z), b[1] * rl * bf_hi(z.z)); o.w = cvt_pk_bf16(b[2] * rl * bf_lo(z.w), b[3] * rl * bf_hi(z.w));
;         *(u32x4*)(P.Y + tq * 1024 + (SWA ? 512 : 0) + hq * 64 + 32 * hh + 8 * fq) = o;
;     }
	v_mfma_f32_16x16x32_bf16 v[112:115], v[132:135], v[128:131], v[116:119]
	s_waitcnt lgkmcnt(8)
	v_mfma_f32_16x16x32_bf16 v[100:103], v[136:139], v[128:131], v[100:103]
	s_waitcnt lgkmcnt(6)
	v_mfma_f32_16x16x32_bf16 v[104:107], v[140:143], v[120:123], v[104:107]
	s_waitcnt lgkmcnt(4)
	v_mfma_f32_16x16x32_bf16 v[108:111], v[144:147], v[120:123], v[108:111]
	s_waitcnt lgkmcnt(2)
	v_mfma_f32_16x16x32_bf16 v[112:115], v[148:151], v[120:123], v[112:115]
	s_waitcnt lgkmcnt(0)
	v_mfma_f32_16x16x32_bf16 v[100:103], v[192:195], v[120:123], v[100:103]
	v_div_scale_f32 v118, s[10:11], v161, v161, 1.0
	v_rcp_f32_e32 v119, v118
	v_or_b32_e32 v116, s53, v171
	v_add_u32_e32 v116, s54, v116
	v_ashrrev_i32_e32 v117, 31, v116
	v_fma_f32 v120, -v118, v119, 1.0
	v_fmac_f32_e32 v119, v120, v119
	v_div_scale_f32 v120, vcc, 1.0, v161, 1.0
	v_mul_f32_e32 v121, v120, v119
	v_fma_f32 v122, -v118, v121, v120
	v_fmac_f32_e32 v121, v122, v119
	v_fma_f32 v118, -v118, v121, v120
	v_div_fmas_f32 v118, v118, v119, v121
	v_div_fixup_f32 v118, v118, v161, 1.0
	s_waitcnt vmcnt(5)
	v_lshlrev_b32_e32 v120, 16, v92
	v_and_b32_e32 v121, 0xffff0000, v92
	v_pk_mul_f32 v[104:105], v[118:119], v[104:105] op_sel_hi:[0,1]
	v_pk_mul_f32 v[104:105], v[104:105], v[120:121]
	v_pk_mul_f32 v[106:107], v[118:119], v[106:107] op_sel_hi:[0,1]
	v_cvt_pk_bf16_f32 v92, v104, v105
	v_lshlrev_b32_e32 v104, 16, v93
	v_and_b32_e32 v105, 0xffff0000, v93
	v_pk_mul_f32 v[104:105], v[106:107], v[104:105]
	v_pk_mul_f32 v[106:107], v[118:119], v[108:109] op_sel_hi:[0,1]
	v_cvt_pk_bf16_f32 v93, v104, v105
	v_lshlrev_b32_e32 v104, 16, v94
	v_and_b32_e32 v105, 0xffff0000, v94
	v_lshlrev_b64 v[144:145], 11, v[116:117]
	v_pk_mul_f32 v[104:105], v[106:107], v[104:105]
	v_lshl_add_u64 v[116:117], s[24:25], 0, v[144:145]
	s_lshl_b32 s0, s51, 7
	s_mov_b32 s1, s39
	v_cvt_pk_bf16_f32 v94, v104, v105
	v_lshlrev_b32_e32 v104, 16, v95
	v_and_b32_e32 v105, 0xffff0000, v95
	v_pk_mul_f32 v[106:107], v[118:119], v[110:111] op_sel_hi:[0,1]
	v_lshl_add_u64 v[116:117], v[116:117], 0, s[0:1]
	v_mov_b32_e32 v163, v157
	v_pk_mul_f32 v[104:105], v[106:107], v[104:105]
	v_lshl_add_u64 v[116:117], v[116:117], 0, v[162:163]
	v_cvt_pk_bf16_f32 v95, v104, v105
	global_store_dwordx4 v[116:117], v[92:95], off
	s_lshl_b32 s38, s51, 6
	s_waitcnt vmcnt(5)
	v_lshlrev_b32_e32 v92, 16, v88
	v_and_b32_e32 v93, 0xffff0000, v88
	v_pk_mul_f32 v[94:95], v[118:119], v[112:113] op_sel_hi:[0,1]
	v_pk_mul_f32 v[92:93], v[94:95], v[92:93]
	v_pk_mul_f32 v[94:95], v[118:119], v[114:115] op_sel_hi:[0,1]
	v_cvt_pk_bf16_f32 v108, v92, v93
	v_lshlrev_b32_e32 v92, 16, v89
	v_and_b32_e32 v93, 0xffff0000, v89
	v_pk_mul_f32 v[92:93], v[94:95], v[92:93]
	v_pk_mul_f32 v[94:95], v[118:119], v[100:101] op_sel_hi:[0,1]
	v_cvt_pk_bf16_f32 v109, v92, v93
	v_lshlrev_b32_e32 v92, 16, v90
	v_and_b32_e32 v93, 0xffff0000, v90
	v_pk_mul_f32 v[92:93], v[94:95], v[92:93]
	s_nop 0
	v_cvt_pk_bf16_f32 v110, v92, v93
	v_mul_f32_e32 v92, v118, v102
	v_lshlrev_b32_e32 v102, 16, v91
	v_mov_b32_e32 v93, v118
	v_pk_mul_f32 v[146:147], v[92:93], v[102:103]
.LBB0_317:
	s_or_saveexec_b64 s[14:15], s[40:41]
	v_mov_b64_e32 v[148:149], s[38:39]
	s_xor_b64 exec, exec, s[14:15]
	s_cbranch_execz .LBB0_319
	s_waitcnt vmcnt(7) lgkmcnt(7)
	v_mfma_f32_16x16x32_bf16 v[108:111], v[112:115], v[104:107], v[96:99]
	s_waitcnt lgkmcnt(6)
	v_mfma_f32_16x16x32_bf16 v[112:115], v[116:119], v[104:107], v[96:99]
	s_waitcnt vmcnt(6) lgkmcnt(5)
	v_mfma_f32_16x16x32_bf16 v[108:111], v[124:127], v[100:103], v[108:111]
	s_waitcnt lgkmcnt(4)
	v_mfma_f32_16x16x32_bf16 v[112:115], v[120:123], v[100:103], v[112:115]
	s_waitcnt lgkmcnt(3)
	v_mfma_f32_16x16x32_bf16 v[116:119], v[128:131], v[104:107], v[96:99]
	s_waitcnt lgkmcnt(2)
	v_mfma_f32_16x16x32_bf16 v[120:123], v[132:135], v[104:107], v[96:99]
	s_waitcnt lgkmcnt(1)
	v_mfma_f32_16x16x32_bf16 v[116:119], v[140:143], v[100:103], v[116:119]
	s_waitcnt lgkmcnt(0)
	v_mfma_f32_16x16x32_bf16 v[120:123], v[136:139], v[100:103], v[120:123]
	ds_read_b128 v[124:127], v194
	ds_read_b128 v[128:131], v194 offset:2048
	ds_read_b128 v[132:135], v193
	ds_read_b128 v[136:139], v193 offset:2048
	ds_read_b128 v[140:143], v151
	ds_read_b128 v[144:147], v151 offset:2048
	ds_read_b128 v[194:197], v150
	ds_read_b128 v[148:151], v150 offset:2048
	s_waitcnt lgkmcnt(7)
	v_mfma_f32_16x16x32_bf16 v[124:127], v[124:127], v[104:107], v[96:99]
	s_waitcnt lgkmcnt(6)
	v_mfma_f32_16x16x32_bf16 v[128:131], v[128:131], v[104:107], v[96:99]
	s_waitcnt lgkmcnt(5)
	v_mfma_f32_16x16x32_bf16 v[124:127], v[132:135], v[100:103], v[124:127]
	s_waitcnt lgkmcnt(4)
	v_mfma_f32_16x16x32_bf16 v[128:131], v[136:139], v[100:103], v[128:131]
	s_waitcnt lgkmcnt(3)
	v_mfma_f32_16x16x32_bf16 v[132:135], v[140:143], v[104:107], v[96:99]
	s_waitcnt lgkmcnt(2)
	v_mfma_f32_16x16x32_bf16 v[136:139], v[144:147], v[104:107], v[96:99]
	s_waitcnt lgkmcnt(1)
	v_mfma_f32_16x16x32_bf16 v[132:135], v[194:197], v[100:103], v[132:135]
	s_waitcnt lgkmcnt(0)
	v_mfma_f32_16x16x32_bf16 v[136:139], v[148:151], v[100:103], v[136:139]
	s_add_i32 s0, s68, 0xe4
	s_bfe_u32 s0, s0, 0x40009
	s_mul_i32 s0, s0, 9
	s_sub_i32 s0, s61, s0
	s_add_i32 s0, s0, 4
	s_and_b32 s0, s0, 0xff
	s_lshl_b32 s19, s0, 13
	s_add_i32 s0, s68, 0x11d
	s_bfe_u32 s0, s0, 0x40009
	s_mul_i32 s0, s0, 9
	s_sub_i32 s0, s61, s0
	s_add_i32 s0, s0, 5
	s_and_b32 s0, s0, 0xff
	v_add_u32_e32 v144, s19, v163
	v_add_u32_e32 v193, s19, v161
	s_lshl_b32 s18, s0, 13
	ds_read_b128 v[140:143], v144
	ds_read_b128 v[144:147], v144 offset:2048
	ds_read_b128 v[148:151], v193
	ds_read_b128 v[194:197], v193 offset:2048
	v_add_u32_e32 v193, s18, v163
	v_add_u32_e32 v210, s18, v161
	ds_read_b128 v[198:201], v193
	ds_read_b128 v[202:205], v193 offset:2048
	ds_read_b128 v[206:209], v210
	ds_read_b128 v[210:213], v210 offset:2048
	s_waitcnt lgkmcnt(7)
; template <bool SWA, bool FAST>
; __device__ __forceinline__ void att_tile(const AttnP& P, LAS unsigned char* lds, int lane, int tb, int qpos0, int hq, int kloc0, int r, int ct, int kr0, int kc0, const AttQZ& qz, float shift) {
;     ...
;     const int krow0 = (SWA ? kloc0 : kc0) + li, ksw = (krow0 >> 1) & 7;
;     const LAS unsigned char* kb0 = lds + krow0 * 128 + ((fq ^ ksw) << 4);
;     const LAS unsigned char* kb1 = lds + krow0 * 128 + (((fq + 4) ^ ksw) << 4);
; #pragma unroll
;     for (int s0 = 0; s0 < NSEG; s0 += GS) {
;         bf16x8 kf[GS][2][2];
; #pragma unroll
;         for (int g = 0; g < GS; ++g)
; #pragma unroll
;             for (int kt = 0; kt < 2; ++kt) { const int s = s0 + g;
;                 const int segoff = SWA ? (32 * s + 16 * kt) * 128 : (((kr0 + s) % 9) * 64 + 16 * kt) * 128;
;                 kf[g][kt][0] = *(const LAS bf16x8*)(kb0 + segoff); kf[g][kt][1] = *(const LAS bf16x8*)(kb1 + segoff); }
;         __builtin_amdgcn_sched_barrier(0);
;         __builtin_amdgcn_s_setprio(1);
; #pragma unroll
;         for (int g = 0; g < GS; ++g)
; #pragma unroll
;             for (int kt = 0; kt < 2; ++kt) {
;                 f32x4 z = FAST ? (f32x4){-shift, -shift, -shift, -shift} : (f32x4){0.f, 0.f, 0.f, 0.f};
;                 z = __builtin_amdgcn_mfma_f32_16x16x32_bf16(kf[g][kt][0], bq0, z, 0, 0, 0);
;                 z = __builtin_amdgcn_mfma_f32_16x16x32_bf16(kf[g][kt][1], bq1, z, 0, 0, 0);
;                 sc[s0 + g][kt] = z; }
;         __builtin_amdgcn_s_setprio(0);
;         __builtin_amdgcn_sched_barrier(0);
;     }
;     ...
;     if constexpr (!SWA && FAST) {
;         const int c = 16 * ct + li, cs = min(max(c - 8, 0), 48), w = cs - kc0;
;         const LAS float* rp = (const LAS float*)(lds + ATT_RPB) + (kr0 - r + 7) * 64 + (kc0 + 4 * fq - c + 31);
;         bool hi[4]; const LAS float* rpj[4];
; #pragma unroll
;         for (int j = 0; j < 4; ++j) { hi[j] = (4 * fq + j) < w; rpj[j] = rp + (hi[j] ? 16 : 0) + j; }
;         const unsigned m01 = (hi[0] ? 0u : 0xffffu) | (hi[1] ? 0u : 0xffff0000u), m23 = (hi[2] ? 0u : 0xffffu) | (hi[3] ? 0u : 0xffff0000u);
; #pragma unroll
;         for (int s = 0; s < NSEG; ++s) {
;             float p[4];
; #pragma unroll
;             for (int j = 0; j < 4; ++j) { const float v = hi[j] ? sc[s][1][j] : sc[s][0][j]; p[j] = __builtin_amdgcn_exp2f(v + rpj[j][s * 64]); }
	v_mfma_f32_16x16x32_bf16 v[140:143], v[140:143], v[104:107], v[96:99]
	s_waitcnt lgkmcnt(5)
	v_mfma_f32_16x16x32_bf16 v[140:143], v[148:151], v[100:103], v[140:143]
	v_mfma_f32_16x16x32_bf16 v[144:147], v[144:147], v[104:107], v[96:99]
	s_waitcnt lgkmcnt(3)
	v_mfma_f32_16x16x32_bf16 v[148:151], v[198:201], v[104:107], v[96:99]
	v_mfma_f32_16x16x32_bf16 v[144:147], v[194:197], v[100:103], v[144:147]
	s_waitcnt lgkmcnt(1)
	v_mfma_f32_16x16x32_bf16 v[148:151], v[206:209], v[100:103], v[148:151]
	v_mfma_f32_16x16x32_bf16 v[194:197], v[202:205], v[104:107], v[96:99]
	s_waitcnt lgkmcnt(0)
	v_mfma_f32_16x16x32_bf16 v[194:197], v[210:213], v[100:103], v[194:197]
	s_add_i32 s0, s68, 0x156
	s_bfe_u32 s0, s0, 0x40009
	s_mul_i32 s0, s0, 9
	s_sub_i32 s0, s61, s0
	s_add_i32 s0, s0, 6
	s_and_b32 s0, s0, 0xff
	s_addk_i32 s68, 0x18f
	s_lshl_b32 s17, s0, 13
	s_bfe_u32 s0, s68, 0x40009
	s_mul_i32 s0, s0, 9
	s_sub_i32 s0, s61, s0
	s_add_i32 s0, s0, 7
	s_and_b32 s0, s0, 0xff
	s_lshl_b32 s16, s0, 13
	v_add_u32_e32 v193, s17, v163
	v_add_u32_e32 v210, s17, v161
	v_add_u32_e32 v163, s16, v163
	ds_read_b128 v[198:201], v193
	ds_read_b128 v[202:205], v193 offset:2048
	ds_read_b128 v[206:209], v210
	ds_read_b128 v[210:213], v210 offset:2048
	v_add_u32_e32 v161, s16, v161
	ds_read_b128 v[214:217], v163
	ds_read_b128 v[218:221], v163 offset:2048
	ds_read_b128 v[222:225], v161
	ds_read_b128 v[226:229], v161 offset:2048
	s_waitcnt lgkmcnt(7)
	v_mfma_f32_16x16x32_bf16 v[198:201], v[198:201], v[104:107], v[96:99]
	s_waitcnt lgkmcnt(5)
	v_mfma_f32_16x16x32_bf16 v[198:201], v[206:209], v[100:103], v[198:201]
	v_mfma_f32_16x16x32_bf16 v[202:205], v[202:205], v[104:107], v[96:99]
	s_waitcnt lgkmcnt(3)
	v_mfma_f32_16x16x32_bf16 v[206:209], v[214:217], v[104:107], v[96:99]
	s_waitcnt lgkmcnt(2)
	v_mfma_f32_16x16x32_bf16 v[104:107], v[218:221], v[104:107], v[96:99]
	v_mfma_f32_16x16x32_bf16 v[202:205], v[210:213], v[100:103], v[202:205]
	s_waitcnt lgkmcnt(1)
	v_mfma_f32_16x16x32_bf16 v[206:209], v[222:225], v[100:103], v[206:209]
	s_waitcnt lgkmcnt(0)
	v_mfma_f32_16x16x32_bf16 v[100:103], v[226:229], v[100:103], v[104:107]
	s_sub_i32 s0, s61, s60
	s_lshl_b32 s0, s0, 8
	v_subrev_u32_e32 v104, s59, v172
	s_add_i32 s0, s0, 0
	s_add_i32 s0, s0, 0x24000
	v_cmp_lt_i32_e32 vcc, v173, v104
	v_lshl_add_u32 v105, v192, 2, s0
	v_cmp_lt_i32_e64 s[0:1], v176, v104
	v_cndmask_b32_e64 v106, 0, 64, vcc
	v_cmp_lt_i32_e64 s[12:13], v178, v104
	v_add_u32_e32 v106, v105, v106
	v_cndmask_b32_e64 v107, 0, 64, s[0:1]
	v_cmp_lt_i32_e64 s[10:11], v177, v104
	v_cndmask_b32_e64 v104, 0, 64, s[12:13]
	v_add_u32_e32 v107, v105, v107
	v_cndmask_b32_e64 v161, 0, 64, s[10:11]
	v_add_u32_e32 v104, v105, v104
	v_cndmask_b32_e32 v163, v108, v112, vcc
	v_add_u32_e32 v112, 0x7c, v106
	v_add_u32_e32 v161, v105, v161
	v_cndmask_b32_e64 v192, v109, v113, s[0:1]
	v_add_u32_e32 v193, 0x80, v107
	v_cndmask_b32_e64 v210, v110, v114, s[10:11]
	v_cndmask_b32_e64 v211, v111, v115, s[12:13]
	v_add_u32_e32 v212, 0x88, v104
	ds_read2st64_b32 v[104:105], v112 offset0:7 offset1:8
	ds_read2st64_b32 v[106:107], v112 offset0:9 offset1:10
	ds_read2st64_b32 v[108:109], v112 offset0:11 offset1:12
	ds_read2st64_b32 v[110:111], v112 offset0:13 offset1:14
	v_add_u32_e32 v161, 0x84, v161
	v_cndmask_b32_e32 v213, v116, v120, vcc
	v_cndmask_b32_e64 v214, v117, v121, s[0:1]
	v_cndmask_b32_e64 v215, v118, v122, s[10:11]
	v_cndmask_b32_e64 v216, v119, v123, s[12:13]
	ds_read2st64_b32 v[112:113], v193 offset0:7 offset1:8
	ds_read2st64_b32 v[114:115], v193 offset0:9 offset1:10
	ds_read2st64_b32 v[116:117], v193 offset0:11 offset1:12
	ds_read2st64_b32 v[118:119], v193 offset0:13 offset1:14
	v_cndmask_b32_e32 v217, v124, v128, vcc
	v_cndmask_b32_e64 v218, v125, v129, s[0:1]
	v_cndmask_b32_e64 v219, v126, v130, s[10:11]
	v_cndmask_b32_e64 v220, v127, v131, s[12:13]
	ds_read2st64_b32 v[120:121], v161 offset0:7 offset1:8
	ds_read2st64_b32 v[122:123], v161 offset0:9 offset1:10
	ds_read2st64_b32 v[124:125], v161 offset0:11 offset1:12
	ds_read2st64_b32 v[126:127], v161 offset0:13 offset1:14
	v_cndmask_b32_e32 v221, v132, v136, vcc
	v_cndmask_b32_e64 v222, v133, v137, s[0:1]
	v_cndmask_b32_e64 v223, v134, v138, s[10:11]
	v_cndmask_b32_e64 v224, v135, v139, s[12:13]
	ds_read2st64_b32 v[128:129], v212 offset0:7 offset1:8
	ds_read2st64_b32 v[130:131], v212 offset0:9 offset1:10
	ds_read2st64_b32 v[132:133], v212 offset0:11 offset1:12
	ds_read2st64_b32 v[134:135], v212 offset0:13 offset1:14
	v_cndmask_b32_e32 v136, v198, v202, vcc
	v_cndmask_b32_e32 v144, v140, v144, vcc
	v_cndmask_b32_e64 v140, v142, v146, s[10:11]
	v_cndmask_b32_e32 v146, v148, v194, vcc
	v_cndmask_b32_e64 v137, v199, v203, s[0:1]
	v_cndmask_b32_e32 v100, v206, v100, vcc
	v_cndmask_b32_e64 v148, v209, v103, s[12:13]
	s_waitcnt lgkmcnt(12)
	v_add_f32_e32 v103, v136, v110
	v_cndmask_b32_e64 v145, v141, v145, s[0:1]
	v_cndmask_b32_e64 v141, v143, v147, s[12:13]
	v_cndmask_b32_e64 v142, v150, v196, s[10:11]
	v_cndmask_b32_e64 v138, v200, v204, s[10:11]
	v_cndmask_b32_e64 v101, v207, v101, s[0:1]
	v_exp_f32_e32 v136, v103
	s_waitcnt lgkmcnt(8)
	v_add_f32_e32 v103, v137, v118
	v_add_f32_e32 v100, v100, v111
	s_waitcnt lgkmcnt(6)
	v_add_f32_e32 v123, v223, v123
	v_add_f32_e32 v120, v210, v120
	v_add_f32_e32 v104, v163, v104
	v_cndmask_b32_e64 v102, v208, v102, s[10:11]
	v_exp_f32_e32 v137, v103
	s_waitcnt lgkmcnt(4)
	v_add_f32_e32 v103, v138, v126
	v_exp_f32_e32 v110, v100
	v_add_f32_e32 v100, v101, v119
	v_add_f32_e32 v118, v142, v125
	s_waitcnt lgkmcnt(1)
; #define LAS __attribute__((address_space(3)))
; template <bool SWA, bool FAST>
; __device__ __forceinline__ void att_tile(const AttnP& P, LAS unsigned char* lds, int lane, int tb, int qpos0, int hq, int kloc0, int r, int ct, int kr0, int kc0, const AttQZ& qz, float shift) {
;     ...
;     if constexpr (!SWA && FAST) {
;         const int c = 16 * ct + li, cs = min(max(c - 8, 0), 48), w = cs - kc0;
;         const LAS float* rp = (const LAS float*)(lds + ATT_RPB) + (kr0 - r + 7) * 64 + (kc0 + 4 * fq - c + 31);
;         bool hi[4]; const LAS float* rpj[4];
; #pragma unroll
;         for (int j = 0; j < 4; ++j) { hi[j] = (4 * fq + j) < w; rpj[j] = rp + (hi[j] ? 16 : 0) + j; }
;         const unsigned m01 = (hi[0] ? 0u : 0xffffu) | (hi[1] ? 0u : 0xffff0000u), m23 = (hi[2] ? 0u : 0xffffu) | (hi[3] ? 0u : 0xffff0000u);
; #pragma unroll
;         for (int s = 0; s < NSEG; ++s) {
;             float p[4];
; #pragma unroll
;             for (int j = 0; j < 4; ++j) { const float v = hi[j] ? sc[s][1][j] : sc[s][0][j]; p[j] = __builtin_amdgcn_exp2f(v + rpj[j][s * 64]); }
;             l2 += (f32x2_t){p[0], p[1]}; l2 += (f32x2_t){p[2], p[3]};
;             const unsigned pk01 = cvt_pk_bf16(p[0], p[1]), pk23 = cvt_pk_bf16(p[2], p[3]);
;             u32x4 wv; wv.x = pk01 & m01; wv.y = pk23 & m23; wv.z = pk01 & ~m01; wv.w = pk23 & ~m23;
;             pb[s] = __builtin_bit_cast(bf16x8, wv);
;         }
;     } else
; #pragma unroll
;     for (int s = 0; s < NSEG; ++s) {
;         float p[8];
; #pragma unroll
;         for (int kt = 0; kt < 2; ++kt)
; #pragma unroll
;             for (int j = 0; j < 4; ++j) p[4 * kt + j] = __builtin_amdgcn_exp2f(FAST ? sc[s][kt][j] : sc[s][kt][j] - mx);
; #pragma unroll
;         for (int e = 0; e < 8; e += 2) l2 += (f32x2_t){p[e], p[e + 1]};
;         u32x4 w; w.x = cvt_pk_bf16(p[0], p[1]); w.y = cvt_pk_bf16(p[2], p[3]); w.z = cvt_pk_bf16(p[4], p[5]); w.w = cvt_pk_bf16(p[6], p[7]);
;         pb[s] = __builtin_bit_cast(bf16x8, w);
;     }
;     l += l2[0] + l2[1];
;     l += __shfl_xor(l, 16); l += __shfl_xor(l, 32);
;     if (SWA) l += __builtin_amdgcn_exp2f(FAST ? sk - shift : sk - mx);
;     const float rl = 1.0f / l;
;     f32x4 oacc[4];
; #pragma unroll
;     for (int dt = 0; dt < 4; ++dt) oacc[dt] = (f32x4){0.f, 0.f, 0.f, 0.f};
;     constexpr int GV = SWA ? 3 : 2;
;     const int g0l = (SWA ? kloc0 : kc0) + 4 * fq;
	v_add_f32_e32 v125, v141, v132
	v_exp_f32_e32 v126, v123
	v_add_f32_e32 v123, v224, v131
	v_add_f32_e32 v121, v215, v121
	v_exp_f32_e32 v132, v120
	v_add_f32_e32 v120, v211, v128
	v_exp_f32_e32 v128, v104
	v_add_f32_e32 v104, v192, v112
	v_cndmask_b32_e64 v143, v151, v197, s[12:13]
	v_exp_f32_e32 v111, v100
	v_add_f32_e32 v100, v102, v127
	v_exp_f32_e32 v127, v123
	v_add_f32_e32 v123, v220, v130
	v_exp_f32_e32 v130, v121
	v_add_f32_e32 v121, v216, v129
	v_exp_f32_e32 v129, v104
	v_add_f32_e32 v104, v213, v105
	v_add_f32_e32 v119, v143, v133
	v_add_f32_e32 v124, v140, v124
	v_exp_f32_e32 v133, v120
	v_exp_f32_e32 v140, v104
	v_add_f32_e32 v104, v214, v113
	v_exp_f32_e32 v141, v104
	v_add_f32_e32 v106, v217, v106
	v_exp_f32_e32 v131, v121
	v_exp_f32_e32 v120, v106
	v_add_f32_e32 v106, v218, v114
	v_add_f32_e32 v122, v219, v122
	v_pk_add_f32 v[104:105], v[128:129], 0 op_sel_hi:[1,0]
	v_exp_f32_e32 v121, v106
	v_add_f32_e32 v106, v221, v107
	v_exp_f32_e32 v122, v122
	v_exp_f32_e32 v123, v123
	v_pk_add_f32 v[104:105], v[104:105], v[132:133]
	v_exp_f32_e32 v142, v106
	v_add_f32_e32 v106, v222, v115
	v_pk_add_f32 v[104:105], v[104:105], v[140:141]
	v_exp_f32_e32 v143, v106
	v_add_f32_e32 v106, v144, v108
	v_pk_add_f32 v[104:105], v[104:105], v[130:131]
	v_exp_f32_e32 v112, v106
	v_add_f32_e32 v106, v145, v116
	v_cndmask_b32_e64 v147, v149, v195, s[0:1]
	v_pk_add_f32 v[104:105], v[104:105], v[120:121]
	v_exp_f32_e32 v113, v106
	v_exp_f32_e32 v124, v124
	v_exp_f32_e32 v125, v125
	v_pk_add_f32 v[104:105], v[104:105], v[122:123]
	v_add_f32_e32 v106, v146, v109
	v_add_f32_e32 v107, v147, v117
	v_pk_add_f32 v[104:105], v[104:105], v[142:143]
	v_exp_f32_e32 v106, v106
	v_exp_f32_e32 v107, v107
	v_exp_f32_e32 v118, v118
	v_exp_f32_e32 v119, v119
	v_pk_add_f32 v[104:105], v[104:105], v[126:127]
	v_cndmask_b32_e64 v139, v201, v205, s[12:13]
	v_pk_add_f32 v[104:105], v[104:105], v[112:113]
	v_exp_f32_e32 v138, v103
	s_waitcnt lgkmcnt(0)
	v_add_f32_e32 v103, v139, v134
	v_pk_add_f32 v[104:105], v[104:105], v[124:125]
	v_exp_f32_e32 v139, v103
	v_pk_add_f32 v[104:105], v[104:105], v[106:107]
	v_cvt_pk_bf16_f32 v106, v106, v107
	v_pk_add_f32 v[104:105], v[104:105], v[118:119]
	v_cvt_pk_bf16_f32 v107, v118, v119
	v_cvt_pk_bf16_f32 v119, v126, v127
	v_cvt_pk_bf16_f32 v127, v130, v131
	v_cvt_pk_bf16_f32 v130, v128, v129
	v_add_f32_e32 v129, v148, v135
	v_exp_f32_e32 v134, v100
	v_exp_f32_e32 v135, v129
	v_pk_add_f32 v[104:105], v[104:105], v[136:137]
	v_cvt_pk_bf16_f32 v131, v132, v133
	v_pk_add_f32 v[108:109], v[104:105], v[138:139]
	v_cndmask_b32_e64 v149, v188, 0, s[12:13]
	v_pk_add_f32 v[108:109], v[108:109], v[110:111]
	v_cndmask_b32_e64 v161, v189, 0, s[10:11]
	v_pk_add_f32 v[108:109], v[108:109], v[134:135]
	v_cvt_pk_bf16_f32 v103, v138, v139
	v_add_f32_e32 v108, v108, v109
	v_add_f32_e32 v108, 0, v108
	ds_bpermute_b32 v109, v180, v108
	v_cvt_pk_bf16_f32 v115, v124, v125
	v_cvt_pk_bf16_f32 v123, v122, v123
	v_cvt_pk_bf16_f32 v110, v110, v111
	v_cvt_pk_bf16_f32 v111, v134, v135
	s_waitcnt lgkmcnt(0)
	v_add_f32_e32 v132, v108, v109
	ds_bpermute_b32 v133, v181, v132
	v_bitop3_b32 v101, v149, v103, v161 bitop3:0xc8
	v_bitop3_b32 v103, v103, v149, v161 bitop3:0x10
	v_bitop3_b32 v105, v149, v107, v161 bitop3:0xc8
	v_bitop3_b32 v107, v107, v149, v161 bitop3:0x10
	v_cvt_pk_bf16_f32 v114, v112, v113
	v_bitop3_b32 v113, v149, v115, v161 bitop3:0xc8
	v_bitop3_b32 v115, v115, v149, v161 bitop3:0x10
	v_bitop3_b32 v117, v149, v119, v161 bitop3:0xc8
	v_bitop3_b32 v119, v119, v149, v161 bitop3:0x10
	v_cvt_pk_bf16_f32 v124, v120, v121
	v_bitop3_b32 v121, v149, v123, v161 bitop3:0xc8
	v_bitop3_b32 v123, v123, v149, v161 bitop3:0x10
	v_bitop3_b32 v125, v149, v127, v161 bitop3:0xc8
	v_bitop3_b32 v127, v127, v149, v161 bitop3:0x10
	v_bitop3_b32 v129, v149, v131, v161 bitop3:0xc8
	v_bitop3_b32 v131, v131, v149, v161 bitop3:0x10
	v_bitop3_b32 v109, v149, v111, v161 bitop3:0xc8
	v_bitop3_b32 v111, v111, v149, v161 bitop3:0x10
	s_waitcnt lgkmcnt(0)
	v_add_f32_e32 v161, v132, v133
	v_lshlrev_b32_e32 v132, 7, v156
	v_lshlrev_b32_e32 v133, 1, v156
	v_and_b32_e32 v132, 0x3c00, v132
	v_and_b32_e32 v133, 8, v133
	v_add3_u32 v156, v175, v132, v133
	v_add_u32_e32 v146, s58, v156
	ds_read_b64 v[132:133], v146
	ds_read_b64 v[134:135], v146 offset:2048
	v_cvt_pk_bf16_f32 v102, v136, v137
	ds_read_b64 v[136:137], v146 offset:256
	ds_read_b64 v[138:139], v146 offset:2304
	v_cvt_pk_bf16_f32 v126, v140, v141
	ds_read_b64 v[140:141], v146 offset:512
	v_cvt_pk_bf16_f32 v118, v142, v143
	ds_read_b64 v[142:143], v146 offset:2560
	ds_read_b64 v[144:145], v146 offset:768
	ds_read_b64 v[146:147], v146 offset:2816
	v_add_u32_e32 v163, s57, v156
	v_cndmask_b32_e64 v150, v188, 0, s[0:1]
	v_cndmask_b32_e64 v151, v189, 0, vcc
	ds_read_b64 v[148:149], v163
	v_bitop3_b32 v100, v150, v102, v151 bitop3:0xc8
	v_bitop3_b32 v102, v102, v150, v151 bitop3:0x10
	v_bitop3_b32 v104, v150, v106, v151 bitop3:0xc8
	v_bitop3_b32 v106, v106, v150, v151 bitop3:0x10
	v_bitop3_b32 v112, v150, v114, v151 bitop3:0xc8
	v_bitop3_b32 v114, v114, v150, v151 bitop3:0x10
	v_bitop3_b32 v116, v150, v118, v151 bitop3:0xc8
	v_bitop3_b32 v118, v118, v150, v151 bitop3:0x10
	v_bitop3_b32 v120, v150, v124, v151 bitop3:0xc8
	v_bitop3_b32 v122, v124, v150, v151 bitop3:0x10
	v_bitop3_b32 v124, v150, v126, v151 bitop3:0xc8
	v_bitop3_b32 v126, v126, v150, v151 bitop3:0x10
	v_bitop3_b32 v128, v150, v130, v151 bitop3:0xc8
	v_bitop3_b32 v130, v130, v150, v151 bitop3:0x10
	v_bitop3_b32 v108, v150, v110, v151 bitop3:0xc8
	v_bitop3_b32 v110, v110, v150, v151 bitop3:0x10
	ds_read_b64 v[150:151], v163 offset:2048
	ds_read_b64 v[192:193], v163 offset:256
	ds_read_b64 v[194:195], v163 offset:2304
	ds_read_b64 v[196:197], v163 offset:512
	ds_read_b64 v[198:199], v163 offset:2560
	ds_read_b64 v[200:201], v163 offset:768
	ds_read_b64 v[202:203], v163 offset:2816
	s_waitcnt lgkmcnt(14)
; #define LAS __attribute__((address_space(3)))
; template <bool SWA, bool FAST>
; __device__ __forceinline__ void att_tile(const AttnP& P, LAS unsigned char* lds, int lane, int tb, int qpos0, int hq, int kloc0, int r, int ct, int kr0, int kc0, const AttQZ& qz, float shift) {
;     ...
; #pragma unroll
;     for (int s0 = 0; s0 < NSEG; s0 += GV) {
;         u32x2 vf[GV][4][2];
; #pragma unroll
;         for (int g = 0; g < GV; ++g) { const int s = s0 + g;
;             const int segv = SWA ? s * 4096 : ((kr0 + s) % 9) * 8192;
; #pragma unroll
;             for (int dt = 0; dt < 4; ++dt) {
;                 vf[g][dt][0] = *(const LAS u32x2*)(vb0 + segv + dt * 256); asm volatile("" ::: "memory");
;                 vf[g][dt][1] = *(const LAS u32x2*)(vb0 + segv + dt * 256 + 2048); asm volatile("" ::: "memory"); } }
;         __builtin_amdgcn_sched_barrier(0);
;         __builtin_amdgcn_s_setprio(1);
; #pragma unroll
;         for (int g = 0; g < GV; ++g)
; #pragma unroll
;             for (int dt = 0; dt < 4; ++dt) {
;                 u32x4 w; w.x = vf[g][dt][0].x; w.y = vf[g][dt][0].y; w.z = vf[g][dt][1].x; w.w = vf[g][dt][1].y;
;                 oacc[dt] = __builtin_amdgcn_mfma_f32_16x16x32_bf16(__builtin_bit_cast(bf16x8, w), pb[s0 + g], oacc[dt], 0, 0, 0); }
;         __builtin_amdgcn_s_setprio(0);
;         __builtin_amdgcn_sched_barrier(0);
;     }
	v_mfma_f32_16x16x32_bf16 v[132:135], v[132:135], v[128:131], 0
	s_waitcnt lgkmcnt(12)
	v_mfma_f32_16x16x32_bf16 v[136:139], v[136:139], v[128:131], 0
	s_waitcnt lgkmcnt(10)
	v_mfma_f32_16x16x32_bf16 v[140:143], v[140:143], v[128:131], 0
	s_waitcnt lgkmcnt(8)
	v_mfma_f32_16x16x32_bf16 v[128:131], v[144:147], v[128:131], 0
	s_waitcnt lgkmcnt(6)
	v_mfma_f32_16x16x32_bf16 v[132:135], v[148:151], v[124:127], v[132:135]
	s_waitcnt lgkmcnt(4)
	v_mfma_f32_16x16x32_bf16 v[136:139], v[192:195], v[124:127], v[136:139]
	s_waitcnt lgkmcnt(2)
	v_mfma_f32_16x16x32_bf16 v[140:143], v[196:199], v[124:127], v[140:143]
	s_waitcnt lgkmcnt(0)
	v_mfma_f32_16x16x32_bf16 v[124:127], v[200:203], v[124:127], v[128:131]
	v_add_u32_e32 v163, s56, v156
	s_nop 0
	ds_read_b64 v[128:129], v163
	ds_read_b64 v[130:131], v163 offset:2048
	ds_read_b64 v[144:145], v163 offset:256
	ds_read_b64 v[146:147], v163 offset:2304
	ds_read_b64 v[148:149], v163 offset:512
	ds_read_b64 v[150:151], v163 offset:2560
	ds_read_b64 v[192:193], v163 offset:768
	ds_read_b64 v[194:195], v163 offset:2816
	v_add_u32_e32 v163, s55, v156
	ds_read_b64 v[196:197], v163
	ds_read_b64 v[198:199], v163 offset:2048
	ds_read_b64 v[200:201], v163 offset:256
	ds_read_b64 v[202:203], v163 offset:2304
	ds_read_b64 v[204:205], v163 offset:512
	ds_read_b64 v[206:207], v163 offset:2560
	ds_read_b64 v[208:209], v163 offset:768
	ds_read_b64 v[210:211], v163 offset:2816
	s_waitcnt lgkmcnt(14)
	v_mfma_f32_16x16x32_bf16 v[128:131], v[128:131], v[120:123], v[132:135]
	s_waitcnt lgkmcnt(12)
	v_mfma_f32_16x16x32_bf16 v[132:135], v[144:147], v[120:123], v[136:139]
	s_waitcnt lgkmcnt(10)
	v_mfma_f32_16x16x32_bf16 v[136:139], v[148:151], v[120:123], v[140:143]
	s_waitcnt lgkmcnt(8)
	v_mfma_f32_16x16x32_bf16 v[120:123], v[192:195], v[120:123], v[124:127]
	s_waitcnt lgkmcnt(6)
	v_mfma_f32_16x16x32_bf16 v[124:127], v[196:199], v[116:119], v[128:131]
	s_waitcnt lgkmcnt(4)
	v_mfma_f32_16x16x32_bf16 v[128:131], v[200:203], v[116:119], v[132:135]
	s_waitcnt lgkmcnt(2)
	v_mfma_f32_16x16x32_bf16 v[132:135], v[204:207], v[116:119], v[136:139]
	s_waitcnt lgkmcnt(0)
	v_mfma_f32_16x16x32_bf16 v[116:119], v[208:211], v[116:119], v[120:123]
	v_add_u32_e32 v146, s19, v156
	s_nop 0
	ds_read_b64 v[120:121], v146
	ds_read_b64 v[122:123], v146 offset:2048
	ds_read_b64 v[136:137], v146 offset:256
	ds_read_b64 v[138:139], v146 offset:2304
	ds_read_b64 v[140:141], v146 offset:512
	ds_read_b64 v[142:143], v146 offset:2560
	ds_read_b64 v[144:145], v146 offset:768
	ds_read_b64 v[146:147], v146 offset:2816
	v_add_u32_e32 v163, s18, v156
	ds_read_b64 v[148:149], v163
	ds_read_b64 v[150:151], v163 offset:2048
	ds_read_b64 v[192:193], v163 offset:256
	ds_read_b64 v[194:195], v163 offset:2304
	ds_read_b64 v[196:197], v163 offset:512
	ds_read_b64 v[198:199], v163 offset:2560
	ds_read_b64 v[200:201], v163 offset:768
	ds_read_b64 v[202:203], v163 offset:2816
	s_waitcnt lgkmcnt(14)
	v_mfma_f32_16x16x32_bf16 v[120:123], v[120:123], v[112:115], v[124:127]
	s_waitcnt lgkmcnt(12)
	v_mfma_f32_16x16x32_bf16 v[124:127], v[136:139], v[112:115], v[128:131]
	s_waitcnt lgkmcnt(10)
	v_mfma_f32_16x16x32_bf16 v[128:131], v[140:143], v[112:115], v[132:135]
	s_waitcnt lgkmcnt(8)
	v_mfma_f32_16x16x32_bf16 v[112:115], v[144:147], v[112:115], v[116:119]
	s_waitcnt lgkmcnt(6)
	v_mfma_f32_16x16x32_bf16 v[116:119], v[148:151], v[104:107], v[120:123]
	s_waitcnt lgkmcnt(4)
	v_mfma_f32_16x16x32_bf16 v[120:123], v[192:195], v[104:107], v[124:127]
	s_waitcnt lgkmcnt(2)
	v_mfma_f32_16x16x32_bf16 v[124:127], v[196:199], v[104:107], v[128:131]
	s_waitcnt lgkmcnt(0)
; #define LAS __attribute__((address_space(3)))
; __device__ __forceinline__ unsigned cvt_pk_bf16(float lo, float hi) { const f32x2_t v = {lo, hi}; const bf16x2_t r = __builtin_convertvector(v, bf16x2_t); return __builtin_bit_cast(unsigned, r); }
; __device__ __forceinline__ float bf_lo(unsigned w) { return __uint_as_float(w << 16); }
; __device__ __forceinline__ float bf_hi(unsigned w) { return __uint_as_float(w & 0xffff0000u); }
; template <bool SWA, bool FAST>
; __device__ __forceinline__ void att_tile(const AttnP& P, LAS unsigned char* lds, int lane, int tb, int qpos0, int hq, int kloc0, int r, int ct, int kr0, int kc0, const AttQZ& qz, float shift) {
;     ...
; #pragma unroll
;     for (int s0 = 0; s0 < NSEG; s0 += GV) {
;         u32x2 vf[GV][4][2];
; #pragma unroll
;         for (int g = 0; g < GV; ++g) { const int s = s0 + g;
;             const int segv = SWA ? s * 4096 : ((kr0 + s) % 9) * 8192;
; #pragma unroll
;             for (int dt = 0; dt < 4; ++dt) {
;                 vf[g][dt][0] = *(const LAS u32x2*)(vb0 + segv + dt * 256); asm volatile("" ::: "memory");
;                 vf[g][dt][1] = *(const LAS u32x2*)(vb0 + segv + dt * 256 + 2048); asm volatile("" ::: "memory"); } }
;         __builtin_amdgcn_sched_barrier(0);
;         __builtin_amdgcn_s_setprio(1);
; #pragma unroll
;         for (int g = 0; g < GV; ++g)
; #pragma unroll
;             for (int dt = 0; dt < 4; ++dt) {
;                 u32x4 w; w.x = vf[g][dt][0].x; w.y = vf[g][dt][0].y; w.z = vf[g][dt][1].x; w.w = vf[g][dt][1].y;
;                 oacc[dt] = __builtin_amdgcn_mfma_f32_16x16x32_bf16(__builtin_bit_cast(bf16x8, w), pb[s0 + g], oacc[dt], 0, 0, 0); }
;         __builtin_amdgcn_s_setprio(0);
;         __builtin_amdgcn_sched_barrier(0);
;     }
;     const size_t tq = (size_t)(tb + qpos0 + li);
; #pragma unroll
;     for (int hh = 0; hh < 2; ++hh) {
;         const u32x4 z = qz.z[hh]; const f32x4 a = oacc[2 * hh], b = oacc[2 * hh + 1];
;         u32x4 o; o.x = cvt_pk_bf16(a[0] * rl * bf_lo(z.x), a[1] * rl * bf_hi(z.x)); o.y = cvt_pk_bf16(a[2] * rl * bf_lo(z.y), a[3] * rl * bf_hi(z.y));
;         o.z = cvt_pk_bf16(b[0] * rl * bf_lo(z.z), b[1] * rl * bf_hi(z.z)); o.w = cvt_pk_bf16(b[2] * rl * bf_lo(z.w), b[3] * rl * bf_hi(z.w));
;         *(u32x4*)(P.Y + tq * 1024 + (SWA ? 512 : 0) + hq * 64 + 32 * hh + 8 * fq) = o;
;     }
	v_mfma_f32_16x16x32_bf16 v[104:107], v[200:203], v[104:107], v[112:115]
	v_add_u32_e32 v138, s17, v156
	s_nop 0
	ds_read_b64 v[112:113], v138
	ds_read_b64 v[114:115], v138 offset:2048
	ds_read_b64 v[128:129], v138 offset:256
	ds_read_b64 v[130:131], v138 offset:2304
	ds_read_b64 v[132:133], v138 offset:512
	ds_read_b64 v[134:135], v138 offset:2560
	ds_read_b64 v[136:137], v138 offset:768
	ds_read_b64 v[138:139], v138 offset:2816
	v_add_u32_e32 v156, s16, v156
	ds_read_b64 v[140:141], v156
	ds_read_b64 v[142:143], v156 offset:2048
	ds_read_b64 v[144:145], v156 offset:256
	ds_read_b64 v[146:147], v156 offset:2304
	ds_read_b64 v[148:149], v156 offset:512
	ds_read_b64 v[150:151], v156 offset:2560
	ds_read_b64 v[192:193], v156 offset:768
	ds_read_b64 v[194:195], v156 offset:2816
	s_waitcnt lgkmcnt(14)
	v_mfma_f32_16x16x32_bf16 v[112:115], v[112:115], v[100:103], v[116:119]
	s_waitcnt lgkmcnt(12)
	v_mfma_f32_16x16x32_bf16 v[116:119], v[128:131], v[100:103], v[120:123]
	s_waitcnt lgkmcnt(10)
	v_mfma_f32_16x16x32_bf16 v[120:123], v[132:135], v[100:103], v[124:127]
	s_waitcnt lgkmcnt(8)
	v_mfma_f32_16x16x32_bf16 v[100:103], v[136:139], v[100:103], v[104:107]
	s_waitcnt lgkmcnt(6)
	v_mfma_f32_16x16x32_bf16 v[104:107], v[140:143], v[108:111], v[112:115]
	s_waitcnt lgkmcnt(4)
	v_mfma_f32_16x16x32_bf16 v[112:115], v[144:147], v[108:111], v[116:119]
	s_waitcnt lgkmcnt(2)
	v_mfma_f32_16x16x32_bf16 v[116:119], v[148:151], v[108:111], v[120:123]
	s_waitcnt lgkmcnt(0)
	v_mfma_f32_16x16x32_bf16 v[100:103], v[192:195], v[108:111], v[100:103]
	v_div_scale_f32 v108, s[0:1], v161, v161, 1.0
	v_rcp_f32_e32 v109, v108
	v_div_scale_f32 v110, vcc, 1.0, v161, 1.0
	s_lshl_b32 s0, s51, 7
	v_fma_f32 v111, -v108, v109, 1.0
	v_fmac_f32_e32 v109, v111, v109
	v_mul_f32_e32 v111, v110, v109
	v_fma_f32 v120, -v108, v111, v110
	v_fmac_f32_e32 v111, v120, v109
	v_fma_f32 v108, -v108, v111, v110
	v_div_fmas_f32 v108, v108, v109, v111
	v_div_fixup_f32 v120, v108, v161, 1.0
	v_or_b32_e32 v108, s53, v171
	v_add_u32_e32 v108, s54, v108
	v_ashrrev_i32_e32 v109, 31, v108
	v_lshlrev_b64 v[144:145], 11, v[108:109]
	v_pk_mul_f32 v[104:105], v[120:121], v[104:105] op_sel_hi:[0,1]
	s_waitcnt vmcnt(5)
	v_lshlrev_b32_e32 v108, 16, v92
	v_and_b32_e32 v109, 0xffff0000, v92
	v_pk_mul_f32 v[104:105], v[104:105], v[108:109]
	s_mov_b32 s1, s39
	v_cvt_pk_bf16_f32 v92, v104, v105
	v_pk_mul_f32 v[104:105], v[120:121], v[106:107] op_sel_hi:[0,1]
	v_lshlrev_b32_e32 v106, 16, v93
	v_and_b32_e32 v107, 0xffff0000, v93
	v_pk_mul_f32 v[104:105], v[104:105], v[106:107]
	v_lshlrev_b32_e32 v106, 16, v94
	v_cvt_pk_bf16_f32 v93, v104, v105
	v_pk_mul_f32 v[104:105], v[120:121], v[112:113] op_sel_hi:[0,1]
	v_and_b32_e32 v107, 0xffff0000, v94
	v_pk_mul_f32 v[104:105], v[104:105], v[106:107]
	v_lshlrev_b32_e32 v106, 16, v95
	v_cvt_pk_bf16_f32 v94, v104, v105
	v_pk_mul_f32 v[104:105], v[120:121], v[114:115] op_sel_hi:[0,1]
	v_and_b32_e32 v107, 0xffff0000, v95
	v_pk_mul_f32 v[104:105], v[104:105], v[106:107]
	v_mov_b32_e32 v163, v157
	v_cvt_pk_bf16_f32 v95, v104, v105
	v_lshl_add_u64 v[104:105], s[24:25], 0, v[144:145]
	v_lshl_add_u64 v[104:105], v[104:105], 0, s[0:1]
	v_lshl_add_u64 v[104:105], v[104:105], 0, v[162:163]
	global_store_dwordx4 v[104:105], v[92:95], off
	s_lshl_b32 s38, s51, 6
	v_mov_b64_e32 v[148:149], s[38:39]
	v_pk_mul_f32 v[92:93], v[120:121], v[116:117] op_sel_hi:[0,1]
	s_waitcnt vmcnt(5)
	v_lshlrev_b32_e32 v94, 16, v88
	v_and_b32_e32 v95, 0xffff0000, v88
	v_pk_mul_f32 v[92:93], v[92:93], v[94:95]
	v_lshlrev_b32_e32 v88, 16, v89
	v_cvt_pk_bf16_f32 v108, v92, v93
	v_pk_mul_f32 v[92:93], v[120:121], v[118:119] op_sel_hi:[0,1]
	v_and_b32_e32 v89, 0xffff0000, v89
	v_pk_mul_f32 v[88:89], v[92:93], v[88:89]
	v_lshlrev_b32_e32 v92, 16, v90
	v_cvt_pk_bf16_f32 v109, v88, v89
	v_pk_mul_f32 v[88:89], v[120:121], v[100:101] op_sel_hi:[0,1]
	v_and_b32_e32 v93, 0xffff0000, v90
	v_pk_mul_f32 v[88:89], v[88:89], v[92:93]
	s_nop 0
	v_cvt_pk_bf16_f32 v110, v88, v89
	v_mul_f32_e32 v88, v120, v102
	v_lshlrev_b32_e32 v102, 16, v91
	v_mov_b32_e32 v89, v120
	v_pk_mul_f32 v[146:147], v[88:89], v[102:103]

; #define LAS __attribute__((address_space(3)))
; template <bool SWA, bool FAST>
; __device__ __forceinline__ void att_tile(const AttnP& P, LAS unsigned char* lds, int lane, int tb, int qpos0, int hq, int kloc0, int r, int ct, int kr0, int kc0, const AttQZ& qz, float shift) {
;     ...
;     const int krow0 = (SWA ? kloc0 : kc0) + li, ksw = (krow0 >> 1) & 7;
;     const LAS unsigned char* kb0 = lds + krow0 * 128 + ((fq ^ ksw) << 4);
;     const LAS unsigned char* kb1 = lds + krow0 * 128 + (((fq + 4) ^ ksw) << 4);
; #pragma unroll
;     for (int s0 = 0; s0 < NSEG; s0 += GS) {
;         bf16x8 kf[GS][2][2];
; #pragma unroll
;         for (int g = 0; g < GS; ++g)
; #pragma unroll
;             for (int kt = 0; kt < 2; ++kt) { const int s = s0 + g;
;                 const int segoff = SWA ? (32 * s + 16 * kt) * 128 : (((kr0 + s) % 9) * 64 + 16 * kt) * 128;
;                 kf[g][kt][0] = *(const LAS bf16x8*)(kb0 + segoff); kf[g][kt][1] = *(const LAS bf16x8*)(kb1 + segoff); }
;         __builtin_amdgcn_sched_barrier(0);
;         __builtin_amdgcn_s_setprio(1);
; #pragma unroll
;         for (int g = 0; g < GS; ++g)
; #pragma unroll
;             for (int kt = 0; kt < 2; ++kt) {
;                 f32x4 z = FAST ? (f32x4){-shift, -shift, -shift, -shift} : (f32x4){0.f, 0.f, 0.f, 0.f};
;                 z = __builtin_amdgcn_mfma_f32_16x16x32_bf16(kf[g][kt][0], bq0, z, 0, 0, 0);
;                 z = __builtin_amdgcn_mfma_f32_16x16x32_bf16(kf[g][kt][1], bq1, z, 0, 0, 0);
;                 sc[s0 + g][kt] = z; }
;         __builtin_amdgcn_s_setprio(0);
;         __builtin_amdgcn_sched_barrier(0);
;     }
.LBB0_359:
	s_lshr_b32 s0, s48, 8
	s_add_i32 s33, s33, s0
	v_sub_u32_e64 v72, s33, 4 clamp
	v_and_b32_e32 v132, 15, v190
	v_readfirstlane_b32 s0, v72
	v_add_u32_e32 v72, s31, v132
	v_lshrrev_b32_e32 v73, 1, v72
	v_lshl_add_u32 v72, v72, 7, 0
	v_bitop3_b32 v74, v73, v183, 7 bitop3:0x6c
	s_lshl_b32 s30, s4, 4
	v_lshl_add_u32 v90, v74, 4, v72
	v_or_b32_e32 v74, 4, v183
	s_min_u32 s34, s0, 56
	s_lshl_b32 s0, s6, 4
	v_bitop3_b32 v73, v73, v74, 7 bitop3:0x6c
	v_or_b32_e32 v134, s30, v132
	s_and_b32 s29, s0, 0xfffff000
	s_lshl_b32 s28, s33, 6
	s_mov_b32 s23, 0
	v_lshl_add_u32 v91, v73, 4, v72
	s_mul_i32 s35, s34, 57
	v_sub_u32_e64 v133, v134, 8 clamp
	s_mov_b64 s[0:1], exec
	v_readlane_b32 s4, v249, 9
	v_readlane_b32 s5, v249, 10
	s_and_b64 s[4:5], s[0:1], s[4:5]
	s_xor_b64 s[20:21], s[4:5], s[0:1]
	s_mov_b64 exec, s[4:5]
	s_cbranch_execz .LBB0_361
	s_lshr_b32 s0, s35, 9
	s_mul_i32 s0, s0, 9
	s_sub_i32 s0, s34, s0
	s_and_b32 s0, s0, 0xff
	s_lshl_b32 s43, s0, 13
	s_add_i32 s0, s35, 57
	s_lshr_b32 s0, s0, 9
	s_mul_i32 s0, s0, 9
	s_sub_i32 s0, s34, s0
	s_add_i32 s0, s0, 1
	s_and_b32 s0, s0, 0xff
	v_add_u32_e32 v76, s43, v90
	v_add_u32_e32 v88, s43, v91
	s_lshl_b32 s41, s0, 13
	ds_read_b128 v[72:75], v76
	ds_read_b128 v[76:79], v76 offset:2048
	ds_read_b128 v[92:95], v88
	ds_read_b128 v[96:99], v88 offset:2048
	v_add_u32_e32 v88, s41, v90
	v_add_u32_e32 v89, s41, v91
	ds_read_b128 v[100:103], v88
	ds_read_b128 v[104:107], v88 offset:2048
	ds_read_b128 v[108:111], v89
	ds_read_b128 v[112:115], v89 offset:2048
	s_waitcnt vmcnt(4) lgkmcnt(7)
	v_mfma_f32_16x16x32_bf16 v[72:75], v[72:75], v[84:87], 0
	s_waitcnt vmcnt(3) lgkmcnt(5)
	v_mfma_f32_16x16x32_bf16 v[136:139], v[92:95], v[80:83], v[72:75]
	v_mfma_f32_16x16x32_bf16 v[72:75], v[76:79], v[84:87], 0
	s_waitcnt lgkmcnt(4)
	v_mfma_f32_16x16x32_bf16 v[140:143], v[96:99], v[80:83], v[72:75]
	s_waitcnt lgkmcnt(3)
	v_mfma_f32_16x16x32_bf16 v[72:75], v[100:103], v[84:87], 0
	s_waitcnt lgkmcnt(1)
	v_mfma_f32_16x16x32_bf16 v[144:147], v[108:111], v[80:83], v[72:75]
	v_mfma_f32_16x16x32_bf16 v[72:75], v[104:107], v[84:87], 0
	s_waitcnt lgkmcnt(0)
	v_mfma_f32_16x16x32_bf16 v[124:127], v[112:115], v[80:83], v[72:75]
	s_add_i32 s0, s35, 0x72
	s_lshr_b32 s0, s0, 9
	s_mul_i32 s0, s0, 9
	s_sub_i32 s0, s34, s0
	s_add_i32 s0, s0, 2
	s_and_b32 s0, s0, 0xff
	s_lshl_b32 s40, s0, 13
	s_add_i32 s0, s35, 0xab
	s_lshr_b32 s0, s0, 9
	s_mul_i32 s0, s0, 9
	s_sub_i32 s0, s34, s0
	s_add_i32 s0, s0, 3
	s_and_b32 s0, s0, 0xff
	v_add_u32_e32 v76, s40, v90
	v_add_u32_e32 v88, s40, v91
	s_lshl_b32 s39, s0, 13
	ds_read_b128 v[72:75], v76
	ds_read_b128 v[76:79], v76 offset:2048
	ds_read_b128 v[92:95], v88
	ds_read_b128 v[96:99], v88 offset:2048
	v_add_u32_e32 v88, s39, v90
	v_add_u32_e32 v89, s39, v91
	ds_read_b128 v[100:103], v88
	ds_read_b128 v[104:107], v88 offset:2048
	ds_read_b128 v[108:111], v89
	ds_read_b128 v[112:115], v89 offset:2048
	s_waitcnt lgkmcnt(7)
	v_mfma_f32_16x16x32_bf16 v[72:75], v[72:75], v[84:87], 0
	s_waitcnt lgkmcnt(5)
	v_mfma_f32_16x16x32_bf16 v[128:131], v[92:95], v[80:83], v[72:75]
	v_mfma_f32_16x16x32_bf16 v[72:75], v[76:79], v[84:87], 0
	s_waitcnt lgkmcnt(4)
	v_mfma_f32_16x16x32_bf16 v[120:123], v[96:99], v[80:83], v[72:75]
	s_waitcnt lgkmcnt(3)
	v_mfma_f32_16x16x32_bf16 v[72:75], v[100:103], v[84:87], 0
	s_waitcnt lgkmcnt(1)
	v_mfma_f32_16x16x32_bf16 v[116:119], v[108:111], v[80:83], v[72:75]
	v_mfma_f32_16x16x32_bf16 v[72:75], v[104:107], v[84:87], 0
	s_waitcnt lgkmcnt(0)
	v_mfma_f32_16x16x32_bf16 v[108:111], v[112:115], v[80:83], v[72:75]
	s_add_i32 s0, s35, 0xe4
	s_lshr_b32 s0, s0, 9
	s_mul_i32 s0, s0, 9
	s_sub_i32 s0, s34, s0
	s_add_i32 s0, s0, 4
	s_and_b32 s0, s0, 0xff
	s_lshl_b32 s38, s0, 13
	s_add_i32 s0, s35, 0x11d
	s_lshr_b32 s0, s0, 9
	s_mul_i32 s0, s0, 9
	s_sub_i32 s0, s34, s0
	s_add_i32 s0, s0, 5
	s_and_b32 s0, s0, 0xff
	v_add_u32_e32 v76, s38, v90
	v_add_u32_e32 v88, s38, v91
	s_lshl_b32 s37, s0, 13
	ds_read_b128 v[72:75], v76
	ds_read_b128 v[76:79], v76 offset:2048
	ds_read_b128 v[92:95], v88
	ds_read_b128 v[96:99], v88 offset:2048
	v_add_u32_e32 v88, s37, v90
	v_add_u32_e32 v89, s37, v91
	ds_read_b128 v[100:103], v88
	ds_read_b128 v[148:151], v88 offset:2048
	ds_read_b128 v[154:157], v89
	ds_read_b128 v[158:161], v89 offset:2048
	s_waitcnt lgkmcnt(7)
	v_mfma_f32_16x16x32_bf16 v[72:75], v[72:75], v[84:87], 0
	s_waitcnt lgkmcnt(5)
	v_mfma_f32_16x16x32_bf16 v[112:115], v[92:95], v[80:83], v[72:75]
	v_mfma_f32_16x16x32_bf16 v[72:75], v[76:79], v[84:87], 0
	s_waitcnt lgkmcnt(4)
	v_mfma_f32_16x16x32_bf16 v[104:107], v[96:99], v[80:83], v[72:75]
	s_waitcnt lgkmcnt(3)
	v_mfma_f32_16x16x32_bf16 v[72:75], v[100:103], v[84:87], 0
	s_waitcnt lgkmcnt(1)
	v_mfma_f32_16x16x32_bf16 v[100:103], v[154:157], v[80:83], v[72:75]
	v_mfma_f32_16x16x32_bf16 v[72:75], v[148:151], v[84:87], 0
	s_waitcnt lgkmcnt(0)
	v_mfma_f32_16x16x32_bf16 v[92:95], v[158:161], v[80:83], v[72:75]
	s_add_i32 s0, s35, 0x156
	s_lshr_b32 s0, s0, 9
	s_mul_i32 s0, s0, 9
	s_sub_i32 s0, s34, s0
	s_add_i32 s0, s0, 6
	s_and_b32 s0, s0, 0xff
	s_lshl_b32 s36, s0, 13
	s_add_i32 s0, s35, 0x18f
	s_lshr_b32 s0, s0, 9
	s_mul_i32 s0, s0, 9
	s_sub_i32 s0, s34, s0
	s_add_i32 s0, s0, 7
	s_and_b32 s0, s0, 0xff
	v_add_u32_e32 v76, s36, v90
	v_add_u32_e32 v88, s36, v91
	s_lshl_b32 s22, s0, 13
	ds_read_b128 v[72:75], v76
	ds_read_b128 v[76:79], v76 offset:2048
	ds_read_b128 v[96:99], v88
	ds_read_b128 v[148:151], v88 offset:2048
	v_add_u32_e32 v88, s22, v90
	v_add_u32_e32 v89, s22, v91
	ds_read_b128 v[154:157], v88
	ds_read_b128 v[158:161], v88 offset:2048
	ds_read_b128 v[162:165], v89
	ds_read_b128 v[166:169], v89 offset:2048
	s_waitcnt lgkmcnt(7)
; #define LAS __attribute__((address_space(3)))
; template <bool SWA, bool FAST>
; __device__ __forceinline__ void att_tile(const AttnP& P, LAS unsigned char* lds, int lane, int tb, int qpos0, int hq, int kloc0, int r, int ct, int kr0, int kc0, const AttQZ& qz, float shift) {
;     ...
;                 z = __builtin_amdgcn_mfma_f32_16x16x32_bf16(kf[g][kt][0], bq0, z, 0, 0, 0);
;                 z = __builtin_amdgcn_mfma_f32_16x16x32_bf16(kf[g][kt][1], bq1, z, 0, 0, 0);
;                 sc[s0 + g][kt] = z; }
;         __builtin_amdgcn_s_setprio(0);
;         __builtin_amdgcn_sched_barrier(0);
;     }
;     ...
;     } else if (!FAST) {
;         const int c = 16 * ct + li, cs = min(max(c - 8, 0), 48);
;         const LAS float* rp = (const LAS float*)(lds + ATT_RPB) + (kr0 - r + 7) * 64 + (kc0 + 4 * fq - c + 31);
; #pragma unroll
;         for (int s = 0; s < NSEG; ++s) {
;             float bias[2][4];
; #pragma unroll
;             for (int kt = 0; kt < 2; ++kt)
; #pragma unroll
;                 for (int j = 0; j < 4; ++j) bias[kt][j] = rp[s * 64 + 16 * kt + j];
; #pragma unroll
;             for (int kt = 0; kt < 2; ++kt)
; #pragma unroll
;                 for (int j = 0; j < 4; ++j) { const int kc = kc0 + 16 * kt + 4 * fq + j; const bool ok = (kc >= cs) && (kc < cs + 16);
;                     float t = sc[s][kt][j] + bias[kt][j]; asm volatile("" : "+v"(t));
;                     const float v = ok ? t : -1e30f; sc[s][kt][j] = v; if (!FAST) mx = fmaxf(mx, v); }
;         }
	v_mfma_f32_16x16x32_bf16 v[72:75], v[72:75], v[84:87], 0
	s_waitcnt lgkmcnt(5)
	v_mfma_f32_16x16x32_bf16 v[96:99], v[96:99], v[80:83], v[72:75]
	v_mfma_f32_16x16x32_bf16 v[72:75], v[76:79], v[84:87], 0
	s_waitcnt lgkmcnt(4)
	v_mfma_f32_16x16x32_bf16 v[88:91], v[148:151], v[80:83], v[72:75]
	s_waitcnt lgkmcnt(3)
	v_mfma_f32_16x16x32_bf16 v[72:75], v[154:157], v[84:87], 0
	s_waitcnt lgkmcnt(1)
	v_mfma_f32_16x16x32_bf16 v[76:79], v[162:165], v[80:83], v[72:75]
	v_mfma_f32_16x16x32_bf16 v[72:75], v[158:161], v[84:87], 0
	s_waitcnt lgkmcnt(0)
	v_mfma_f32_16x16x32_bf16 v[72:75], v[166:169], v[80:83], v[72:75]
	s_sub_i32 s0, s34, s33
	s_lshl_b32 s0, s0, 8
	v_min_u32_e32 v135, 48, v133
	s_add_i32 s0, s0, 0
	v_lshl_add_u32 v133, v183, 2, s31
	s_add_i32 s0, s0, 0x24000
	v_sub_u32_e32 v80, v133, v134
	v_lshl_add_u32 v134, v80, 2, s0
	v_add_u32_e32 v80, 0x77c, v134
	v_add_u32_e32 v81, 16, v133
	v_add_u32_e32 v82, 0x784, v134
	v_add_u32_e32 v84, 0x7bc, v134
	v_add_u32_e32 v86, 0x7c4, v134
	v_cmp_ge_u32_e64 s[6:7], v81, v135
	ds_read2_b32 v[80:81], v80 offset1:1
	ds_read2_b32 v[82:83], v82 offset1:1
	ds_read2_b32 v[84:85], v84 offset1:1
	ds_read2_b32 v[86:87], v86 offset1:1
	v_add_u32_e32 v148, 16, v135
	v_cmp_ge_u32_e32 vcc, v133, v135
	v_cmp_lt_u32_e64 s[0:1], v133, v148
	s_waitcnt lgkmcnt(3)
	v_add_f32_e32 v80, v136, v80
	v_mov_b32_e32 v136, 0xf149f2ca
	s_and_b64 vcc, vcc, s[0:1]
	v_cndmask_b32_e32 v149, v136, v80, vcc
	v_or_b32_e32 v80, 1, v133
	v_cmp_ge_u32_e64 s[0:1], v80, v135
	v_cmp_lt_u32_e64 s[4:5], v80, v148
	v_add_f32_e32 v80, v137, v81
	s_and_b64 s[0:1], s[0:1], s[4:5]
	s_mov_b32 s10, 0xf149f2ca
	v_or_b32_e32 v81, 2, v133
	v_cndmask_b32_e64 v137, v136, v80, s[0:1]
	v_max3_f32 v80, v149, s10, v137
	v_cmp_ge_u32_e64 s[4:5], v81, v135
	v_cmp_lt_u32_e64 s[10:11], v81, v148
	s_waitcnt lgkmcnt(2)
	v_add_f32_e32 v81, v138, v82
	s_and_b64 s[14:15], s[4:5], s[10:11]
	v_cndmask_b32_e64 v138, v136, v81, s[14:15]
	v_or_b32_e32 v81, 3, v133
	v_cmp_ge_u32_e64 s[4:5], v81, v135
	v_cmp_lt_u32_e64 s[10:11], v81, v148
	v_add_f32_e32 v81, v139, v83
	s_and_b64 s[4:5], s[4:5], s[10:11]
	v_cmp_lt_u32_e64 s[8:9], v133, v135
	v_cndmask_b32_e64 v139, v136, v81, s[4:5]
	s_waitcnt lgkmcnt(1)
	v_add_f32_e32 v81, v140, v84
	s_and_b64 s[6:7], s[6:7], s[8:9]
	v_cndmask_b32_e64 v140, v136, v81, s[6:7]
	v_add_u32_e32 v81, 17, v133
	v_cmp_ge_u32_e64 s[8:9], v81, v135
	v_cmp_lt_u32_e64 s[10:11], v81, v148
	v_add_f32_e32 v81, v141, v85
	s_and_b64 s[8:9], s[8:9], s[10:11]
	v_cndmask_b32_e64 v141, v136, v81, s[8:9]
	v_add_u32_e32 v81, 18, v133
	v_cmp_ge_u32_e64 s[10:11], v81, v135
	v_cmp_lt_u32_e64 s[12:13], v81, v148
	s_waitcnt lgkmcnt(0)
	v_add_f32_e32 v81, v142, v86
	s_and_b64 s[10:11], s[10:11], s[12:13]
	v_cndmask_b32_e64 v142, v136, v81, s[10:11]
	v_add_u32_e32 v81, 19, v133
	v_cmp_ge_u32_e64 s[12:13], v81, v135
	v_cmp_lt_u32_e64 s[16:17], v81, v148
	v_max3_f32 v80, v80, v138, v139
	v_add_f32_e32 v81, v143, v87
	s_and_b64 s[12:13], s[12:13], s[16:17]
	v_max3_f32 v80, v80, v140, v141
	v_add_u32_e32 v82, 0x884, v134
	v_cndmask_b32_e64 v135, v136, v81, s[12:13]
	v_max3_f32 v143, v80, v142, v135
	v_add_u32_e32 v80, 0x87c, v134
	ds_read2_b32 v[80:81], v80 offset1:1
	v_add_u32_e32 v84, 0x8bc, v134
	v_add_u32_e32 v86, 0x8c4, v134
	ds_read2_b32 v[82:83], v82 offset1:1
	ds_read2_b32 v[84:85], v84 offset1:1
	ds_read2_b32 v[86:87], v86 offset1:1
	s_waitcnt lgkmcnt(3)
	v_add_f32_e32 v80, v144, v80
	s_nop 0
	v_cndmask_b32_e32 v144, v136, v80, vcc
	v_add_f32_e32 v80, v145, v81
	s_waitcnt lgkmcnt(2)
	v_add_f32_e32 v81, v146, v82
	v_add_u32_e32 v82, 0x984, v134
	v_cndmask_b32_e64 v145, v136, v80, s[0:1]
	v_max3_f32 v80, v143, v144, v145
	v_cndmask_b32_e64 v143, v136, v81, s[14:15]
	v_add_f32_e32 v81, v147, v83
	s_nop 0
	v_cndmask_b32_e64 v146, v136, v81, s[4:5]
	s_waitcnt lgkmcnt(1)
	v_add_f32_e32 v81, v124, v84
	v_max3_f32 v80, v80, v143, v146
	v_cndmask_b32_e64 v124, v136, v81, s[6:7]
	v_add_f32_e32 v81, v125, v85
	v_add_u32_e32 v84, 0x9bc, v134
	v_cndmask_b32_e64 v125, v136, v81, s[8:9]
	s_waitcnt lgkmcnt(0)
	v_add_f32_e32 v81, v126, v86
	v_max3_f32 v80, v80, v124, v125
	v_cndmask_b32_e64 v126, v136, v81, s[10:11]
	v_add_f32_e32 v81, v127, v87
	v_add_u32_e32 v86, 0x9c4, v134
	v_cndmask_b32_e64 v127, v136, v81, s[12:13]
	v_max3_f32 v147, v80, v126, v127
	v_add_u32_e32 v80, 0x97c, v134
	ds_read2_b32 v[80:81], v80 offset1:1
	ds_read2_b32 v[82:83], v82 offset1:1
	ds_read2_b32 v[84:85], v84 offset1:1
	ds_read2_b32 v[86:87], v86 offset1:1
	s_waitcnt lgkmcnt(3)
	v_add_f32_e32 v80, v128, v80
	s_nop 0
	v_cndmask_b32_e32 v128, v136, v80, vcc
	v_add_f32_e32 v80, v129, v81
	s_waitcnt lgkmcnt(2)
	v_add_f32_e32 v81, v130, v82
	v_add_u32_e32 v82, 0xa84, v134
	v_cndmask_b32_e64 v130, v136, v81, s[14:15]
	v_add_f32_e32 v81, v131, v83
	v_cndmask_b32_e64 v129, v136, v80, s[0:1]
	v_cndmask_b32_e64 v131, v136, v81, s[4:5]
	s_waitcnt lgkmcnt(1)
	v_add_f32_e32 v81, v120, v84
	v_max3_f32 v80, v147, v128, v129
	v_cndmask_b32_e64 v120, v136, v81, s[6:7]
	v_add_f32_e32 v81, v121, v85
	v_max3_f32 v80, v80, v130, v131
	v_cndmask_b32_e64 v121, v136, v81, s[8:9]
	s_waitcnt lgkmcnt(0)
	v_add_f32_e32 v81, v122, v86
	v_max3_f32 v80, v80, v120, v121
	v_cndmask_b32_e64 v122, v136, v81, s[10:11]
	v_add_f32_e32 v81, v123, v87
	v_add_u32_e32 v84, 0xabc, v134
	v_cndmask_b32_e64 v123, v136, v81, s[12:13]
	v_max3_f32 v147, v80, v122, v123
	v_add_u32_e32 v80, 0xa7c, v134
	ds_read2_b32 v[80:81], v80 offset1:1
	v_add_u32_e32 v86, 0xac4, v134
	ds_read2_b32 v[82:83], v82 offset1:1
	ds_read2_b32 v[84:85], v84 offset1:1
	ds_read2_b32 v[86:87], v86 offset1:1
	s_waitcnt lgkmcnt(3)
; #define LAS __attribute__((address_space(3)))
; template <bool SWA, bool FAST>
; __device__ __forceinline__ void att_tile(const AttnP& P, LAS unsigned char* lds, int lane, int tb, int qpos0, int hq, int kloc0, int r, int ct, int kr0, int kc0, const AttQZ& qz, float shift) {
;     ...
;     } else if (!FAST) {
;         const int c = 16 * ct + li, cs = min(max(c - 8, 0), 48);
;         const LAS float* rp = (const LAS float*)(lds + ATT_RPB) + (kr0 - r + 7) * 64 + (kc0 + 4 * fq - c + 31);
; #pragma unroll
;         for (int s = 0; s < NSEG; ++s) {
;             float bias[2][4];
; #pragma unroll
;             for (int kt = 0; kt < 2; ++kt)
; #pragma unroll
;                 for (int j = 0; j < 4; ++j) bias[kt][j] = rp[s * 64 + 16 * kt + j];
; #pragma unroll
;             for (int kt = 0; kt < 2; ++kt)
; #pragma unroll
;                 for (int j = 0; j < 4; ++j) { const int kc = kc0 + 16 * kt + 4 * fq + j; const bool ok = (kc >= cs) && (kc < cs + 16);
;                     float t = sc[s][kt][j] + bias[kt][j]; asm volatile("" : "+v"(t));
;                     const float v = ok ? t : -1e30f; sc[s][kt][j] = v; if (!FAST) mx = fmaxf(mx, v); }
;         }
;     }
;     if (!FAST) { mx = fmaxf(mx, __shfl_xor(mx, 16)); mx = fmaxf(mx, __shfl_xor(mx, 32)); }
	v_add_f32_e32 v80, v116, v80
	s_nop 0
	v_cndmask_b32_e32 v116, v136, v80, vcc
	v_add_f32_e32 v80, v117, v81
	s_waitcnt lgkmcnt(2)
	v_add_f32_e32 v81, v118, v82
	v_add_u32_e32 v82, 0xb84, v134
	v_cndmask_b32_e64 v118, v136, v81, s[14:15]
	v_add_f32_e32 v81, v119, v83
	v_cndmask_b32_e64 v117, v136, v80, s[0:1]
	v_cndmask_b32_e64 v119, v136, v81, s[4:5]
	s_waitcnt lgkmcnt(1)
	v_add_f32_e32 v81, v108, v84
	v_max3_f32 v80, v147, v116, v117
	v_cndmask_b32_e64 v108, v136, v81, s[6:7]
	v_add_f32_e32 v81, v109, v85
	v_max3_f32 v80, v80, v118, v119
	v_cndmask_b32_e64 v109, v136, v81, s[8:9]
	s_waitcnt lgkmcnt(0)
	v_add_f32_e32 v81, v110, v86
	v_max3_f32 v80, v80, v108, v109
	v_cndmask_b32_e64 v110, v136, v81, s[10:11]
	v_add_f32_e32 v81, v111, v87
	v_add_u32_e32 v84, 0xbbc, v134
	v_cndmask_b32_e64 v111, v136, v81, s[12:13]
	v_max3_f32 v147, v80, v110, v111
	v_add_u32_e32 v80, 0xb7c, v134
	ds_read2_b32 v[80:81], v80 offset1:1
	v_add_u32_e32 v86, 0xbc4, v134
	ds_read2_b32 v[82:83], v82 offset1:1
	ds_read2_b32 v[84:85], v84 offset1:1
	ds_read2_b32 v[86:87], v86 offset1:1
	s_waitcnt lgkmcnt(3)
	v_add_f32_e32 v80, v112, v80
	s_nop 0
	v_cndmask_b32_e32 v112, v136, v80, vcc
	v_add_f32_e32 v80, v113, v81
	s_waitcnt lgkmcnt(2)
	v_add_f32_e32 v81, v114, v82
	v_add_u32_e32 v82, 0xc84, v134
	v_cndmask_b32_e64 v114, v136, v81, s[14:15]
	v_add_f32_e32 v81, v115, v83
	v_cndmask_b32_e64 v113, v136, v80, s[0:1]
	v_cndmask_b32_e64 v115, v136, v81, s[4:5]
	s_waitcnt lgkmcnt(1)
	v_add_f32_e32 v81, v104, v84
	v_max3_f32 v80, v147, v112, v113
	v_cndmask_b32_e64 v104, v136, v81, s[6:7]
	v_add_f32_e32 v81, v105, v85
	v_max3_f32 v80, v80, v114, v115
	v_cndmask_b32_e64 v105, v136, v81, s[8:9]
	s_waitcnt lgkmcnt(0)
	v_add_f32_e32 v81, v106, v86
	v_max3_f32 v80, v80, v104, v105
	v_cndmask_b32_e64 v106, v136, v81, s[10:11]
	v_add_f32_e32 v81, v107, v87
	v_add_u32_e32 v84, 0xcbc, v134
	v_cndmask_b32_e64 v107, v136, v81, s[12:13]
	v_max3_f32 v147, v80, v106, v107
	v_add_u32_e32 v80, 0xc7c, v134
	ds_read2_b32 v[80:81], v80 offset1:1
	v_add_u32_e32 v86, 0xcc4, v134
	ds_read2_b32 v[82:83], v82 offset1:1
	ds_read2_b32 v[84:85], v84 offset1:1
	ds_read2_b32 v[86:87], v86 offset1:1
	s_waitcnt lgkmcnt(3)
	v_add_f32_e32 v80, v100, v80
	s_nop 0
	v_cndmask_b32_e32 v100, v136, v80, vcc
	v_add_f32_e32 v80, v101, v81
	s_waitcnt lgkmcnt(2)
	v_add_f32_e32 v81, v102, v82
	v_add_u32_e32 v82, 0xd84, v134
	v_cndmask_b32_e64 v102, v136, v81, s[14:15]
	v_add_f32_e32 v81, v103, v83
	v_cndmask_b32_e64 v101, v136, v80, s[0:1]
	v_cndmask_b32_e64 v103, v136, v81, s[4:5]
	s_waitcnt lgkmcnt(1)
	v_add_f32_e32 v81, v92, v84
	v_max3_f32 v80, v147, v100, v101
	v_cndmask_b32_e64 v147, v136, v81, s[6:7]
	v_add_f32_e32 v81, v93, v85
	v_max3_f32 v80, v80, v102, v103
	v_cndmask_b32_e64 v148, v136, v81, s[8:9]
	s_waitcnt lgkmcnt(0)
	v_add_f32_e32 v81, v94, v86
	v_max3_f32 v80, v80, v147, v148
	v_cndmask_b32_e64 v150, v136, v81, s[10:11]
	v_add_f32_e32 v81, v95, v87
	v_add_u32_e32 v84, 0xdbc, v134
	v_cndmask_b32_e64 v151, v136, v81, s[12:13]
	v_max3_f32 v92, v80, v150, v151
	v_add_u32_e32 v80, 0xd7c, v134
	ds_read2_b32 v[80:81], v80 offset1:1
	v_add_u32_e32 v86, 0xdc4, v134
	ds_read2_b32 v[82:83], v82 offset1:1
	ds_read2_b32 v[84:85], v84 offset1:1
	ds_read2_b32 v[86:87], v86 offset1:1
	s_waitcnt lgkmcnt(3)
	v_add_f32_e32 v80, v96, v80
	s_nop 0
	v_cndmask_b32_e32 v154, v136, v80, vcc
	v_add_f32_e32 v80, v97, v81
	s_waitcnt lgkmcnt(2)
	v_add_f32_e32 v81, v98, v82
	v_add_u32_e32 v82, 0xe84, v134
	v_cndmask_b32_e64 v156, v136, v81, s[14:15]
	v_add_f32_e32 v81, v99, v83
	v_cndmask_b32_e64 v155, v136, v80, s[0:1]
	v_cndmask_b32_e64 v157, v136, v81, s[4:5]
	s_waitcnt lgkmcnt(1)
	v_add_f32_e32 v81, v88, v84
	v_max3_f32 v80, v92, v154, v155
	v_cndmask_b32_e64 v158, v136, v81, s[6:7]
	v_add_f32_e32 v81, v89, v85
	v_max3_f32 v80, v80, v156, v157
	v_cndmask_b32_e64 v159, v136, v81, s[8:9]
	s_waitcnt lgkmcnt(0)
	v_add_f32_e32 v81, v90, v86
	v_max3_f32 v80, v80, v158, v159
	v_cndmask_b32_e64 v160, v136, v81, s[10:11]
	v_add_f32_e32 v81, v91, v87
	v_add_u32_e32 v84, 0xebc, v134
	v_cndmask_b32_e64 v161, v136, v81, s[12:13]
	v_max3_f32 v88, v80, v160, v161
	v_add_u32_e32 v80, 0xe7c, v134
	ds_read2_b32 v[80:81], v80 offset1:1
	v_add_u32_e32 v86, 0xec4, v134
	ds_read2_b32 v[82:83], v82 offset1:1
	ds_read2_b32 v[84:85], v84 offset1:1
	ds_read2_b32 v[86:87], v86 offset1:1
	s_waitcnt lgkmcnt(3)
	v_add_f32_e32 v76, v76, v80
	s_waitcnt lgkmcnt(1)
	v_add_f32_e32 v72, v72, v84
	v_cndmask_b32_e32 v134, v136, v76, vcc
	v_add_f32_e32 v76, v77, v81
	v_add_f32_e32 v77, v78, v82
	s_nop 0
	v_cndmask_b32_e64 v163, v136, v77, s[14:15]
	v_add_f32_e32 v77, v79, v83
	v_cndmask_b32_e64 v162, v136, v76, s[0:1]
	v_cndmask_b32_e64 v165, v136, v72, s[6:7]
	v_add_f32_e32 v72, v73, v85
	s_waitcnt lgkmcnt(0)
	v_add_f32_e32 v73, v74, v86
	v_max3_f32 v76, v88, v134, v162
	v_cndmask_b32_e64 v164, v136, v77, s[4:5]
	v_max3_f32 v76, v76, v163, v164
	v_cndmask_b32_e64 v166, v136, v72, s[8:9]
	v_cndmask_b32_e64 v167, v136, v73, s[10:11]
	v_add_f32_e32 v73, v75, v87
	v_max3_f32 v72, v76, v165, v166
	s_nop 0
	v_cndmask_b32_e64 v136, v136, v73, s[12:13]
	v_max3_f32 v72, v72, v167, v136
	ds_bpermute_b32 v73, v180, v72
	s_waitcnt lgkmcnt(0)
	v_max_f32_e32 v73, v73, v73
	v_max_f32_e32 v72, v72, v73
	ds_bpermute_b32 v73, v181, v72
	s_waitcnt lgkmcnt(0)
; __device__ __forceinline__ unsigned cvt_pk_bf16(float lo, float hi) { const f32x2_t v = {lo, hi}; const bf16x2_t r = __builtin_convertvector(v, bf16x2_t); return __builtin_bit_cast(unsigned, r); }
; template <bool SWA, bool FAST>
; __device__ __forceinline__ void att_tile(const AttnP& P, LAS unsigned char* lds, int lane, int tb, int qpos0, int hq, int kloc0, int r, int ct, int kr0, int kc0, const AttQZ& qz, float shift) {
;     ...
; #pragma unroll
;     for (int s = 0; s < NSEG; ++s) {
;         float p[8];
; #pragma unroll
;         for (int kt = 0; kt < 2; ++kt)
; #pragma unroll
;             for (int j = 0; j < 4; ++j) p[4 * kt + j] = __builtin_amdgcn_exp2f(FAST ? sc[s][kt][j] : sc[s][kt][j] - mx);
; #pragma unroll
;         for (int e = 0; e < 8; e += 2) l2 += (f32x2_t){p[e], p[e + 1]};
;         u32x4 w; w.x = cvt_pk_bf16(p[0], p[1]); w.y = cvt_pk_bf16(p[2], p[3]); w.z = cvt_pk_bf16(p[4], p[5]); w.w = cvt_pk_bf16(p[6], p[7]);
;         pb[s] = __builtin_bit_cast(bf16x8, w);
;     }
;     l += l2[0] + l2[1];
;     l += __shfl_xor(l, 16); l += __shfl_xor(l, 32);
	v_max_f32_e32 v73, v73, v73
	v_max_f32_e32 v168, v72, v73
	v_sub_f32_e32 v72, v149, v168
	v_sub_f32_e32 v73, v137, v168
	v_exp_f32_e32 v72, v72
	v_exp_f32_e32 v73, v73
	v_sub_f32_e32 v74, v138, v168
	v_sub_f32_e32 v75, v139, v168
	v_exp_f32_e32 v74, v74
	v_exp_f32_e32 v75, v75
	v_sub_f32_e32 v76, v140, v168
	v_sub_f32_e32 v77, v141, v168
	v_exp_f32_e32 v76, v76
	v_exp_f32_e32 v77, v77
	v_sub_f32_e32 v78, v142, v168
	v_sub_f32_e32 v79, v135, v168
	v_exp_f32_e32 v78, v78
	v_exp_f32_e32 v79, v79
	v_pk_add_f32 v[80:81], v[72:73], 0 op_sel_hi:[1,0]
	v_cvt_pk_bf16_f32 v82, v76, v77
	v_pk_add_f32 v[80:81], v[74:75], v[80:81]
	v_cvt_pk_bf16_f32 v83, v78, v79
	v_pk_add_f32 v[80:81], v[76:77], v[80:81]
	v_sub_f32_e32 v76, v124, v168
	v_pk_add_f32 v[84:85], v[78:79], v[80:81]
	v_cvt_pk_bf16_f32 v80, v72, v73
	v_sub_f32_e32 v72, v144, v168
	v_sub_f32_e32 v73, v145, v168
	v_cvt_pk_bf16_f32 v81, v74, v75
	v_exp_f32_e32 v72, v72
	v_exp_f32_e32 v73, v73
	v_sub_f32_e32 v74, v143, v168
	v_sub_f32_e32 v75, v146, v168
	v_exp_f32_e32 v74, v74
	v_exp_f32_e32 v75, v75
	v_sub_f32_e32 v77, v125, v168
	v_exp_f32_e32 v76, v76
	v_exp_f32_e32 v77, v77
	v_sub_f32_e32 v78, v126, v168
	v_sub_f32_e32 v79, v127, v168
	v_exp_f32_e32 v78, v78
	v_exp_f32_e32 v79, v79
	v_pk_add_f32 v[84:85], v[72:73], v[84:85]
	v_cvt_pk_bf16_f32 v96, v72, v73
	v_pk_add_f32 v[84:85], v[74:75], v[84:85]
	v_cvt_pk_bf16_f32 v98, v76, v77
	v_pk_add_f32 v[84:85], v[76:77], v[84:85]
	v_sub_f32_e32 v72, v128, v168
	v_sub_f32_e32 v73, v129, v168
	v_sub_f32_e32 v76, v120, v168
	v_pk_add_f32 v[84:85], v[78:79], v[84:85]
	v_cvt_pk_bf16_f32 v97, v74, v75
	v_cvt_pk_bf16_f32 v99, v78, v79
	v_exp_f32_e32 v72, v72
	v_exp_f32_e32 v73, v73
	v_sub_f32_e32 v74, v130, v168
	v_sub_f32_e32 v75, v131, v168
	v_exp_f32_e32 v78, v76
	v_sub_f32_e32 v76, v121, v168
	v_exp_f32_e32 v74, v74
	v_exp_f32_e32 v75, v75
	v_exp_f32_e32 v79, v76
	v_sub_f32_e32 v76, v122, v168
	v_exp_f32_e32 v86, v76
	v_sub_f32_e32 v76, v123, v168
	v_exp_f32_e32 v87, v76
	v_pk_add_f32 v[76:77], v[72:73], v[84:85]
	v_sub_f32_e32 v88, v110, v168
	v_pk_add_f32 v[76:77], v[74:75], v[76:77]
	v_exp_f32_e32 v92, v88
	v_pk_add_f32 v[76:77], v[78:79], v[76:77]
	v_cvt_pk_bf16_f32 v78, v78, v79
	v_pk_add_f32 v[84:85], v[86:87], v[76:77]
	v_cvt_pk_bf16_f32 v76, v72, v73
	v_sub_f32_e32 v72, v116, v168
	v_sub_f32_e32 v73, v117, v168
	v_cvt_pk_bf16_f32 v77, v74, v75
	v_exp_f32_e32 v72, v72
	v_exp_f32_e32 v73, v73
	v_sub_f32_e32 v74, v118, v168
	v_sub_f32_e32 v75, v119, v168
	v_cvt_pk_bf16_f32 v79, v86, v87
	v_exp_f32_e32 v74, v74
	v_exp_f32_e32 v75, v75
	v_sub_f32_e32 v86, v108, v168
	v_sub_f32_e32 v87, v109, v168
	v_exp_f32_e32 v86, v86
	v_exp_f32_e32 v87, v87
	v_sub_f32_e32 v88, v111, v168
	v_exp_f32_e32 v93, v88
	v_pk_add_f32 v[84:85], v[72:73], v[84:85]
	v_cvt_pk_bf16_f32 v88, v72, v73
	v_sub_f32_e32 v72, v112, v168
	v_sub_f32_e32 v73, v113, v168
	v_pk_add_f32 v[84:85], v[74:75], v[84:85]
	v_cvt_pk_bf16_f32 v89, v74, v75
	v_exp_f32_e32 v72, v72
	v_exp_f32_e32 v73, v73
	v_sub_f32_e32 v74, v114, v168
	v_sub_f32_e32 v75, v115, v168
	v_pk_add_f32 v[84:85], v[86:87], v[84:85]
	v_cvt_pk_bf16_f32 v90, v86, v87
	v_exp_f32_e32 v74, v74
	v_exp_f32_e32 v75, v75
	v_sub_f32_e32 v86, v104, v168
	v_sub_f32_e32 v87, v105, v168
	v_pk_add_f32 v[84:85], v[92:93], v[84:85]
	v_cvt_pk_bf16_f32 v91, v92, v93
	v_exp_f32_e32 v86, v86
	v_exp_f32_e32 v87, v87
	v_sub_f32_e32 v92, v106, v168
	v_sub_f32_e32 v93, v107, v168
	v_exp_f32_e32 v92, v92
	v_exp_f32_e32 v93, v93
	v_pk_add_f32 v[84:85], v[72:73], v[84:85]
	v_cvt_pk_bf16_f32 v72, v72, v73
	v_pk_add_f32 v[84:85], v[74:75], v[84:85]
	v_cvt_pk_bf16_f32 v73, v74, v75
	v_pk_add_f32 v[84:85], v[86:87], v[84:85]
	v_cvt_pk_bf16_f32 v74, v86, v87
	v_sub_f32_e32 v86, v100, v168
	v_sub_f32_e32 v87, v101, v168
	v_pk_add_f32 v[84:85], v[92:93], v[84:85]
	v_cvt_pk_bf16_f32 v75, v92, v93
	v_exp_f32_e32 v86, v86
	v_exp_f32_e32 v87, v87
	v_sub_f32_e32 v92, v102, v168
	v_sub_f32_e32 v93, v103, v168
	v_exp_f32_e32 v92, v92
	v_exp_f32_e32 v93, v93
	v_sub_f32_e32 v94, v147, v168
	v_sub_f32_e32 v95, v148, v168
	v_exp_f32_e32 v94, v94
	v_exp_f32_e32 v95, v95
	v_sub_f32_e32 v100, v150, v168
	v_sub_f32_e32 v101, v151, v168
	v_exp_f32_e32 v100, v100
	v_exp_f32_e32 v101, v101
	v_pk_add_f32 v[84:85], v[86:87], v[84:85]
	s_nop 0
	v_pk_add_f32 v[84:85], v[92:93], v[84:85]
	s_nop 0
	v_pk_add_f32 v[84:85], v[94:95], v[84:85]
	s_nop 0
	v_pk_add_f32 v[102:103], v[100:101], v[84:85]
	v_cvt_pk_bf16_f32 v85, v92, v93
	v_sub_f32_e32 v92, v154, v168
	v_sub_f32_e32 v93, v155, v168
	v_cvt_pk_bf16_f32 v84, v86, v87
	v_cvt_pk_bf16_f32 v87, v100, v101
	v_exp_f32_e32 v92, v92
	v_exp_f32_e32 v93, v93
	v_sub_f32_e32 v100, v158, v168
	v_exp_f32_e32 v104, v100
	v_sub_f32_e32 v100, v159, v168
	v_exp_f32_e32 v105, v100
	v_sub_f32_e32 v100, v160, v168
	v_exp_f32_e32 v106, v100
	v_sub_f32_e32 v100, v161, v168
	v_exp_f32_e32 v107, v100
	v_pk_add_f32 v[100:101], v[92:93], v[102:103]
	v_sub_f32_e32 v102, v134, v168
	v_cvt_pk_bf16_f32 v86, v94, v95
	v_sub_f32_e32 v94, v156, v168
	v_sub_f32_e32 v95, v157, v168
	v_exp_f32_e32 v108, v102
	v_sub_f32_e32 v102, v162, v168
	v_exp_f32_e32 v94, v94
	v_exp_f32_e32 v95, v95
	v_exp_f32_e32 v109, v102
	v_sub_f32_e32 v102, v163, v168
	v_exp_f32_e32 v110, v102
	v_sub_f32_e32 v102, v164, v168
	v_exp_f32_e32 v111, v102
	v_sub_f32_e32 v102, v165, v168
	v_exp_f32_e32 v112, v102
	v_sub_f32_e32 v102, v166, v168
	v_pk_add_f32 v[100:101], v[94:95], v[100:101]
	v_exp_f32_e32 v113, v102
	v_sub_f32_e32 v102, v167, v168
	v_pk_add_f32 v[100:101], v[104:105], v[100:101]
	v_exp_f32_e32 v114, v102
	v_sub_f32_e32 v102, v136, v168
	v_pk_add_f32 v[100:101], v[106:107], v[100:101]
	v_exp_f32_e32 v115, v102
	v_pk_add_f32 v[100:101], v[108:109], v[100:101]
	v_cvt_pk_bf16_f32 v102, v104, v105
	v_pk_add_f32 v[100:101], v[110:111], v[100:101]
	v_cvt_pk_bf16_f32 v103, v106, v107
	v_pk_add_f32 v[100:101], v[112:113], v[100:101]
	v_lshlrev_b32_e32 v106, 1, v133
	v_pk_add_f32 v[100:101], v[114:115], v[100:101]
	v_and_b32_e32 v106, 8, v106
	v_add_f32_e32 v100, v100, v101
	v_add_f32_e32 v116, 0, v100
	ds_bpermute_b32 v117, v180, v116
	v_cvt_pk_bf16_f32 v100, v92, v93
	v_cvt_pk_bf16_f32 v92, v108, v109
	v_cvt_pk_bf16_f32 v93, v110, v111
	v_cvt_pk_bf16_f32 v101, v94, v95
	s_waitcnt lgkmcnt(0)
; #define LAS __attribute__((address_space(3)))
; template <bool SWA, bool FAST>
; __device__ __forceinline__ void att_tile(const AttnP& P, LAS unsigned char* lds, int lane, int tb, int qpos0, int hq, int kloc0, int r, int ct, int kr0, int kc0, const AttQZ& qz, float shift) {
;     ...
;     l += __shfl_xor(l, 16); l += __shfl_xor(l, 32);
;     if (SWA) l += __builtin_amdgcn_exp2f(FAST ? sk - shift : sk - mx);
;     const float rl = 1.0f / l;
;     f32x4 oacc[4];
; #pragma unroll
;     for (int dt = 0; dt < 4; ++dt) oacc[dt] = (f32x4){0.f, 0.f, 0.f, 0.f};
;     constexpr int GV = SWA ? 3 : 2;
;     const int g0l = (SWA ? kloc0 : kc0) + 4 * fq;
;     const LAS unsigned char* vb0 = lds + ATT_VOFF + (g0l >> 3) * 1024 + li * 16 + (g0l & 7) * 2;
; #pragma unroll
;     for (int s0 = 0; s0 < NSEG; s0 += GV) {
;         u32x2 vf[GV][4][2];
; #pragma unroll
;         for (int g = 0; g < GV; ++g) { const int s = s0 + g;
;             const int segv = SWA ? s * 4096 : ((kr0 + s) % 9) * 8192;
; #pragma unroll
;             for (int dt = 0; dt < 4; ++dt) {
;                 vf[g][dt][0] = *(const LAS u32x2*)(vb0 + segv + dt * 256); asm volatile("" ::: "memory");
;                 vf[g][dt][1] = *(const LAS u32x2*)(vb0 + segv + dt * 256 + 2048); asm volatile("" ::: "memory"); } }
;         __builtin_amdgcn_sched_barrier(0);
;         __builtin_amdgcn_s_setprio(1);
; #pragma unroll
;         for (int g = 0; g < GV; ++g)
; #pragma unroll
;             for (int dt = 0; dt < 4; ++dt) {
;                 u32x4 w; w.x = vf[g][dt][0].x; w.y = vf[g][dt][0].y; w.z = vf[g][dt][1].x; w.w = vf[g][dt][1].y;
;                 oacc[dt] = __builtin_amdgcn_mfma_f32_16x16x32_bf16(__builtin_bit_cast(bf16x8, w), pb[s0 + g], oacc[dt], 0, 0, 0); }
;         __builtin_amdgcn_s_setprio(0);
;         __builtin_amdgcn_sched_barrier(0);
;     }
	v_add_f32_e32 v104, v116, v117
	ds_bpermute_b32 v105, v181, v104
	v_cvt_pk_bf16_f32 v94, v112, v113
	v_cvt_pk_bf16_f32 v95, v114, v115
	s_waitcnt lgkmcnt(0)
	v_add_f32_e32 v146, v104, v105
	v_lshlrev_b32_e32 v104, 7, v133
	v_and_b32_e32 v104, 0x3c00, v104
	v_add_u32_e32 v104, s27, v104
	v_lshlrev_b32_e32 v105, 4, v132
	v_add3_u32 v133, v104, v105, v106
	v_add_u32_e32 v118, s43, v133
	ds_read_b64 v[104:105], v118
	ds_read_b64 v[106:107], v118 offset:2048
	ds_read_b64 v[108:109], v118 offset:256
	ds_read_b64 v[110:111], v118 offset:2304
	ds_read_b64 v[112:113], v118 offset:512
	ds_read_b64 v[114:115], v118 offset:2560
	ds_read_b64 v[116:117], v118 offset:768
	ds_read_b64 v[118:119], v118 offset:2816
	v_add_u32_e32 v136, s41, v133
	ds_read_b64 v[120:121], v136
	ds_read_b64 v[122:123], v136 offset:2048
	ds_read_b64 v[124:125], v136 offset:256
	ds_read_b64 v[126:127], v136 offset:2304
	ds_read_b64 v[128:129], v136 offset:512
	ds_read_b64 v[130:131], v136 offset:2560
	ds_read_b64 v[134:135], v136 offset:768
	ds_read_b64 v[136:137], v136 offset:2816
	s_waitcnt lgkmcnt(14)
	v_mfma_f32_16x16x32_bf16 v[104:107], v[104:107], v[80:83], 0
	s_waitcnt lgkmcnt(12)
	v_mfma_f32_16x16x32_bf16 v[108:111], v[108:111], v[80:83], 0
	s_waitcnt lgkmcnt(10)
	v_mfma_f32_16x16x32_bf16 v[112:115], v[112:115], v[80:83], 0
	s_waitcnt lgkmcnt(8)
	v_mfma_f32_16x16x32_bf16 v[80:83], v[116:119], v[80:83], 0
	s_waitcnt lgkmcnt(0)
	v_mfma_f32_16x16x32_bf16 v[80:83], v[134:137], v[96:99], v[80:83]
	v_mfma_f32_16x16x32_bf16 v[104:107], v[120:123], v[96:99], v[104:107]
	v_mfma_f32_16x16x32_bf16 v[108:111], v[124:127], v[96:99], v[108:111]
	v_mfma_f32_16x16x32_bf16 v[112:115], v[128:131], v[96:99], v[112:115]
	v_add_u32_e32 v126, s40, v133
	ds_read_b64 v[96:97], v126
	ds_read_b64 v[98:99], v126 offset:2048
	ds_read_b64 v[116:117], v126 offset:256
	ds_read_b64 v[118:119], v126 offset:2304
	ds_read_b64 v[120:121], v126 offset:512
	ds_read_b64 v[122:123], v126 offset:2560
	ds_read_b64 v[124:125], v126 offset:768
	ds_read_b64 v[126:127], v126 offset:2816
	v_add_u32_e32 v144, s39, v133
	ds_read_b64 v[128:129], v144
	ds_read_b64 v[130:131], v144 offset:2048
	ds_read_b64 v[134:135], v144 offset:256
	ds_read_b64 v[136:137], v144 offset:2304
	ds_read_b64 v[138:139], v144 offset:512
	ds_read_b64 v[140:141], v144 offset:2560
	ds_read_b64 v[142:143], v144 offset:768
	ds_read_b64 v[144:145], v144 offset:2816
	s_waitcnt lgkmcnt(14)
	v_mfma_f32_16x16x32_bf16 v[96:99], v[96:99], v[76:79], v[104:107]
	s_waitcnt lgkmcnt(12)
	v_mfma_f32_16x16x32_bf16 v[104:107], v[116:119], v[76:79], v[108:111]
	s_waitcnt lgkmcnt(10)
	v_mfma_f32_16x16x32_bf16 v[108:111], v[120:123], v[76:79], v[112:115]
	s_waitcnt lgkmcnt(8)
	v_mfma_f32_16x16x32_bf16 v[76:79], v[124:127], v[76:79], v[80:83]
	s_waitcnt lgkmcnt(6)
	v_mfma_f32_16x16x32_bf16 v[80:83], v[128:131], v[88:91], v[96:99]
	s_waitcnt lgkmcnt(0)
	v_mfma_f32_16x16x32_bf16 v[76:79], v[142:145], v[88:91], v[76:79]
	v_mfma_f32_16x16x32_bf16 v[96:99], v[134:137], v[88:91], v[104:107]
	v_mfma_f32_16x16x32_bf16 v[104:107], v[138:141], v[88:91], v[108:111]
	v_add_u32_e32 v118, s38, v133
	ds_read_b64 v[88:89], v118
	ds_read_b64 v[90:91], v118 offset:2048
	ds_read_b64 v[108:109], v118 offset:256
	ds_read_b64 v[110:111], v118 offset:2304
	ds_read_b64 v[112:113], v118 offset:512
	ds_read_b64 v[114:115], v118 offset:2560
	ds_read_b64 v[116:117], v118 offset:768
	ds_read_b64 v[118:119], v118 offset:2816
	v_add_u32_e32 v136, s37, v133
	ds_read_b64 v[120:121], v136
	ds_read_b64 v[122:123], v136 offset:2048
	ds_read_b64 v[124:125], v136 offset:256
	ds_read_b64 v[126:127], v136 offset:2304
	ds_read_b64 v[128:129], v136 offset:512
	ds_read_b64 v[130:131], v136 offset:2560
	ds_read_b64 v[134:135], v136 offset:768
	ds_read_b64 v[136:137], v136 offset:2816
	s_waitcnt lgkmcnt(14)
	v_mfma_f32_16x16x32_bf16 v[80:83], v[88:91], v[72:75], v[80:83]
	s_waitcnt lgkmcnt(12)
	v_mfma_f32_16x16x32_bf16 v[88:91], v[108:111], v[72:75], v[96:99]
	s_waitcnt lgkmcnt(10)
	v_mfma_f32_16x16x32_bf16 v[96:99], v[112:115], v[72:75], v[104:107]
	s_waitcnt lgkmcnt(8)
	v_mfma_f32_16x16x32_bf16 v[72:75], v[116:119], v[72:75], v[76:79]
	s_waitcnt lgkmcnt(6)
	v_mfma_f32_16x16x32_bf16 v[76:79], v[120:123], v[84:87], v[80:83]
	s_waitcnt lgkmcnt(4)
	v_mfma_f32_16x16x32_bf16 v[80:83], v[124:127], v[84:87], v[88:91]
	s_waitcnt lgkmcnt(2)
	v_mfma_f32_16x16x32_bf16 v[88:91], v[128:131], v[84:87], v[96:99]
	s_waitcnt lgkmcnt(0)
	v_mfma_f32_16x16x32_bf16 v[72:75], v[134:137], v[84:87], v[72:75]
	v_add_u32_e32 v110, s36, v133
	ds_read_b64 v[84:85], v110
	ds_read_b64 v[86:87], v110 offset:2048
	ds_read_b64 v[96:97], v110 offset:256
	ds_read_b64 v[98:99], v110 offset:2304
	ds_read_b64 v[104:105], v110 offset:512
	ds_read_b64 v[106:107], v110 offset:2560
	ds_read_b64 v[108:109], v110 offset:768
	ds_read_b64 v[110:111], v110 offset:2816
	v_add_u32_e32 v126, s22, v133
	ds_read_b64 v[112:113], v126
	ds_read_b64 v[114:115], v126 offset:2048
	ds_read_b64 v[116:117], v126 offset:256
	ds_read_b64 v[118:119], v126 offset:2304
	ds_read_b64 v[120:121], v126 offset:512
	ds_read_b64 v[122:123], v126 offset:2560
	ds_read_b64 v[124:125], v126 offset:768
	ds_read_b64 v[126:127], v126 offset:2816
	s_waitcnt lgkmcnt(14)
	v_mfma_f32_16x16x32_bf16 v[76:79], v[84:87], v[100:103], v[76:79]
	s_waitcnt lgkmcnt(12)
	v_mfma_f32_16x16x32_bf16 v[80:83], v[96:99], v[100:103], v[80:83]
	s_waitcnt lgkmcnt(10)
	v_mfma_f32_16x16x32_bf16 v[84:87], v[104:107], v[100:103], v[88:91]
	s_waitcnt lgkmcnt(8)
	v_mfma_f32_16x16x32_bf16 v[72:75], v[108:111], v[100:103], v[72:75]
	s_waitcnt lgkmcnt(6)
	v_mfma_f32_16x16x32_bf16 v[88:91], v[112:115], v[92:95], v[76:79]
	s_waitcnt lgkmcnt(4)
; template <bool SWA, bool FAST>
; __device__ __forceinline__ void att_tile(const AttnP& P, LAS unsigned char* lds, int lane, int tb, int qpos0, int hq, int kloc0, int r, int ct, int kr0, int kc0, const AttQZ& qz, float shift) {
;     ...
;     const int krow0 = (SWA ? kloc0 : kc0) + li, ksw = (krow0 >> 1) & 7;
;     const LAS unsigned char* kb0 = lds + krow0 * 128 + ((fq ^ ksw) << 4);
;     const LAS unsigned char* kb1 = lds + krow0 * 128 + (((fq + 4) ^ ksw) << 4);
; #pragma unroll
;     for (int s0 = 0; s0 < NSEG; s0 += GS) {
;         bf16x8 kf[GS][2][2];
; #pragma unroll
;         for (int g = 0; g < GS; ++g)
; #pragma unroll
;             for (int kt = 0; kt < 2; ++kt) { const int s = s0 + g;
;                 const int segoff = SWA ? (32 * s + 16 * kt) * 128 : (((kr0 + s) % 9) * 64 + 16 * kt) * 128;
;                 kf[g][kt][0] = *(const LAS bf16x8*)(kb0 + segoff); kf[g][kt][1] = *(const LAS bf16x8*)(kb1 + segoff); }
;         __builtin_amdgcn_sched_barrier(0);
;         __builtin_amdgcn_s_setprio(1);
; #pragma unroll
;         for (int g = 0; g < GS; ++g)
; #pragma unroll
;             for (int kt = 0; kt < 2; ++kt) {
;                 f32x4 z = FAST ? (f32x4){-shift, -shift, -shift, -shift} : (f32x4){0.f, 0.f, 0.f, 0.f};
;                 z = __builtin_amdgcn_mfma_f32_16x16x32_bf16(kf[g][kt][0], bq0, z, 0, 0, 0);
;                 z = __builtin_amdgcn_mfma_f32_16x16x32_bf16(kf[g][kt][1], bq1, z, 0, 0, 0);
;                 sc[s0 + g][kt] = z; }
;         __builtin_amdgcn_s_setprio(0);
;         __builtin_amdgcn_sched_barrier(0);
;     }
;     ...
;                 oacc[dt] = __builtin_amdgcn_mfma_f32_16x16x32_bf16(__builtin_bit_cast(bf16x8, w), pb[s0 + g], oacc[dt], 0, 0, 0); }
;         __builtin_amdgcn_s_setprio(0);
;         __builtin_amdgcn_sched_barrier(0);
;     }
;     const size_t tq = (size_t)(tb + qpos0 + li);
; #pragma unroll
;     for (int hh = 0; hh < 2; ++hh) {
;         const u32x4 z = qz.z[hh]; const f32x4 a = oacc[2 * hh], b = oacc[2 * hh + 1];
;         u32x4 o; o.x = cvt_pk_bf16(a[0] * rl * bf_lo(z.x), a[1] * rl * bf_hi(z.x)); o.y = cvt_pk_bf16(a[2] * rl * bf_lo(z.y), a[3] * rl * bf_hi(z.y));
;         o.z = cvt_pk_bf16(b[0] * rl * bf_lo(z.z), b[1] * rl * bf_hi(z.z)); o.w = cvt_pk_bf16(b[2] * rl * bf_lo(z.w), b[3] * rl * bf_hi(z.w));
;         *(u32x4*)(P.Y + tq * 1024 + (SWA ? 512 : 0) + hq * 64 + 32 * hh + 8 * fq) = o;
;     }
	v_mfma_f32_16x16x32_bf16 v[80:83], v[116:119], v[92:95], v[80:83]
	s_waitcnt lgkmcnt(2)
	v_mfma_f32_16x16x32_bf16 v[84:87], v[120:123], v[92:95], v[84:87]
	s_waitcnt lgkmcnt(0)
	v_mfma_f32_16x16x32_bf16 v[92:95], v[124:127], v[92:95], v[72:75]
	s_nop 1
	v_div_scale_f32 v74, s[0:1], v146, v146, 1.0
	v_rcp_f32_e32 v75, v74
	v_or_b32_e32 v72, s29, v132
	v_or_b32_e32 v72, s30, v72
	v_add_u32_e32 v72, s28, v72
	v_fma_f32 v96, -v74, v75, 1.0
	v_fmac_f32_e32 v75, v96, v75
	v_div_scale_f32 v96, vcc, 1.0, v146, 1.0
	v_mul_f32_e32 v97, v96, v75
	v_fma_f32 v98, -v74, v97, v96
	v_fmac_f32_e32 v97, v98, v75
	v_fma_f32 v74, -v74, v97, v96
	v_div_fmas_f32 v74, v74, v75, v97
	v_div_fixup_f32 v96, v74, v146, 1.0
	s_waitcnt vmcnt(2)
	v_lshlrev_b32_e32 v74, 16, v60
	v_and_b32_e32 v75, 0xffff0000, v60
	v_pk_mul_f32 v[88:89], v[96:97], v[88:89] op_sel_hi:[0,1]
	v_pk_mul_f32 v[74:75], v[88:89], v[74:75]
	v_pk_mul_f32 v[88:89], v[96:97], v[90:91] op_sel_hi:[0,1]
	v_cvt_pk_bf16_f32 v60, v74, v75
	v_lshlrev_b32_e32 v74, 16, v61
	v_and_b32_e32 v75, 0xffff0000, v61
	v_pk_mul_f32 v[74:75], v[88:89], v[74:75]
	v_ashrrev_i32_e32 v73, 31, v72
	v_cvt_pk_bf16_f32 v61, v74, v75
	v_lshlrev_b32_e32 v74, 16, v62
	v_and_b32_e32 v75, 0xffff0000, v62
	v_pk_mul_f32 v[80:81], v[96:97], v[80:81] op_sel_hi:[0,1]
	v_lshlrev_b64 v[72:73], 11, v[72:73]
	v_pk_mul_f32 v[74:75], v[80:81], v[74:75]
	v_mov_b32_e32 v77, 0
	v_lshl_add_u64 v[72:73], s[24:25], 0, v[72:73]
	s_lshl_b32 s22, s26, 7
	v_cvt_pk_bf16_f32 v62, v74, v75
	v_lshlrev_b32_e32 v74, 16, v63
	v_and_b32_e32 v75, 0xffff0000, v63
	v_pk_mul_f32 v[80:81], v[96:97], v[82:83] op_sel_hi:[0,1]
	v_lshl_add_u64 v[78:79], v[72:73], 0, s[22:23]
	v_lshlrev_b32_e32 v72, 4, v183
	v_mov_b32_e32 v73, v77
	v_pk_mul_f32 v[74:75], v[80:81], v[74:75]
	v_lshl_add_u64 v[72:73], v[78:79], 0, v[72:73]
	v_cvt_pk_bf16_f32 v63, v74, v75
	global_store_dwordx4 v[72:73], v[60:63], off
	v_lshlrev_b32_e32 v76, 3, v183
	s_waitcnt vmcnt(2)
	v_lshlrev_b32_e32 v60, 16, v56
	v_and_b32_e32 v61, 0xffff0000, v56
	v_pk_mul_f32 v[62:63], v[96:97], v[84:85] op_sel_hi:[0,1]
	v_pk_mul_f32 v[60:61], v[62:63], v[60:61]
	v_lshlrev_b32_e32 v56, 16, v57
	v_cvt_pk_bf16_f32 v72, v60, v61
	v_and_b32_e32 v57, 0xffff0000, v57
	v_pk_mul_f32 v[60:61], v[96:97], v[86:87] op_sel_hi:[0,1]
	v_pk_mul_f32 v[56:57], v[60:61], v[56:57]
	v_pk_mul_f32 v[60:61], v[96:97], v[92:93] op_sel_hi:[0,1]
	v_cvt_pk_bf16_f32 v73, v56, v57
	v_lshlrev_b32_e32 v56, 16, v58
	v_and_b32_e32 v57, 0xffff0000, v58
	v_pk_mul_f32 v[56:57], v[60:61], v[56:57]
	s_nop 0
	v_cvt_pk_bf16_f32 v74, v56, v57
	v_mul_f32_e32 v56, v96, v94
	v_lshlrev_b32_e32 v94, 16, v59
	v_mov_b32_e32 v57, v96
	v_pk_mul_f32 v[88:89], v[56:57], v[94:95]
.LBB0_361:
	s_andn2_saveexec_b64 s[8:9], s[20:21]
	s_cbranch_execz .LBB0_363
	s_lshr_b32 s0, s35, 9
	s_mul_i32 s0, s0, 9
	s_sub_i32 s0, s34, s0
	s_and_b32 s0, s0, 0xff
	s_lshl_b32 s20, s0, 13
	s_add_i32 s0, s35, 57
	s_lshr_b32 s0, s0, 9
	s_mul_i32 s0, s0, 9
	s_sub_i32 s0, s34, s0
	s_add_i32 s0, s0, 1
	s_and_b32 s0, s0, 0xff
	v_add_u32_e32 v76, s20, v90
	v_add_u32_e32 v88, s20, v91
	s_lshl_b32 s17, s0, 13
	ds_read_b128 v[72:75], v76
	ds_read_b128 v[76:79], v76 offset:2048
	ds_read_b128 v[92:95], v88
	ds_read_b128 v[96:99], v88 offset:2048
	v_add_u32_e32 v88, s17, v90
	v_add_u32_e32 v89, s17, v91
	ds_read_b128 v[100:103], v88
	ds_read_b128 v[104:107], v88 offset:2048
	ds_read_b128 v[108:111], v89
	ds_read_b128 v[112:115], v89 offset:2048
	v_xor_b32_e32 v116, 0x80000000, v155
	v_mov_b32_e32 v117, v116
	v_mov_b32_e32 v118, v116
	v_mov_b32_e32 v119, v116
	s_waitcnt vmcnt(4) lgkmcnt(7)
	v_mfma_f32_16x16x32_bf16 v[72:75], v[72:75], v[84:87], v[116:119]
	s_waitcnt lgkmcnt(6)
	v_mfma_f32_16x16x32_bf16 v[76:79], v[76:79], v[84:87], v[116:119]
	s_waitcnt vmcnt(3) lgkmcnt(5)
	v_mfma_f32_16x16x32_bf16 v[72:75], v[92:95], v[80:83], v[72:75]
	s_waitcnt lgkmcnt(4)
	v_mfma_f32_16x16x32_bf16 v[76:79], v[96:99], v[80:83], v[76:79]
	s_waitcnt lgkmcnt(3)
	v_mfma_f32_16x16x32_bf16 v[92:95], v[100:103], v[84:87], v[116:119]
	s_waitcnt lgkmcnt(2)
	v_mfma_f32_16x16x32_bf16 v[96:99], v[104:107], v[84:87], v[116:119]
	s_waitcnt lgkmcnt(1)
	v_mfma_f32_16x16x32_bf16 v[92:95], v[108:111], v[80:83], v[92:95]
	s_waitcnt lgkmcnt(0)
	v_mfma_f32_16x16x32_bf16 v[96:99], v[112:115], v[80:83], v[96:99]
	s_add_i32 s0, s35, 0x72
	s_lshr_b32 s0, s0, 9
	s_mul_i32 s0, s0, 9
	s_sub_i32 s0, s34, s0
	s_add_i32 s0, s0, 2
	s_and_b32 s0, s0, 0xff
	s_lshl_b32 s16, s0, 13
	s_add_i32 s0, s35, 0xab
	s_lshr_b32 s0, s0, 9
	s_mul_i32 s0, s0, 9
	s_sub_i32 s0, s34, s0
	s_add_i32 s0, s0, 3
	s_and_b32 s0, s0, 0xff
	v_add_u32_e32 v88, s16, v90
	s_lshl_b32 s15, s0, 13
	v_add_u32_e32 v89, s16, v91
	ds_read_b128 v[100:103], v88
	ds_read_b128 v[104:107], v88 offset:2048
	ds_read_b128 v[108:111], v89
	ds_read_b128 v[112:115], v89 offset:2048
	v_add_u32_e32 v88, s15, v90
	v_add_u32_e32 v89, s15, v91
	ds_read_b128 v[120:123], v88
	ds_read_b128 v[124:127], v88 offset:2048
	ds_read_b128 v[128:131], v89
	ds_read_b128 v[136:139], v89 offset:2048
	s_waitcnt lgkmcnt(7)
	v_mfma_f32_16x16x32_bf16 v[100:103], v[100:103], v[84:87], v[116:119]
	s_waitcnt lgkmcnt(6)
	v_mfma_f32_16x16x32_bf16 v[104:107], v[104:107], v[84:87], v[116:119]
	s_waitcnt lgkmcnt(5)
	v_mfma_f32_16x16x32_bf16 v[100:103], v[108:111], v[80:83], v[100:103]
	s_waitcnt lgkmcnt(4)
	v_mfma_f32_16x16x32_bf16 v[104:107], v[112:115], v[80:83], v[104:107]
	s_waitcnt lgkmcnt(3)
	v_mfma_f32_16x16x32_bf16 v[108:111], v[120:123], v[84:87], v[116:119]
	s_waitcnt lgkmcnt(2)
	v_mfma_f32_16x16x32_bf16 v[112:115], v[124:127], v[84:87], v[116:119]
	s_waitcnt lgkmcnt(1)
; template <bool SWA, bool FAST>
; __device__ __forceinline__ void att_tile(const AttnP& P, LAS unsigned char* lds, int lane, int tb, int qpos0, int hq, int kloc0, int r, int ct, int kr0, int kc0, const AttQZ& qz, float shift) {
;     ...
;     const int krow0 = (SWA ? kloc0 : kc0) + li, ksw = (krow0 >> 1) & 7;
;     const LAS unsigned char* kb0 = lds + krow0 * 128 + ((fq ^ ksw) << 4);
;     const LAS unsigned char* kb1 = lds + krow0 * 128 + (((fq + 4) ^ ksw) << 4);
; #pragma unroll
;     for (int s0 = 0; s0 < NSEG; s0 += GS) {
;         bf16x8 kf[GS][2][2];
; #pragma unroll
;         for (int g = 0; g < GS; ++g)
; #pragma unroll
;             for (int kt = 0; kt < 2; ++kt) { const int s = s0 + g;
;                 const int segoff = SWA ? (32 * s + 16 * kt) * 128 : (((kr0 + s) % 9) * 64 + 16 * kt) * 128;
;                 kf[g][kt][0] = *(const LAS bf16x8*)(kb0 + segoff); kf[g][kt][1] = *(const LAS bf16x8*)(kb1 + segoff); }
;         __builtin_amdgcn_sched_barrier(0);
;         __builtin_amdgcn_s_setprio(1);
; #pragma unroll
;         for (int g = 0; g < GS; ++g)
; #pragma unroll
;             for (int kt = 0; kt < 2; ++kt) {
;                 f32x4 z = FAST ? (f32x4){-shift, -shift, -shift, -shift} : (f32x4){0.f, 0.f, 0.f, 0.f};
;                 z = __builtin_amdgcn_mfma_f32_16x16x32_bf16(kf[g][kt][0], bq0, z, 0, 0, 0);
;                 z = __builtin_amdgcn_mfma_f32_16x16x32_bf16(kf[g][kt][1], bq1, z, 0, 0, 0);
;                 sc[s0 + g][kt] = z; }
;         __builtin_amdgcn_s_setprio(0);
;         __builtin_amdgcn_sched_barrier(0);
;     }
;     ...
;     if constexpr (!SWA && FAST) {
;         const int c = 16 * ct + li, cs = min(max(c - 8, 0), 48), w = cs - kc0;
;         const LAS float* rp = (const LAS float*)(lds + ATT_RPB) + (kr0 - r + 7) * 64 + (kc0 + 4 * fq - c + 31);
;         bool hi[4]; const LAS float* rpj[4];
; #pragma unroll
;         for (int j = 0; j < 4; ++j) { hi[j] = (4 * fq + j) < w; rpj[j] = rp + (hi[j] ? 16 : 0) + j; }
;         const unsigned m01 = (hi[0] ? 0u : 0xffffu) | (hi[1] ? 0u : 0xffff0000u), m23 = (hi[2] ? 0u : 0xffffu) | (hi[3] ? 0u : 0xffff0000u);
; #pragma unroll
;         for (int s = 0; s < NSEG; ++s) {
;             float p[4];
; #pragma unroll
;             for (int j = 0; j < 4; ++j) { const float v = hi[j] ? sc[s][1][j] : sc[s][0][j]; p[j] = __builtin_amdgcn_exp2f(v + rpj[j][s * 64]); }
	v_mfma_f32_16x16x32_bf16 v[108:111], v[128:131], v[80:83], v[108:111]
	s_waitcnt lgkmcnt(0)
	v_mfma_f32_16x16x32_bf16 v[112:115], v[136:139], v[80:83], v[112:115]
	s_add_i32 s0, s35, 0xe4
	s_lshr_b32 s0, s0, 9
	s_mul_i32 s0, s0, 9
	s_sub_i32 s0, s34, s0
	s_add_i32 s0, s0, 4
	s_and_b32 s0, s0, 0xff
	s_lshl_b32 s14, s0, 13
	s_add_i32 s0, s35, 0x11d
	s_lshr_b32 s0, s0, 9
	s_mul_i32 s0, s0, 9
	s_sub_i32 s0, s34, s0
	s_add_i32 s0, s0, 5
	s_and_b32 s0, s0, 0xff
	v_add_u32_e32 v88, s14, v90
	s_lshl_b32 s13, s0, 13
	v_add_u32_e32 v89, s14, v91
	ds_read_b128 v[120:123], v88
	ds_read_b128 v[124:127], v88 offset:2048
	ds_read_b128 v[128:131], v89
	ds_read_b128 v[136:139], v89 offset:2048
	v_add_u32_e32 v88, s13, v90
	v_add_u32_e32 v89, s13, v91
	ds_read_b128 v[140:143], v88
	ds_read_b128 v[144:147], v88 offset:2048
	ds_read_b128 v[148:151], v89
	ds_read_b128 v[154:157], v89 offset:2048
	s_waitcnt lgkmcnt(7)
	v_mfma_f32_16x16x32_bf16 v[120:123], v[120:123], v[84:87], v[116:119]
	s_waitcnt lgkmcnt(6)
	v_mfma_f32_16x16x32_bf16 v[124:127], v[124:127], v[84:87], v[116:119]
	s_waitcnt lgkmcnt(5)
	v_mfma_f32_16x16x32_bf16 v[120:123], v[128:131], v[80:83], v[120:123]
	s_waitcnt lgkmcnt(4)
	v_mfma_f32_16x16x32_bf16 v[124:127], v[136:139], v[80:83], v[124:127]
	s_waitcnt lgkmcnt(3)
	v_mfma_f32_16x16x32_bf16 v[128:131], v[140:143], v[84:87], v[116:119]
	s_waitcnt lgkmcnt(2)
	v_mfma_f32_16x16x32_bf16 v[136:139], v[144:147], v[84:87], v[116:119]
	s_waitcnt lgkmcnt(1)
	v_mfma_f32_16x16x32_bf16 v[128:131], v[148:151], v[80:83], v[128:131]
	s_waitcnt lgkmcnt(0)
	v_mfma_f32_16x16x32_bf16 v[136:139], v[154:157], v[80:83], v[136:139]
	s_add_i32 s0, s35, 0x156
	s_lshr_b32 s0, s0, 9
	s_mul_i32 s0, s0, 9
	s_sub_i32 s0, s34, s0
	s_add_i32 s0, s0, 6
	s_and_b32 s0, s0, 0xff
	s_addk_i32 s35, 0x18f
	s_lshl_b32 s12, s0, 13
	s_lshr_b32 s0, s35, 9
	s_mul_i32 s0, s0, 9
	s_sub_i32 s0, s34, s0
	s_add_i32 s0, s0, 7
	s_and_b32 s0, s0, 0xff
	s_lshl_b32 s10, s0, 13
	v_add_u32_e32 v88, s12, v90
	v_add_u32_e32 v89, s12, v91
	v_add_u32_e32 v135, s10, v90
	v_add_u32_e32 v166, s10, v91
	ds_read_b128 v[140:143], v88
	ds_read_b128 v[144:147], v88 offset:2048
	ds_read_b128 v[148:151], v89
	ds_read_b128 v[154:157], v89 offset:2048
	ds_read_b128 v[88:91], v135
	ds_read_b128 v[158:161], v135 offset:2048
	ds_read_b128 v[162:165], v166
	ds_read_b128 v[166:169], v166 offset:2048
	s_waitcnt lgkmcnt(3)
	v_mfma_f32_16x16x32_bf16 v[88:91], v[88:91], v[84:87], v[116:119]
	v_mfma_f32_16x16x32_bf16 v[140:143], v[140:143], v[84:87], v[116:119]
	v_mfma_f32_16x16x32_bf16 v[144:147], v[144:147], v[84:87], v[116:119]
	s_waitcnt lgkmcnt(1)
	v_mfma_f32_16x16x32_bf16 v[88:91], v[162:165], v[80:83], v[88:91]
	v_mfma_f32_16x16x32_bf16 v[84:87], v[158:161], v[84:87], v[116:119]
	v_mfma_f32_16x16x32_bf16 v[140:143], v[148:151], v[80:83], v[140:143]
	v_mfma_f32_16x16x32_bf16 v[144:147], v[154:157], v[80:83], v[144:147]
	s_waitcnt lgkmcnt(0)
	v_mfma_f32_16x16x32_bf16 v[80:83], v[166:169], v[80:83], v[84:87]
	s_sub_i32 s0, s34, s33
	s_nop 1
	v_min_u32_e32 v84, 48, v133
	s_lshl_b32 s0, s0, 8
	v_lshlrev_b32_e32 v85, 2, v183
	v_subrev_u32_e32 v84, s31, v84
	s_add_i32 s0, s0, 0
	v_add_u32_e32 v116, s31, v85
	s_add_i32 s0, s0, 0x24000
	v_sub_u32_e32 v86, v116, v134
	v_cmp_lt_i32_e32 vcc, v85, v84
	v_or_b32_e32 v117, 1, v85
	v_or_b32_e32 v118, 2, v85
	v_or_b32_e32 v85, 3, v85
	v_lshl_add_u32 v86, v86, 2, s0
	v_cndmask_b32_e64 v87, 0, 64, vcc
	v_cmp_lt_i32_e64 s[0:1], v117, v84
	v_cmp_lt_i32_e64 s[6:7], v85, v84
	v_add_u32_e32 v87, v86, v87
	v_cndmask_b32_e64 v117, 0, 64, s[0:1]
	v_cmp_lt_i32_e64 s[4:5], v118, v84
	v_cndmask_b32_e64 v84, 0, 64, s[6:7]
	v_add_u32_e32 v117, v86, v117
	v_cndmask_b32_e64 v118, 0, 64, s[4:5]
	v_add_u32_e32 v84, v86, v84
	v_cndmask_b32_e32 v119, v72, v76, vcc
	v_add_u32_e32 v72, 0x7c, v87
	v_add_u32_e32 v118, v86, v118
	v_cndmask_b32_e64 v133, v73, v77, s[0:1]
	v_add_u32_e32 v117, 0x80, v117
	v_cndmask_b32_e64 v134, v74, v78, s[4:5]
	v_cndmask_b32_e64 v135, v75, v79, s[6:7]
	v_add_u32_e32 v148, 0x88, v84
	ds_read2st64_b32 v[76:77], v72 offset0:7 offset1:8
	ds_read2st64_b32 v[78:79], v72 offset0:9 offset1:10
	ds_read2st64_b32 v[84:85], v72 offset0:11 offset1:12
	ds_read2st64_b32 v[72:73], v72 offset0:13 offset1:14
	v_add_u32_e32 v118, 0x84, v118
	v_cndmask_b32_e32 v149, v92, v96, vcc
	v_cndmask_b32_e64 v150, v93, v97, s[0:1]
	v_cndmask_b32_e64 v151, v94, v98, s[4:5]
	v_cndmask_b32_e64 v154, v95, v99, s[6:7]
	ds_read2st64_b32 v[86:87], v117 offset0:7 offset1:8
	ds_read2st64_b32 v[92:93], v117 offset0:9 offset1:10
	ds_read2st64_b32 v[94:95], v117 offset0:11 offset1:12
	ds_read2st64_b32 v[74:75], v117 offset0:13 offset1:14
	v_cndmask_b32_e32 v155, v100, v104, vcc
	v_cndmask_b32_e64 v156, v101, v105, s[0:1]
	v_cndmask_b32_e64 v157, v102, v106, s[4:5]
	v_cndmask_b32_e64 v158, v103, v107, s[6:7]
	ds_read2st64_b32 v[96:97], v118 offset0:7 offset1:8
	ds_read2st64_b32 v[98:99], v118 offset0:9 offset1:10
	ds_read2st64_b32 v[100:101], v118 offset0:11 offset1:12
	ds_read2st64_b32 v[102:103], v118 offset0:13 offset1:14
	v_cndmask_b32_e32 v159, v108, v112, vcc
	v_cndmask_b32_e64 v160, v109, v113, s[0:1]
	v_cndmask_b32_e64 v114, v110, v114, s[4:5]
	v_cndmask_b32_e64 v115, v111, v115, s[6:7]
	ds_read2st64_b32 v[104:105], v148 offset0:7 offset1:8
	ds_read2st64_b32 v[106:107], v148 offset0:9 offset1:10
	ds_read2st64_b32 v[108:109], v148 offset0:11 offset1:12
	ds_read2st64_b32 v[110:111], v148 offset0:13 offset1:14
	v_cndmask_b32_e32 v112, v140, v144, vcc
	v_cndmask_b32_e64 v113, v141, v145, s[0:1]
	s_waitcnt lgkmcnt(12)
	v_add_f32_e32 v72, v112, v72
	v_cndmask_b32_e64 v117, v142, v146, s[4:5]
	v_cndmask_b32_e32 v88, v88, v80, vcc
	v_exp_f32_e32 v80, v72
	s_waitcnt lgkmcnt(8)
; #define LAS __attribute__((address_space(3)))
; __device__ __forceinline__ unsigned cvt_pk_bf16(float lo, float hi) { const f32x2_t v = {lo, hi}; const bf16x2_t r = __builtin_convertvector(v, bf16x2_t); return __builtin_bit_cast(unsigned, r); }
; template <bool SWA, bool FAST>
; __device__ __forceinline__ void att_tile(const AttnP& P, LAS unsigned char* lds, int lane, int tb, int qpos0, int hq, int kloc0, int r, int ct, int kr0, int kc0, const AttQZ& qz, float shift) {
;     ...
;     if constexpr (!SWA && FAST) {
;         const int c = 16 * ct + li, cs = min(max(c - 8, 0), 48), w = cs - kc0;
;         const LAS float* rp = (const LAS float*)(lds + ATT_RPB) + (kr0 - r + 7) * 64 + (kc0 + 4 * fq - c + 31);
;         bool hi[4]; const LAS float* rpj[4];
; #pragma unroll
;         for (int j = 0; j < 4; ++j) { hi[j] = (4 * fq + j) < w; rpj[j] = rp + (hi[j] ? 16 : 0) + j; }
;         const unsigned m01 = (hi[0] ? 0u : 0xffffu) | (hi[1] ? 0u : 0xffff0000u), m23 = (hi[2] ? 0u : 0xffffu) | (hi[3] ? 0u : 0xffff0000u);
; #pragma unroll
;         for (int s = 0; s < NSEG; ++s) {
;             float p[4];
; #pragma unroll
;             for (int j = 0; j < 4; ++j) { const float v = hi[j] ? sc[s][1][j] : sc[s][0][j]; p[j] = __builtin_amdgcn_exp2f(v + rpj[j][s * 64]); }
;             l2 += (f32x2_t){p[0], p[1]}; l2 += (f32x2_t){p[2], p[3]};
;             const unsigned pk01 = cvt_pk_bf16(p[0], p[1]), pk23 = cvt_pk_bf16(p[2], p[3]);
;             u32x4 wv; wv.x = pk01 & m01; wv.y = pk23 & m23; wv.z = pk01 & ~m01; wv.w = pk23 & ~m23;
;             pb[s] = __builtin_bit_cast(bf16x8, wv);
;         }
;     } else
; #pragma unroll
;     for (int s = 0; s < NSEG; ++s) {
;         float p[8];
; #pragma unroll
;         for (int kt = 0; kt < 2; ++kt)
; #pragma unroll
;             for (int j = 0; j < 4; ++j) p[4 * kt + j] = __builtin_amdgcn_exp2f(FAST ? sc[s][kt][j] : sc[s][kt][j] - mx);
; #pragma unroll
;         for (int e = 0; e < 8; e += 2) l2 += (f32x2_t){p[e], p[e + 1]};
;         u32x4 w; w.x = cvt_pk_bf16(p[0], p[1]); w.y = cvt_pk_bf16(p[2], p[3]); w.z = cvt_pk_bf16(p[4], p[5]); w.w = cvt_pk_bf16(p[6], p[7]);
;         pb[s] = __builtin_bit_cast(bf16x8, w);
;     }
;     l += l2[0] + l2[1];
;     l += __shfl_xor(l, 16); l += __shfl_xor(l, 32);
	v_add_f32_e32 v72, v113, v74
	v_cndmask_b32_e64 v118, v143, v147, s[6:7]
	v_cndmask_b32_e64 v89, v89, v81, s[0:1]
	v_exp_f32_e32 v81, v72
	s_waitcnt lgkmcnt(4)
	v_add_f32_e32 v72, v117, v102
	v_cndmask_b32_e64 v90, v90, v82, s[4:5]
	v_exp_f32_e32 v82, v72
	s_waitcnt lgkmcnt(0)
	v_add_f32_e32 v72, v118, v110
	v_cndmask_b32_e32 v120, v120, v124, vcc
	v_cndmask_b32_e32 v124, v128, v136, vcc
	v_cndmask_b32_e64 v128, v91, v83, s[6:7]
	v_exp_f32_e32 v83, v72
	v_add_f32_e32 v72, v88, v73
	v_cndmask_b32_e64 v122, v122, v126, s[4:5]
	v_exp_f32_e32 v112, v72
	v_add_f32_e32 v72, v89, v75
	v_add_f32_e32 v99, v114, v99
	v_cndmask_b32_e64 v126, v130, v138, s[4:5]
	v_exp_f32_e32 v113, v72
	v_add_f32_e32 v72, v90, v103
	v_add_f32_e32 v90, v122, v100
	v_exp_f32_e32 v100, v99
	v_add_f32_e32 v99, v115, v107
	v_add_f32_e32 v96, v134, v96
	v_add_f32_e32 v76, v119, v76
	v_add_f32_e32 v88, v126, v101
	v_exp_f32_e32 v101, v99
	v_add_f32_e32 v99, v158, v106
	v_exp_f32_e32 v106, v96
	v_add_f32_e32 v96, v135, v104
	v_exp_f32_e32 v104, v76
	v_add_f32_e32 v76, v133, v86
	v_add_f32_e32 v103, v154, v105
	v_exp_f32_e32 v105, v76
	v_add_f32_e32 v76, v149, v77
	v_add_f32_e32 v97, v151, v97
	v_exp_f32_e32 v107, v96
	v_exp_f32_e32 v96, v76
	v_add_f32_e32 v76, v150, v87
	v_cndmask_b32_e64 v123, v123, v127, s[6:7]
	v_mov_b32_e32 v91, 0xffff0000
	v_exp_f32_e32 v102, v97
	v_exp_f32_e32 v97, v76
	v_add_f32_e32 v78, v155, v78
	v_cndmask_b32_e64 v121, v121, v125, s[0:1]
	v_cndmask_b32_e64 v125, v129, v137, s[0:1]
	v_cndmask_b32_e64 v127, v131, v139, s[6:7]
	v_cndmask_b32_e64 v129, v91, 0, s[6:7]
	v_cndmask_b32_e64 v117, v91, 0, s[0:1]
	v_add_f32_e32 v91, v123, v108
	v_exp_f32_e32 v103, v103
	v_exp_f32_e32 v108, v78
	v_add_f32_e32 v78, v156, v92
	v_add_f32_e32 v89, v127, v109
	v_add_f32_e32 v98, v157, v98
	v_pk_add_f32 v[76:77], v[104:105], 0 op_sel_hi:[1,0]
	v_exp_f32_e32 v109, v78
	v_add_f32_e32 v78, v159, v79
	v_exp_f32_e32 v98, v98
	v_exp_f32_e32 v99, v99
	v_pk_add_f32 v[76:77], v[76:77], v[106:107]
	v_exp_f32_e32 v92, v78
	v_add_f32_e32 v78, v160, v93
	v_pk_add_f32 v[76:77], v[76:77], v[96:97]
	v_exp_f32_e32 v93, v78
	v_add_f32_e32 v78, v120, v84
	v_pk_add_f32 v[76:77], v[76:77], v[102:103]
	v_exp_f32_e32 v86, v78
	v_add_f32_e32 v78, v121, v94
	v_pk_add_f32 v[76:77], v[76:77], v[108:109]
	v_exp_f32_e32 v87, v78
	v_exp_f32_e32 v90, v90
	v_exp_f32_e32 v91, v91
	v_pk_add_f32 v[76:77], v[76:77], v[98:99]
	v_add_f32_e32 v78, v124, v85
	v_add_f32_e32 v79, v125, v95
	v_pk_add_f32 v[76:77], v[76:77], v[92:93]
	v_exp_f32_e32 v78, v78
	v_exp_f32_e32 v79, v79
	v_exp_f32_e32 v88, v88
	v_exp_f32_e32 v89, v89
	v_pk_add_f32 v[76:77], v[76:77], v[100:101]
	v_mov_b32_e32 v73, 0xffff
	v_pk_add_f32 v[76:77], v[76:77], v[86:87]
	v_cvt_pk_bf16_f32 v74, v80, v81
	v_pk_add_f32 v[76:77], v[76:77], v[90:91]
	v_cndmask_b32_e64 v130, v73, 0, s[4:5]
	v_pk_add_f32 v[76:77], v[76:77], v[78:79]
	v_cvt_pk_bf16_f32 v75, v82, v83
	v_pk_add_f32 v[76:77], v[76:77], v[88:89]
	v_cndmask_b32_e64 v118, v73, 0, vcc
	v_pk_add_f32 v[76:77], v[76:77], v[80:81]
	v_cvt_pk_bf16_f32 v78, v78, v79
	v_pk_add_f32 v[80:81], v[76:77], v[82:83]
	v_cvt_pk_bf16_f32 v83, v90, v91
	v_cvt_pk_bf16_f32 v82, v86, v87
	v_bitop3_b32 v85, v129, v83, v130 bitop3:0xc8
	v_bitop3_b32 v87, v83, v129, v130 bitop3:0x10
	v_cvt_pk_bf16_f32 v83, v100, v101
	v_cvt_pk_bf16_f32 v79, v88, v89
	v_bitop3_b32 v84, v117, v82, v118 bitop3:0xc8
	v_bitop3_b32 v86, v82, v117, v118 bitop3:0x10
	v_cvt_pk_bf16_f32 v82, v92, v93
	v_bitop3_b32 v89, v129, v83, v130 bitop3:0xc8
	v_bitop3_b32 v91, v83, v129, v130 bitop3:0x10
	v_cvt_pk_bf16_f32 v83, v98, v99
	v_bitop3_b32 v88, v117, v82, v118 bitop3:0xc8
	v_bitop3_b32 v90, v82, v117, v118 bitop3:0x10
	v_cvt_pk_bf16_f32 v82, v108, v109
	v_bitop3_b32 v93, v129, v83, v130 bitop3:0xc8
	v_bitop3_b32 v95, v83, v129, v130 bitop3:0x10
	v_cvt_pk_bf16_f32 v83, v102, v103
	v_bitop3_b32 v92, v117, v82, v118 bitop3:0xc8
	v_bitop3_b32 v94, v82, v117, v118 bitop3:0x10
	v_cvt_pk_bf16_f32 v82, v96, v97
	v_bitop3_b32 v97, v129, v83, v130 bitop3:0xc8
	v_bitop3_b32 v99, v83, v129, v130 bitop3:0x10
	v_add_f32_e32 v83, v128, v111
	v_exp_f32_e32 v110, v72
	v_exp_f32_e32 v111, v83
	v_pk_add_f32 v[80:81], v[80:81], v[112:113]
	v_bitop3_b32 v96, v117, v82, v118 bitop3:0xc8
	v_bitop3_b32 v98, v82, v117, v118 bitop3:0x10
	v_pk_add_f32 v[80:81], v[80:81], v[110:111]
	v_cvt_pk_bf16_f32 v82, v104, v105
	v_add_f32_e32 v80, v80, v81
	v_add_f32_e32 v80, 0, v80
	ds_bpermute_b32 v81, v180, v80
	v_cvt_pk_bf16_f32 v83, v106, v107
	v_lshlrev_b32_e32 v106, 1, v116
	v_and_b32_e32 v106, 8, v106
	v_bitop3_b32 v100, v117, v82, v118 bitop3:0xc8
	s_waitcnt lgkmcnt(0)
	v_add_f32_e32 v104, v80, v81
	ds_bpermute_b32 v105, v181, v104
	v_bitop3_b32 v102, v82, v117, v118 bitop3:0x10
	v_cvt_pk_bf16_f32 v82, v112, v113
	v_bitop3_b32 v72, v117, v74, v118 bitop3:0xc8
	v_bitop3_b32 v74, v74, v117, v118 bitop3:0x10
	s_waitcnt lgkmcnt(0)
; #define LAS __attribute__((address_space(3)))
; template <bool SWA, bool FAST>
; __device__ __forceinline__ void att_tile(const AttnP& P, LAS unsigned char* lds, int lane, int tb, int qpos0, int hq, int kloc0, int r, int ct, int kr0, int kc0, const AttQZ& qz, float shift) {
;     ...
;     l += __shfl_xor(l, 16); l += __shfl_xor(l, 32);
;     if (SWA) l += __builtin_amdgcn_exp2f(FAST ? sk - shift : sk - mx);
;     const float rl = 1.0f / l;
;     f32x4 oacc[4];
; #pragma unroll
;     for (int dt = 0; dt < 4; ++dt) oacc[dt] = (f32x4){0.f, 0.f, 0.f, 0.f};
;     constexpr int GV = SWA ? 3 : 2;
;     const int g0l = (SWA ? kloc0 : kc0) + 4 * fq;
;     const LAS unsigned char* vb0 = lds + ATT_VOFF + (g0l >> 3) * 1024 + li * 16 + (g0l & 7) * 2;
; #pragma unroll
;     for (int s0 = 0; s0 < NSEG; s0 += GV) {
;         u32x2 vf[GV][4][2];
; #pragma unroll
;         for (int g = 0; g < GV; ++g) { const int s = s0 + g;
;             const int segv = SWA ? s * 4096 : ((kr0 + s) % 9) * 8192;
; #pragma unroll
;             for (int dt = 0; dt < 4; ++dt) {
;                 vf[g][dt][0] = *(const LAS u32x2*)(vb0 + segv + dt * 256); asm volatile("" ::: "memory");
;                 vf[g][dt][1] = *(const LAS u32x2*)(vb0 + segv + dt * 256 + 2048); asm volatile("" ::: "memory"); } }
;         __builtin_amdgcn_sched_barrier(0);
;         __builtin_amdgcn_s_setprio(1);
; #pragma unroll
;         for (int g = 0; g < GV; ++g)
; #pragma unroll
;             for (int dt = 0; dt < 4; ++dt) {
;                 u32x4 w; w.x = vf[g][dt][0].x; w.y = vf[g][dt][0].y; w.z = vf[g][dt][1].x; w.w = vf[g][dt][1].y;
;                 oacc[dt] = __builtin_amdgcn_mfma_f32_16x16x32_bf16(__builtin_bit_cast(bf16x8, w), pb[s0 + g], oacc[dt], 0, 0, 0); }
;         __builtin_amdgcn_s_setprio(0);
;         __builtin_amdgcn_sched_barrier(0);
;     }
	v_add_f32_e32 v133, v104, v105
	v_lshlrev_b32_e32 v104, 7, v116
	v_and_b32_e32 v104, 0x3c00, v104
	v_add_u32_e32 v104, s27, v104
	v_lshlrev_b32_e32 v105, 4, v132
	v_add3_u32 v146, v104, v105, v106
	v_bitop3_b32 v76, v117, v78, v118 bitop3:0xc8
	v_bitop3_b32 v78, v78, v117, v118 bitop3:0x10
	v_bitop3_b32 v80, v117, v82, v118 bitop3:0xc8
	v_bitop3_b32 v82, v82, v117, v118 bitop3:0x10
	v_add_u32_e32 v118, s20, v146
	ds_read_b64 v[104:105], v118
	ds_read_b64 v[106:107], v118 offset:2048
	ds_read_b64 v[108:109], v118 offset:256
	v_bitop3_b32 v101, v129, v83, v130 bitop3:0xc8
	v_bitop3_b32 v103, v83, v129, v130 bitop3:0x10
	v_cvt_pk_bf16_f32 v83, v110, v111
	ds_read_b64 v[110:111], v118 offset:2304
	ds_read_b64 v[112:113], v118 offset:512
	ds_read_b64 v[114:115], v118 offset:2560
	ds_read_b64 v[116:117], v118 offset:768
	ds_read_b64 v[118:119], v118 offset:2816
	v_add_u32_e32 v136, s17, v146
	ds_read_b64 v[120:121], v136
	ds_read_b64 v[122:123], v136 offset:2048
	ds_read_b64 v[124:125], v136 offset:256
	ds_read_b64 v[126:127], v136 offset:2304
	v_bitop3_b32 v73, v129, v75, v130 bitop3:0xc8
	v_bitop3_b32 v75, v75, v129, v130 bitop3:0x10
	v_bitop3_b32 v77, v129, v79, v130 bitop3:0xc8
	v_bitop3_b32 v79, v79, v129, v130 bitop3:0x10
	v_bitop3_b32 v81, v129, v83, v130 bitop3:0xc8
	v_bitop3_b32 v83, v83, v129, v130 bitop3:0x10
	ds_read_b64 v[128:129], v136 offset:512
	ds_read_b64 v[130:131], v136 offset:2560
	ds_read_b64 v[134:135], v136 offset:768
	ds_read_b64 v[136:137], v136 offset:2816
	s_mov_b32 s11, 0
	s_waitcnt lgkmcnt(14)
	v_mfma_f32_16x16x32_bf16 v[104:107], v[104:107], v[100:103], 0
	s_waitcnt lgkmcnt(12)
	v_mfma_f32_16x16x32_bf16 v[108:111], v[108:111], v[100:103], 0
	s_waitcnt lgkmcnt(10)
	v_mfma_f32_16x16x32_bf16 v[112:115], v[112:115], v[100:103], 0
	s_waitcnt lgkmcnt(8)
	v_mfma_f32_16x16x32_bf16 v[100:103], v[116:119], v[100:103], 0
	s_waitcnt lgkmcnt(6)
	v_mfma_f32_16x16x32_bf16 v[104:107], v[120:123], v[96:99], v[104:107]
	s_waitcnt lgkmcnt(4)
	v_mfma_f32_16x16x32_bf16 v[108:111], v[124:127], v[96:99], v[108:111]
	s_waitcnt lgkmcnt(2)
	v_mfma_f32_16x16x32_bf16 v[112:115], v[128:131], v[96:99], v[112:115]
	s_waitcnt lgkmcnt(0)
	v_mfma_f32_16x16x32_bf16 v[96:99], v[134:137], v[96:99], v[100:103]
	v_add_u32_e32 v126, s16, v146
	s_nop 0
	ds_read_b64 v[100:101], v126
	ds_read_b64 v[102:103], v126 offset:2048
	ds_read_b64 v[116:117], v126 offset:256
	ds_read_b64 v[118:119], v126 offset:2304
	ds_read_b64 v[120:121], v126 offset:512
	ds_read_b64 v[122:123], v126 offset:2560
	ds_read_b64 v[124:125], v126 offset:768
	ds_read_b64 v[126:127], v126 offset:2816
	v_add_u32_e32 v144, s15, v146
	ds_read_b64 v[128:129], v144
	ds_read_b64 v[130:131], v144 offset:2048
	ds_read_b64 v[134:135], v144 offset:256
	ds_read_b64 v[136:137], v144 offset:2304
	ds_read_b64 v[138:139], v144 offset:512
	ds_read_b64 v[140:141], v144 offset:2560
	ds_read_b64 v[142:143], v144 offset:768
	ds_read_b64 v[144:145], v144 offset:2816
	s_waitcnt lgkmcnt(14)
	v_mfma_f32_16x16x32_bf16 v[100:103], v[100:103], v[92:95], v[104:107]
	s_waitcnt lgkmcnt(12)
	v_mfma_f32_16x16x32_bf16 v[104:107], v[116:119], v[92:95], v[108:111]
	s_waitcnt lgkmcnt(10)
	v_mfma_f32_16x16x32_bf16 v[108:111], v[120:123], v[92:95], v[112:115]
	s_waitcnt lgkmcnt(8)
	v_mfma_f32_16x16x32_bf16 v[92:95], v[124:127], v[92:95], v[96:99]
	s_waitcnt lgkmcnt(6)
	v_mfma_f32_16x16x32_bf16 v[96:99], v[128:131], v[88:91], v[100:103]
	s_waitcnt lgkmcnt(4)
	v_mfma_f32_16x16x32_bf16 v[100:103], v[134:137], v[88:91], v[104:107]
	s_waitcnt lgkmcnt(2)
	v_mfma_f32_16x16x32_bf16 v[104:107], v[138:141], v[88:91], v[108:111]
	s_waitcnt lgkmcnt(0)
	v_mfma_f32_16x16x32_bf16 v[88:91], v[142:145], v[88:91], v[92:95]
	v_add_u32_e32 v118, s14, v146
	s_nop 0
	ds_read_b64 v[92:93], v118
	ds_read_b64 v[94:95], v118 offset:2048
	ds_read_b64 v[108:109], v118 offset:256
	ds_read_b64 v[110:111], v118 offset:2304
	ds_read_b64 v[112:113], v118 offset:512
	ds_read_b64 v[114:115], v118 offset:2560
	ds_read_b64 v[116:117], v118 offset:768
	ds_read_b64 v[118:119], v118 offset:2816
	v_add_u32_e32 v136, s13, v146
	ds_read_b64 v[120:121], v136
	ds_read_b64 v[122:123], v136 offset:2048
	ds_read_b64 v[124:125], v136 offset:256
	ds_read_b64 v[126:127], v136 offset:2304
	ds_read_b64 v[128:129], v136 offset:512
	ds_read_b64 v[130:131], v136 offset:2560
	ds_read_b64 v[134:135], v136 offset:768
	ds_read_b64 v[136:137], v136 offset:2816
	s_waitcnt lgkmcnt(14)
	v_mfma_f32_16x16x32_bf16 v[92:95], v[92:95], v[84:87], v[96:99]
	s_waitcnt lgkmcnt(12)
; #define LAS __attribute__((address_space(3)))
; __device__ __forceinline__ unsigned cvt_pk_bf16(float lo, float hi) { const f32x2_t v = {lo, hi}; const bf16x2_t r = __builtin_convertvector(v, bf16x2_t); return __builtin_bit_cast(unsigned, r); }
; __device__ __forceinline__ float bf_lo(unsigned w) { return __uint_as_float(w << 16); }
; __device__ __forceinline__ float bf_hi(unsigned w) { return __uint_as_float(w & 0xffff0000u); }
; template <bool SWA, bool FAST>
; __device__ __forceinline__ void att_tile(const AttnP& P, LAS unsigned char* lds, int lane, int tb, int qpos0, int hq, int kloc0, int r, int ct, int kr0, int kc0, const AttQZ& qz, float shift) {
;     ...
; #pragma unroll
;     for (int s0 = 0; s0 < NSEG; s0 += GV) {
;         u32x2 vf[GV][4][2];
; #pragma unroll
;         for (int g = 0; g < GV; ++g) { const int s = s0 + g;
;             const int segv = SWA ? s * 4096 : ((kr0 + s) % 9) * 8192;
; #pragma unroll
;             for (int dt = 0; dt < 4; ++dt) {
;                 vf[g][dt][0] = *(const LAS u32x2*)(vb0 + segv + dt * 256); asm volatile("" ::: "memory");
;                 vf[g][dt][1] = *(const LAS u32x2*)(vb0 + segv + dt * 256 + 2048); asm volatile("" ::: "memory"); } }
;         __builtin_amdgcn_sched_barrier(0);
;         __builtin_amdgcn_s_setprio(1);
; #pragma unroll
;         for (int g = 0; g < GV; ++g)
; #pragma unroll
;             for (int dt = 0; dt < 4; ++dt) {
;                 u32x4 w; w.x = vf[g][dt][0].x; w.y = vf[g][dt][0].y; w.z = vf[g][dt][1].x; w.w = vf[g][dt][1].y;
;                 oacc[dt] = __builtin_amdgcn_mfma_f32_16x16x32_bf16(__builtin_bit_cast(bf16x8, w), pb[s0 + g], oacc[dt], 0, 0, 0); }
;         __builtin_amdgcn_s_setprio(0);
;         __builtin_amdgcn_sched_barrier(0);
;     }
;     const size_t tq = (size_t)(tb + qpos0 + li);
; #pragma unroll
;     for (int hh = 0; hh < 2; ++hh) {
;         const u32x4 z = qz.z[hh]; const f32x4 a = oacc[2 * hh], b = oacc[2 * hh + 1];
;         u32x4 o; o.x = cvt_pk_bf16(a[0] * rl * bf_lo(z.x), a[1] * rl * bf_hi(z.x)); o.y = cvt_pk_bf16(a[2] * rl * bf_lo(z.y), a[3] * rl * bf_hi(z.y));
;         o.z = cvt_pk_bf16(b[0] * rl * bf_lo(z.z), b[1] * rl * bf_hi(z.z)); o.w = cvt_pk_bf16(b[2] * rl * bf_lo(z.w), b[3] * rl * bf_hi(z.w));
;         *(u32x4*)(P.Y + tq * 1024 + (SWA ? 512 : 0) + hq * 64 + 32 * hh + 8 * fq) = o;
;     }
	v_mfma_f32_16x16x32_bf16 v[96:99], v[108:111], v[84:87], v[100:103]
	s_waitcnt lgkmcnt(10)
	v_mfma_f32_16x16x32_bf16 v[100:103], v[112:115], v[84:87], v[104:107]
	s_waitcnt lgkmcnt(8)
	v_mfma_f32_16x16x32_bf16 v[84:87], v[116:119], v[84:87], v[88:91]
	s_waitcnt lgkmcnt(6)
	v_mfma_f32_16x16x32_bf16 v[88:91], v[120:123], v[76:79], v[92:95]
	s_waitcnt lgkmcnt(4)
	v_mfma_f32_16x16x32_bf16 v[92:95], v[124:127], v[76:79], v[96:99]
	s_waitcnt lgkmcnt(2)
	v_mfma_f32_16x16x32_bf16 v[96:99], v[128:131], v[76:79], v[100:103]
	s_waitcnt lgkmcnt(0)
	v_mfma_f32_16x16x32_bf16 v[76:79], v[134:137], v[76:79], v[84:87]
	v_add_u32_e32 v110, s12, v146
	s_nop 0
	ds_read_b64 v[84:85], v110
	ds_read_b64 v[86:87], v110 offset:2048
	ds_read_b64 v[100:101], v110 offset:256
	ds_read_b64 v[102:103], v110 offset:2304
	ds_read_b64 v[104:105], v110 offset:512
	ds_read_b64 v[106:107], v110 offset:2560
	ds_read_b64 v[108:109], v110 offset:768
	ds_read_b64 v[110:111], v110 offset:2816
	v_add_u32_e32 v126, s10, v146
	ds_read_b64 v[112:113], v126
	ds_read_b64 v[114:115], v126 offset:2048
	ds_read_b64 v[116:117], v126 offset:256
	ds_read_b64 v[118:119], v126 offset:2304
	ds_read_b64 v[120:121], v126 offset:512
	ds_read_b64 v[122:123], v126 offset:2560
	ds_read_b64 v[124:125], v126 offset:768
	ds_read_b64 v[126:127], v126 offset:2816
	s_waitcnt lgkmcnt(14)
	v_mfma_f32_16x16x32_bf16 v[84:87], v[84:87], v[72:75], v[88:91]
	s_waitcnt lgkmcnt(12)
	v_mfma_f32_16x16x32_bf16 v[88:91], v[100:103], v[72:75], v[92:95]
	s_waitcnt lgkmcnt(10)
	v_mfma_f32_16x16x32_bf16 v[92:95], v[104:107], v[72:75], v[96:99]
	s_waitcnt lgkmcnt(8)
	v_mfma_f32_16x16x32_bf16 v[72:75], v[108:111], v[72:75], v[76:79]
	s_waitcnt lgkmcnt(4)
	v_mfma_f32_16x16x32_bf16 v[88:91], v[116:119], v[80:83], v[88:91]
	v_mfma_f32_16x16x32_bf16 v[84:87], v[112:115], v[80:83], v[84:87]
	s_waitcnt lgkmcnt(2)
	v_mfma_f32_16x16x32_bf16 v[92:95], v[120:123], v[80:83], v[92:95]
	s_waitcnt lgkmcnt(0)
	v_mfma_f32_16x16x32_bf16 v[80:83], v[124:127], v[80:83], v[72:75]
	s_nop 1
	v_div_scale_f32 v72, s[0:1], v133, v133, 1.0
	v_rcp_f32_e32 v73, v72
	v_div_scale_f32 v74, vcc, 1.0, v133, 1.0
	s_waitcnt vmcnt(2)
	v_lshlrev_b32_e32 v78, 16, v60
	v_fma_f32 v75, -v72, v73, 1.0
	v_fmac_f32_e32 v73, v75, v73
	v_mul_f32_e32 v75, v74, v73
	v_fma_f32 v76, -v72, v75, v74
	v_fmac_f32_e32 v75, v76, v73
	v_fma_f32 v72, -v72, v75, v74
	v_div_fmas_f32 v72, v72, v73, v75
	v_div_fixup_f32 v96, v72, v133, 1.0
	v_pk_mul_f32 v[74:75], v[96:97], v[84:85] op_sel_hi:[0,1]
	v_and_b32_e32 v79, 0xffff0000, v60
	v_or_b32_e32 v72, s29, v132
	v_pk_mul_f32 v[74:75], v[74:75], v[78:79]
	v_or_b32_e32 v72, s30, v72
	v_cvt_pk_bf16_f32 v60, v74, v75
	v_pk_mul_f32 v[74:75], v[96:97], v[86:87] op_sel_hi:[0,1]
	v_lshlrev_b32_e32 v78, 16, v61
	v_and_b32_e32 v79, 0xffff0000, v61
	v_add_u32_e32 v72, s28, v72
	v_pk_mul_f32 v[74:75], v[74:75], v[78:79]
	v_ashrrev_i32_e32 v73, 31, v72
	v_cvt_pk_bf16_f32 v61, v74, v75
	v_pk_mul_f32 v[74:75], v[96:97], v[88:89] op_sel_hi:[0,1]
	v_lshlrev_b32_e32 v78, 16, v62
	v_and_b32_e32 v79, 0xffff0000, v62
	v_lshlrev_b64 v[72:73], 11, v[72:73]
	v_pk_mul_f32 v[74:75], v[74:75], v[78:79]
	v_mov_b32_e32 v77, 0
	v_cvt_pk_bf16_f32 v62, v74, v75
	v_pk_mul_f32 v[74:75], v[96:97], v[90:91] op_sel_hi:[0,1]
	v_lshlrev_b32_e32 v78, 16, v63
	v_and_b32_e32 v79, 0xffff0000, v63
	v_lshl_add_u64 v[72:73], s[24:25], 0, v[72:73]
	s_lshl_b32 s10, s26, 7
	v_pk_mul_f32 v[74:75], v[74:75], v[78:79]
	v_lshl_add_u64 v[78:79], v[72:73], 0, s[10:11]
	v_lshlrev_b32_e32 v72, 4, v183
	v_mov_b32_e32 v73, v77
	v_cvt_pk_bf16_f32 v63, v74, v75
	v_lshl_add_u64 v[72:73], v[78:79], 0, v[72:73]
	global_store_dwordx4 v[72:73], v[60:63], off
	v_lshlrev_b32_e32 v76, 3, v183
	s_nop 0
	v_pk_mul_f32 v[60:61], v[96:97], v[92:93] op_sel_hi:[0,1]
	s_waitcnt vmcnt(2)
	v_lshlrev_b32_e32 v62, 16, v56
	v_and_b32_e32 v63, 0xffff0000, v56
	v_pk_mul_f32 v[60:61], v[60:61], v[62:63]
	v_lshlrev_b32_e32 v56, 16, v57
	v_cvt_pk_bf16_f32 v72, v60, v61
	v_pk_mul_f32 v[60:61], v[96:97], v[94:95] op_sel_hi:[0,1]
	v_and_b32_e32 v57, 0xffff0000, v57
	v_pk_mul_f32 v[56:57], v[60:61], v[56:57]
	v_lshlrev_b32_e32 v60, 16, v58
	v_cvt_pk_bf16_f32 v73, v56, v57
	v_pk_mul_f32 v[56:57], v[96:97], v[80:81] op_sel_hi:[0,1]
	v_and_b32_e32 v61, 0xffff0000, v58
	v_pk_mul_f32 v[56:57], v[56:57], v[60:61]
	s_nop 0
	v_cvt_pk_bf16_f32 v74, v56, v57
	v_mul_f32_e32 v56, v96, v82
	v_lshlrev_b32_e32 v82, 16, v59
	v_mov_b32_e32 v57, v96
	v_pk_mul_f32 v[88:89], v[56:57], v[82:83]

; template <bool SWA, bool FAST>
; __device__ __forceinline__ void att_tile(const AttnP& P, LAS unsigned char* lds, int lane, int tb, int qpos0, int hq, int kloc0, int r, int ct, int kr0, int kc0, const AttQZ& qz, float shift) {
;     ...
;     const int krow0 = (SWA ? kloc0 : kc0) + li, ksw = (krow0 >> 1) & 7;
;     const LAS unsigned char* kb0 = lds + krow0 * 128 + ((fq ^ ksw) << 4);
;     const LAS unsigned char* kb1 = lds + krow0 * 128 + (((fq + 4) ^ ksw) << 4);
; #pragma unroll
;     for (int s0 = 0; s0 < NSEG; s0 += GS) {
;         bf16x8 kf[GS][2][2];
; #pragma unroll
;         for (int g = 0; g < GS; ++g)
; #pragma unroll
;             for (int kt = 0; kt < 2; ++kt) { const int s = s0 + g;
;                 const int segoff = SWA ? (32 * s + 16 * kt) * 128 : (((kr0 + s) % 9) * 64 + 16 * kt) * 128;
;                 kf[g][kt][0] = *(const LAS bf16x8*)(kb0 + segoff); kf[g][kt][1] = *(const LAS bf16x8*)(kb1 + segoff); }
;         __builtin_amdgcn_sched_barrier(0);
;         __builtin_amdgcn_s_setprio(1);
; #pragma unroll
;         for (int g = 0; g < GS; ++g)
; #pragma unroll
;             for (int kt = 0; kt < 2; ++kt) {
;                 f32x4 z = FAST ? (f32x4){-shift, -shift, -shift, -shift} : (f32x4){0.f, 0.f, 0.f, 0.f};
;                 z = __builtin_amdgcn_mfma_f32_16x16x32_bf16(kf[g][kt][0], bq0, z, 0, 0, 0);
;                 z = __builtin_amdgcn_mfma_f32_16x16x32_bf16(kf[g][kt][1], bq1, z, 0, 0, 0);
;                 sc[s0 + g][kt] = z; }
;         __builtin_amdgcn_s_setprio(0);
;         __builtin_amdgcn_sched_barrier(0);
;     }
;     float mx = -1e30f;
;     if (SWA) {
;         const int qp = qpos0 + li;
; #pragma unroll
;         for (int s = 0; s < NSEG; ++s) {
;             const int kb0 = qpos0 - 128 + 32 * s;
;             if (s >= 1 && s <= 7 && kb0 >= 0 && kb0 + 31 < SEQ) {
; #pragma unroll
;                 for (int kt = 0; kt < 2; ++kt)
; #pragma unroll
;                     for (int j = 0; j < 4; ++j) { if (!FAST) mx = fmaxf(mx, sc[s][kt][j]); }
;             } else {
;                 asm volatile("");
; #pragma unroll
;                 for (int kt = 0; kt < 2; ++kt)
; #pragma unroll
;                     for (int j = 0; j < 4; ++j) { const int kp = kb0 + 16 * kt + 4 * fq + j; const int d = kp - qp;
;                         const bool ok = (kp >= 0) && (kp < SEQ) && (d <= 128) && (d >= -128);
.LBB0_378:
	v_add_u32_e32 v60, v221, v196
	v_lshrrev_b32_e32 v61, 1, v60
	v_lshl_add_u32 v63, v60, 7, 0
	v_bitop3_b32 v60, v61, v183, 7 bitop3:0x6c
	v_lshlrev_b32_e32 v60, 4, v60
	v_bitop3_b32 v61, v61, v198, 7 bitop3:0x6c
	v_add_u32_e32 v60, v63, v60
	v_lshlrev_b32_e32 v61, 4, v61
	v_add_u32_e32 v61, v63, v61
	s_waitcnt lgkmcnt(11)
	ds_read_b128 v[96:99], v60
	s_waitcnt lgkmcnt(11)
	ds_read_b128 v[108:111], v60 offset:2048
	s_waitcnt lgkmcnt(11)
	ds_read_b128 v[124:127], v61
	s_waitcnt lgkmcnt(11)
	ds_read_b128 v[112:115], v61 offset:2048
	s_waitcnt lgkmcnt(11)
	ds_read_b128 v[116:119], v60 offset:4096
	s_waitcnt lgkmcnt(11)
	ds_read_b128 v[120:123], v60 offset:6144
	s_waitcnt lgkmcnt(11)
	ds_read_b128 v[136:139], v61 offset:4096
	s_waitcnt lgkmcnt(11)
	ds_read_b128 v[128:131], v61 offset:6144
	s_waitcnt lgkmcnt(11)
	ds_read_b128 v[132:135], v60 offset:8192
	s_waitcnt lgkmcnt(11)
	ds_read_b128 v[152:155], v60 offset:10240
	s_waitcnt lgkmcnt(11)
	ds_read_b128 v[160:163], v61 offset:8192
	s_waitcnt lgkmcnt(11)
	ds_read_b128 v[156:159], v61 offset:10240
	v_cndmask_b32_e64 v63, 0, 1, s[68:69]
	v_cmp_ne_u32_e64 s[56:57], 1, v63
	s_mov_b64 s[84:85], exec
	v_readlane_b32 s86, v249, 9
	v_readlane_b32 s87, v249, 10
	s_and_b64 s[86:87], s[84:85], s[86:87]
	s_xor_b64 s[84:85], s[86:87], s[84:85]
	s_mov_b64 exec, s[86:87]
	s_cbranch_execz .LBB0_408
	s_waitcnt lgkmcnt(11)
	v_mfma_f32_16x16x32_bf16 v[88:91], v[96:99], v[64:67], 0
	s_waitcnt lgkmcnt(9)
	v_mfma_f32_16x16x32_bf16 v[146:149], v[124:127], v[68:71], v[88:91]
	v_mfma_f32_16x16x32_bf16 v[88:91], v[108:111], v[64:67], 0
	s_waitcnt lgkmcnt(8)
	v_mfma_f32_16x16x32_bf16 v[222:225], v[112:115], v[68:71], v[88:91]
	s_waitcnt lgkmcnt(7)
	v_mfma_f32_16x16x32_bf16 v[88:91], v[116:119], v[64:67], 0
	s_waitcnt lgkmcnt(5)
	v_mfma_f32_16x16x32_bf16 v[136:139], v[136:139], v[68:71], v[88:91]
	v_mfma_f32_16x16x32_bf16 v[88:91], v[120:123], v[64:67], 0
	s_waitcnt lgkmcnt(4)
	v_mfma_f32_16x16x32_bf16 v[140:143], v[128:131], v[68:71], v[88:91]
	s_waitcnt lgkmcnt(3)
	v_mfma_f32_16x16x32_bf16 v[88:91], v[132:135], v[64:67], 0
	s_waitcnt lgkmcnt(1)
	v_mfma_f32_16x16x32_bf16 v[128:131], v[160:163], v[68:71], v[88:91]
	v_mfma_f32_16x16x32_bf16 v[88:91], v[152:155], v[64:67], 0
	s_waitcnt lgkmcnt(0)
	v_mfma_f32_16x16x32_bf16 v[132:135], v[156:159], v[68:71], v[88:91]
	s_nop 4
	ds_read_b128 v[88:91], v60 offset:12288
	ds_read_b128 v[92:95], v60 offset:14336
	ds_read_b128 v[96:99], v61 offset:12288
	ds_read_b128 v[100:103], v61 offset:14336
	ds_read_b128 v[104:107], v60 offset:16384
	ds_read_b128 v[108:111], v60 offset:18432
	ds_read_b128 v[112:115], v61 offset:16384
	ds_read_b128 v[116:119], v61 offset:18432
	ds_read_b128 v[150:153], v60 offset:20480
	ds_read_b128 v[154:157], v60 offset:22528
	ds_read_b128 v[158:161], v61 offset:20480
	ds_read_b128 v[226:229], v61 offset:22528
	s_waitcnt lgkmcnt(11)
	v_mfma_f32_16x16x32_bf16 v[88:91], v[88:91], v[64:67], 0
	s_waitcnt lgkmcnt(9)
	v_mfma_f32_16x16x32_bf16 v[120:123], v[96:99], v[68:71], v[88:91]
	v_mfma_f32_16x16x32_bf16 v[88:91], v[92:95], v[64:67], 0
	s_waitcnt lgkmcnt(8)
	v_mfma_f32_16x16x32_bf16 v[124:127], v[100:103], v[68:71], v[88:91]
	s_waitcnt lgkmcnt(7)
	v_mfma_f32_16x16x32_bf16 v[88:91], v[104:107], v[64:67], 0
	s_waitcnt lgkmcnt(5)
	v_mfma_f32_16x16x32_bf16 v[112:115], v[112:115], v[68:71], v[88:91]
	v_mfma_f32_16x16x32_bf16 v[88:91], v[108:111], v[64:67], 0
	s_waitcnt lgkmcnt(4)
	v_mfma_f32_16x16x32_bf16 v[116:119], v[116:119], v[68:71], v[88:91]
	s_waitcnt lgkmcnt(3)
	v_mfma_f32_16x16x32_bf16 v[88:91], v[150:153], v[64:67], 0
	s_waitcnt lgkmcnt(1)
	v_mfma_f32_16x16x32_bf16 v[104:107], v[158:161], v[68:71], v[88:91]
	v_mfma_f32_16x16x32_bf16 v[88:91], v[154:157], v[64:67], 0
	s_waitcnt lgkmcnt(0)
	v_mfma_f32_16x16x32_bf16 v[108:111], v[226:229], v[68:71], v[88:91]
	s_nop 4
	ds_read_b128 v[88:91], v61 offset:24576
	ds_read_b128 v[92:95], v61 offset:26624
	ds_read_b128 v[100:103], v60 offset:26624
	ds_read_b128 v[150:153], v60 offset:28672
	ds_read_b128 v[154:157], v61 offset:28672
	ds_read_b128 v[158:161], v61 offset:30720
	ds_read_b128 v[96:99], v60 offset:24576
	ds_read_b128 v[226:229], v60 offset:32768
	ds_read_b128 v[230:233], v60 offset:30720
	ds_read_b128 v[234:237], v61 offset:32768
	s_waitcnt lgkmcnt(3)
	v_mfma_f32_16x16x32_bf16 v[96:99], v[96:99], v[64:67], 0
	v_mfma_f32_16x16x32_bf16 v[96:99], v[88:91], v[68:71], v[96:99]
	v_mfma_f32_16x16x32_bf16 v[88:91], v[100:103], v[64:67], 0
	v_mfma_f32_16x16x32_bf16 v[100:103], v[92:95], v[68:71], v[88:91]
	v_mfma_f32_16x16x32_bf16 v[88:91], v[150:153], v[64:67], 0
	s_waitcnt lgkmcnt(1)
	v_mfma_f32_16x16x32_bf16 v[92:95], v[230:233], v[64:67], 0
	v_mfma_f32_16x16x32_bf16 v[64:67], v[226:229], v[64:67], 0
	v_mfma_f32_16x16x32_bf16 v[88:91], v[154:157], v[68:71], v[88:91]
	v_mfma_f32_16x16x32_bf16 v[92:95], v[158:161], v[68:71], v[92:95]
	s_waitcnt lgkmcnt(0)
	v_mfma_f32_16x16x32_bf16 v[64:67], v[234:237], v[68:71], v[64:67]
	v_cndmask_b32_e64 v150, v220, v146, s[16:17]
	v_cndmask_b32_e64 v147, v220, v147, s[18:19]
	s_mov_b32 s86, 0xf149f2ca
	v_max3_f32 v60, v150, s86, v147
	v_cndmask_b32_e64 v146, v220, v148, s[20:21]
	v_cndmask_b32_e64 v145, v220, v149, s[22:23]
	v_max3_f32 v60, v60, v146, v145
	v_cndmask_b32_e64 v144, v220, v222, s[24:25]
	v_cndmask_b32_e64 v69, v220, v223, s[26:27]
	v_max3_f32 v63, v60, v144, v69
	v_cndmask_b32_e64 v61, v220, v224, s[28:29]
	v_cndmask_b32_e64 v60, v220, v225, s[30:31]
	v_max3_f32 v154, v63, v61, v60
	s_mov_b64 s[86:87], -1
	s_and_b64 vcc, exec, s[56:57]
	v_mov_b32_e32 v63, v139
	v_mov_b32_e32 v68, v138
	v_mov_b32_e32 v70, v137
	v_mov_b32_e32 v71, v136
	v_mov_b32_e32 v148, v143
	v_mov_b32_e32 v149, v142
	v_mov_b32_e32 v151, v141
	v_mov_b32_e32 v152, v140
	s_cbranch_vccnz .LBB0_381
	v_readlane_b32 s86, v249, 48
	v_readlane_b32 s87, v249, 49
	s_nop 1
	v_cndmask_b32_e64 v71, v220, v136, s[86:87]
	v_readlane_b32 s86, v249, 50
	v_readlane_b32 s87, v249, 51
	s_nop 1
	v_cndmask_b32_e64 v70, v220, v137, s[86:87]
	v_readlane_b32 s86, v249, 52
	v_readlane_b32 s87, v249, 53
	v_max3_f32 v148, v154, v71, v70
	s_nop 0
	v_cndmask_b32_e64 v68, v220, v138, s[86:87]
	v_readlane_b32 s86, v249, 54
	v_readlane_b32 s87, v249, 55
	s_nop 1
	v_cndmask_b32_e64 v63, v220, v139, s[86:87]
	v_readlane_b32 s86, v249, 56
	v_readlane_b32 s87, v249, 57
	v_max3_f32 v148, v148, v68, v63
	s_nop 0
	v_cndmask_b32_e64 v152, v220, v140, s[86:87]
	v_readlane_b32 s86, v249, 58
	v_readlane_b32 s87, v249, 59
	s_nop 1
	v_cndmask_b32_e64 v151, v220, v141, s[86:87]
	v_readlane_b32 s86, v249, 60
	v_readlane_b32 s87, v249, 61
	v_max3_f32 v153, v148, v152, v151
	s_nop 0
	v_cndmask_b32_e64 v149, v220, v142, s[86:87]
	v_readlane_b32 s86, v249, 62
	v_readlane_b32 s87, v249, 63
	s_nop 1
	v_cndmask_b32_e64 v148, v220, v143, s[86:87]
	v_max3_f32 v153, v153, v149, v148
	s_mov_b64 s[86:87], 0

; #define LAS __attribute__((address_space(3)))
; template <bool SWA, bool FAST>
; __device__ __forceinline__ void att_tile(const AttnP& P, LAS unsigned char* lds, int lane, int tb, int qpos0, int hq, int kloc0, int r, int ct, int kr0, int kc0, const AttQZ& qz, float shift) {
;     ...
;     if (!FAST) { mx = fmaxf(mx, __shfl_xor(mx, 16)); mx = fmaxf(mx, __shfl_xor(mx, 32)); }
;     float sk = 0.f;
;     if (SWA) { sk = P.sink[hq] * LOG2E; if (!FAST) mx = fmaxf(mx, sk); }
;     float l = 0.f; f32x2_t l2 = {0.f, 0.f};
;     bf16x8 pb[NSEG];
;     if constexpr (!SWA && FAST) {
;         const int c = 16 * ct + li, cs = min(max(c - 8, 0), 48), w = cs - kc0;
;         const LAS float* rp = (const LAS float*)(lds + ATT_RPB) + (kr0 - r + 7) * 64 + (kc0 + 4 * fq - c + 31);
;         bool hi[4]; const LAS float* rpj[4];
; #pragma unroll
;         for (int j = 0; j < 4; ++j) { hi[j] = (4 * fq + j) < w; rpj[j] = rp + (hi[j] ? 16 : 0) + j; }
;         const unsigned m01 = (hi[0] ? 0u : 0xffffu) | (hi[1] ? 0u : 0xffff0000u), m23 = (hi[2] ? 0u : 0xffffu) | (hi[3] ? 0u : 0xffff0000u);
; #pragma unroll
;         for (int s = 0; s < NSEG; ++s) {
;             float p[4];
; #pragma unroll
;             for (int j = 0; j < 4; ++j) { const float v = hi[j] ? sc[s][1][j] : sc[s][0][j]; p[j] = __builtin_amdgcn_exp2f(v + rpj[j][s * 64]); }
;             l2 += (f32x2_t){p[0], p[1]}; l2 += (f32x2_t){p[2], p[3]};
;             const unsigned pk01 = cvt_pk_bf16(p[0], p[1]), pk23 = cvt_pk_bf16(p[2], p[3]);
;             u32x4 wv; wv.x = pk01 & m01; wv.y = pk23 & m23; wv.z = pk01 & ~m01; wv.w = pk23 & ~m23;
;             pb[s] = __builtin_bit_cast(bf16x8, wv);
;         }
;     } else
; #pragma unroll
;     for (int s = 0; s < NSEG; ++s) {
;         float p[8];
; #pragma unroll
;         for (int kt = 0; kt < 2; ++kt)
; #pragma unroll
;             for (int j = 0; j < 4; ++j) p[4 * kt + j] = __builtin_amdgcn_exp2f(FAST ? sc[s][kt][j] : sc[s][kt][j] - mx);
; #pragma unroll
;         for (int e = 0; e < 8; e += 2) l2 += (f32x2_t){p[e], p[e + 1]};
;         u32x4 w; w.x = cvt_pk_bf16(p[0], p[1]); w.y = cvt_pk_bf16(p[2], p[3]); w.z = cvt_pk_bf16(p[4], p[5]); w.w = cvt_pk_bf16(p[6], p[7]);
;         pb[s] = __builtin_bit_cast(bf16x8, w);
;     }
.LBB0_407:
	global_load_dword v227, v165, s[2:3]
	v_cndmask_b32_e64 v228, v220, v64, s[10:11]
	v_max_f32_e32 v64, v100, v100
	v_cndmask_b32_e64 v229, v220, v65, s[12:13]
	v_max_f32_e32 v65, v228, v228
	v_cndmask_b32_e64 v230, v220, v66, s[14:15]
	v_max_f32_e32 v64, v64, v65
	v_cndmask_b32_e64 v231, v220, v67, s[34:35]
	v_max3_f32 v64, v64, v229, v230
	s_mov_b32 s86, 0xf149f2ca
	v_max3_f32 v64, v64, v231, s86
	ds_bpermute_b32 v65, v180, v64
	s_mov_b32 s86, 0x3fb8aa3b
	s_waitcnt lgkmcnt(0)
	v_max_f32_e32 v65, v65, v65
	v_max_f32_e32 v64, v64, v65
	ds_bpermute_b32 v65, v181, v64
	s_waitcnt vmcnt(0)
	v_mul_f32_e32 v66, 0x3fb8aa3b, v227
	s_waitcnt lgkmcnt(0)
	v_max3_f32 v232, v64, v65, v66
	v_sub_f32_e32 v64, v150, v232
	v_sub_f32_e32 v65, v147, v232
	v_sub_f32_e32 v66, v146, v232
	v_sub_f32_e32 v67, v145, v232
	v_sub_f32_e32 v89, v61, v232
	v_sub_f32_e32 v90, v60, v232
	v_exp_f32_e32 v60, v64
	v_exp_f32_e32 v61, v65
	v_sub_f32_e32 v88, v144, v232
	v_sub_f32_e32 v69, v69, v232
	v_exp_f32_e32 v64, v66
	v_exp_f32_e32 v65, v67
	v_exp_f32_e32 v66, v88
	v_exp_f32_e32 v67, v69
	v_sub_f32_e32 v71, v71, v232
	v_sub_f32_e32 v91, v70, v232
	v_sub_f32_e32 v92, v68, v232
	v_exp_f32_e32 v68, v89
	v_exp_f32_e32 v69, v90
	v_sub_f32_e32 v63, v63, v232
	v_sub_f32_e32 v107, v141, v232
	v_sub_f32_e32 v108, v140, v232
	v_sub_f32_e32 v112, v131, v232
	v_exp_f32_e32 v70, v71
	v_exp_f32_e32 v71, v91
	v_pk_add_f32 v[140:141], v[60:61], 0 op_sel_hi:[1,0]
	v_sub_f32_e32 v93, v152, v232
	v_sub_f32_e32 v94, v151, v232
	v_sub_f32_e32 v103, v137, v232
	v_exp_f32_e32 v88, v92
	v_exp_f32_e32 v89, v63
	v_exp_f32_e32 v137, v112
	v_cvt_pk_bf16_f32 v112, v60, v61
	v_pk_add_f32 v[60:61], v[64:65], v[140:141]
	v_sub_f32_e32 v95, v149, v232
	v_sub_f32_e32 v100, v148, v232
	v_exp_f32_e32 v90, v93
	v_exp_f32_e32 v91, v94
	v_pk_add_f32 v[60:61], v[66:67], v[60:61]
	v_sub_f32_e32 v101, v139, v232
	v_sub_f32_e32 v102, v138, v232
	v_exp_f32_e32 v92, v95
	v_exp_f32_e32 v93, v100
	v_pk_add_f32 v[60:61], v[68:69], v[60:61]
	v_sub_f32_e32 v104, v136, v232
	v_exp_f32_e32 v94, v101
	v_exp_f32_e32 v95, v102
	v_pk_add_f32 v[60:61], v[70:71], v[60:61]
	v_sub_f32_e32 v105, v143, v232
	v_sub_f32_e32 v106, v142, v232
	v_exp_f32_e32 v100, v103
	v_exp_f32_e32 v101, v104
	v_pk_add_f32 v[60:61], v[88:89], v[60:61]
	v_exp_f32_e32 v102, v105
	v_exp_f32_e32 v103, v106
	v_pk_add_f32 v[60:61], v[90:91], v[60:61]
	v_sub_f32_e32 v109, v134, v232
	v_sub_f32_e32 v110, v133, v232
	v_sub_f32_e32 v111, v132, v232
	v_exp_f32_e32 v132, v107
	v_exp_f32_e32 v133, v108
	v_pk_add_f32 v[60:61], v[92:93], v[60:61]
	v_sub_f32_e32 v113, v135, v232
	v_exp_f32_e32 v134, v109
	v_exp_f32_e32 v135, v110
	v_pk_add_f32 v[60:61], v[94:95], v[60:61]
	v_sub_f32_e32 v63, v130, v232
	v_exp_f32_e32 v136, v111
	v_pk_add_f32 v[60:61], v[100:101], v[60:61]
	v_exp_f32_e32 v139, v63
	v_sub_f32_e32 v63, v129, v232
	v_exp_f32_e32 v138, v113
	v_cvt_pk_bf16_f32 v113, v64, v65
	v_pk_add_f32 v[60:61], v[102:103], v[60:61]
	v_exp_f32_e32 v64, v63
	v_sub_f32_e32 v63, v128, v232
	v_pk_add_f32 v[60:61], v[132:133], v[60:61]
	v_exp_f32_e32 v65, v63
	v_pk_add_f32 v[60:61], v[134:135], v[60:61]
	v_sub_f32_e32 v63, v127, v232
	v_pk_add_f32 v[60:61], v[136:137], v[60:61]
	v_cvt_pk_bf16_f32 v108, v70, v71
	v_pk_add_f32 v[60:61], v[138:139], v[60:61]
	v_cvt_pk_bf16_f32 v71, v64, v65
	v_pk_add_f32 v[60:61], v[64:65], v[60:61]
	v_exp_f32_e32 v64, v63
	v_sub_f32_e32 v63, v126, v232
	v_exp_f32_e32 v65, v63
	v_sub_f32_e32 v63, v125, v232
	v_cvt_pk_bf16_f32 v114, v66, v67
	v_exp_f32_e32 v66, v63
	v_sub_f32_e32 v63, v124, v232
	v_exp_f32_e32 v67, v63
	v_sub_f32_e32 v63, v123, v232
	v_cvt_pk_bf16_f32 v109, v88, v89
	v_exp_f32_e32 v88, v63
	v_sub_f32_e32 v63, v122, v232
	v_exp_f32_e32 v89, v63
	v_sub_f32_e32 v63, v121, v232
	v_cvt_pk_bf16_f32 v110, v90, v91
	v_exp_f32_e32 v90, v63
	v_sub_f32_e32 v63, v120, v232
	v_exp_f32_e32 v91, v63
	v_sub_f32_e32 v63, v156, v232
	v_cvt_pk_bf16_f32 v111, v92, v93
	v_pk_add_f32 v[60:61], v[64:65], v[60:61]
	v_cvt_pk_bf16_f32 v92, v64, v65
	v_exp_f32_e32 v64, v63
	v_sub_f32_e32 v63, v155, v232
	v_exp_f32_e32 v65, v63
	v_sub_f32_e32 v63, v154, v232
	v_pk_add_f32 v[60:61], v[66:67], v[60:61]
	v_cvt_pk_bf16_f32 v93, v66, v67
	v_exp_f32_e32 v66, v63
	v_sub_f32_e32 v63, v153, v232
	v_exp_f32_e32 v67, v63
	v_sub_f32_e32 v63, v119, v232
	v_cvt_pk_bf16_f32 v104, v94, v95
	v_pk_add_f32 v[60:61], v[88:89], v[60:61]
	v_cvt_pk_bf16_f32 v94, v88, v89
	v_exp_f32_e32 v88, v63
	v_sub_f32_e32 v63, v118, v232
	v_exp_f32_e32 v89, v63
	v_sub_f32_e32 v63, v117, v232
	v_pk_add_f32 v[60:61], v[90:91], v[60:61]
	v_cvt_pk_bf16_f32 v95, v90, v91
	v_exp_f32_e32 v90, v63
	v_sub_f32_e32 v63, v116, v232
	v_exp_f32_e32 v91, v63
	v_sub_f32_e32 v63, v222, v232
	v_cvt_pk_bf16_f32 v105, v100, v101
	v_pk_add_f32 v[60:61], v[64:65], v[60:61]
	v_cvt_pk_bf16_f32 v100, v64, v65
	v_exp_f32_e32 v64, v63
	v_sub_f32_e32 v63, v163, v232
	v_exp_f32_e32 v65, v63
	v_sub_f32_e32 v63, v162, v232
	v_pk_add_f32 v[60:61], v[66:67], v[60:61]
	v_cvt_pk_bf16_f32 v101, v66, v67
	v_exp_f32_e32 v66, v63
	v_sub_f32_e32 v63, v161, v232
	v_exp_f32_e32 v67, v63
	v_sub_f32_e32 v63, v160, v232
	v_cvt_pk_bf16_f32 v106, v102, v103
	v_pk_add_f32 v[60:61], v[88:89], v[60:61]
	v_cvt_pk_bf16_f32 v102, v88, v89
	v_exp_f32_e32 v88, v63
	v_sub_f32_e32 v63, v159, v232
	v_exp_f32_e32 v89, v63
	v_sub_f32_e32 v63, v158, v232
	v_pk_add_f32 v[60:61], v[90:91], v[60:61]
	v_cvt_pk_bf16_f32 v103, v90, v91
	v_exp_f32_e32 v90, v63
	v_sub_f32_e32 v63, v157, v232
	v_exp_f32_e32 v91, v63
	v_pk_add_f32 v[60:61], v[64:65], v[60:61]
	v_sub_f32_e32 v63, v225, v232
	v_pk_add_f32 v[60:61], v[66:67], v[60:61]
; template <bool SWA, bool FAST>
; __device__ __forceinline__ void att_tile(const AttnP& P, LAS unsigned char* lds, int lane, int tb, int qpos0, int hq, int kloc0, int r, int ct, int kr0, int kc0, const AttQZ& qz, float shift) {
;     ...
; #pragma unroll
;     for (int s = 0; s < NSEG; ++s) {
;         float p[8];
; #pragma unroll
;         for (int kt = 0; kt < 2; ++kt)
; #pragma unroll
;             for (int j = 0; j < 4; ++j) p[4 * kt + j] = __builtin_amdgcn_exp2f(FAST ? sc[s][kt][j] : sc[s][kt][j] - mx);
; #pragma unroll
;         for (int e = 0; e < 8; e += 2) l2 += (f32x2_t){p[e], p[e + 1]};
;         u32x4 w; w.x = cvt_pk_bf16(p[0], p[1]); w.y = cvt_pk_bf16(p[2], p[3]); w.z = cvt_pk_bf16(p[4], p[5]); w.w = cvt_pk_bf16(p[6], p[7]);
;         pb[s] = __builtin_bit_cast(bf16x8, w);
;     }
;     l += l2[0] + l2[1];
;     l += __shfl_xor(l, 16); l += __shfl_xor(l, 32);
;     if (SWA) l += __builtin_amdgcn_exp2f(FAST ? sk - shift : sk - mx);
;     const float rl = 1.0f / l;
;     f32x4 oacc[4];
; #pragma unroll
;     for (int dt = 0; dt < 4; ++dt) oacc[dt] = (f32x4){0.f, 0.f, 0.f, 0.f};
;     constexpr int GV = SWA ? 3 : 2;
;     const int g0l = (SWA ? kloc0 : kc0) + 4 * fq;
;     const LAS unsigned char* vb0 = lds + ATT_VOFF + (g0l >> 3) * 1024 + li * 16 + (g0l & 7) * 2;
; #pragma unroll
;     for (int s0 = 0; s0 < NSEG; s0 += GV) {
;         u32x2 vf[GV][4][2];
; #pragma unroll
;         for (int g = 0; g < GV; ++g) { const int s = s0 + g;
;             const int segv = SWA ? s * 4096 : ((kr0 + s) % 9) * 8192;
; #pragma unroll
;             for (int dt = 0; dt < 4; ++dt) {
;                 vf[g][dt][0] = *(const LAS u32x2*)(vb0 + segv + dt * 256); asm volatile("" ::: "memory");
;                 vf[g][dt][1] = *(const LAS u32x2*)(vb0 + segv + dt * 256 + 2048); asm volatile("" ::: "memory"); } }
;         __builtin_amdgcn_sched_barrier(0);
;         __builtin_amdgcn_s_setprio(1);
; #pragma unroll
;         for (int g = 0; g < GV; ++g)
; #pragma unroll
;             for (int dt = 0; dt < 4; ++dt) {
;                 u32x4 w; w.x = vf[g][dt][0].x; w.y = vf[g][dt][0].y; w.z = vf[g][dt][1].x; w.w = vf[g][dt][1].y;
;                 oacc[dt] = __builtin_amdgcn_mfma_f32_16x16x32_bf16(__builtin_bit_cast(bf16x8, w), pb[s0 + g], oacc[dt], 0, 0, 0); }
;         __builtin_amdgcn_s_setprio(0);
;         __builtin_amdgcn_sched_barrier(0);
;     }
	v_cvt_pk_bf16_f32 v64, v64, v65
	v_pk_add_f32 v[60:61], v[88:89], v[60:61]
	v_cvt_pk_bf16_f32 v65, v66, v67
	v_cvt_pk_bf16_f32 v66, v88, v89
	v_exp_f32_e32 v88, v63
	v_sub_f32_e32 v63, v226, v232
	v_exp_f32_e32 v89, v63
	v_sub_f32_e32 v63, v223, v232
	v_pk_add_f32 v[60:61], v[90:91], v[60:61]
	v_cvt_pk_bf16_f32 v67, v90, v91
	v_exp_f32_e32 v90, v63
	v_sub_f32_e32 v63, v224, v232
	v_exp_f32_e32 v91, v63
	v_sub_f32_e32 v63, v98, v232
	v_exp_f32_e32 v98, v63
	v_sub_f32_e32 v63, v99, v232
	v_exp_f32_e32 v99, v63
	v_sub_f32_e32 v63, v96, v232
	v_exp_f32_e32 v96, v63
	v_sub_f32_e32 v63, v97, v232
	v_exp_f32_e32 v97, v63
	v_sub_f32_e32 v63, v228, v232
	v_exp_f32_e32 v116, v63
	v_sub_f32_e32 v63, v229, v232
	v_exp_f32_e32 v117, v63
	v_sub_f32_e32 v63, v230, v232
	v_pk_add_f32 v[60:61], v[88:89], v[60:61]
	v_exp_f32_e32 v118, v63
	v_sub_f32_e32 v63, v231, v232
	v_pk_add_f32 v[60:61], v[90:91], v[60:61]
	v_exp_f32_e32 v119, v63
	v_sub_f32_e32 v63, 0xf149f2ca, v232
	v_pk_add_f32 v[60:61], v[98:99], v[60:61]
	v_exp_f32_e32 v120, v63
	v_pk_add_f32 v[60:61], v[96:97], v[60:61]
	v_fma_f32 v63, v227, s86, -v232
	v_pk_add_f32 v[60:61], v[116:117], v[60:61]
	v_exp_f32_e32 v63, v63
	v_pk_add_f32 v[60:61], v[118:119], v[60:61]
	v_cvt_pk_bf16_f32 v88, v88, v89
	v_pk_add_f32 v[60:61], v[120:121], v[60:61] op_sel_hi:[0,1]
	v_pk_add_f32 v[60:61], v[120:121], v[60:61] op_sel_hi:[0,1]
	v_add_f32_e32 v60, v60, v61
	v_add_f32_e32 v60, 0, v60
	ds_bpermute_b32 v61, v180, v60
	v_cvt_pk_bf16_f32 v89, v90, v91
	v_cvt_pk_bf16_f32 v91, v96, v97
	v_cvt_pk_bf16_f32 v96, v116, v117
	v_cvt_pk_bf16_f32 v97, v118, v119
	s_waitcnt lgkmcnt(0)
	v_add_f32_e32 v60, v60, v61
	ds_bpermute_b32 v61, v181, v60
	v_cvt_pk_bf16_f32 v90, v98, v99
	v_cvt_pk_bf16_f32 v98, v120, v120
	v_cvt_pk_bf16_f32 v107, v132, v133
	v_cvt_pk_bf16_f32 v115, v68, v69
	s_waitcnt lgkmcnt(0)
	v_add_f32_e32 v60, v60, v61
	v_add_f32_e32 v140, v63, v60
	v_add_u32_e32 v60, v221, v199
	v_lshlrev_b32_e32 v61, 7, v60
	v_lshlrev_b32_e32 v60, 1, v60
	v_and_b32_e32 v61, 0xfffffc00, v61
	v_and_b32_e32 v60, 14, v60
	v_add3_u32 v60, v200, v61, v60
	ds_read_b64 v[116:117], v60
	ds_read_b64 v[118:119], v60 offset:2048
	ds_read_b64 v[120:121], v60 offset:256
	ds_read_b64 v[122:123], v60 offset:2304
	ds_read_b64 v[124:125], v60 offset:512
	ds_read_b64 v[126:127], v60 offset:2560
	ds_read_b64 v[128:129], v60 offset:768
	ds_read_b64 v[130:131], v60 offset:2816
	ds_read_b64 v[132:133], v60 offset:4096
	v_cvt_pk_bf16_f32 v68, v134, v135
	ds_read_b64 v[134:135], v60 offset:6144
	v_cvt_pk_bf16_f32 v69, v136, v137
	ds_read_b64 v[136:137], v60 offset:4352
	v_cvt_pk_bf16_f32 v70, v138, v139
	ds_read_b64 v[138:139], v60 offset:6400
	ds_read_b64 v[142:143], v60 offset:4608
	ds_read_b64 v[144:145], v60 offset:6656
	ds_read_b64 v[146:147], v60 offset:4864
	ds_read_b64 v[148:149], v60 offset:6912
	ds_read_b64 v[150:151], v60 offset:8192
	ds_read_b64 v[152:153], v60 offset:10240
	ds_read_b64 v[154:155], v60 offset:8448
	ds_read_b64 v[156:157], v60 offset:10496
	ds_read_b64 v[158:159], v60 offset:8704
	ds_read_b64 v[160:161], v60 offset:10752
	ds_read_b64 v[222:223], v60 offset:8960
	ds_read_b64 v[224:225], v60 offset:11008
	v_mov_b32_e32 v99, v98
	s_waitcnt lgkmcnt(14)
	v_mfma_f32_16x16x32_bf16 v[116:119], v[116:119], v[112:115], 0
	v_mfma_f32_16x16x32_bf16 v[120:123], v[120:123], v[112:115], 0
	v_mfma_f32_16x16x32_bf16 v[124:127], v[124:127], v[112:115], 0
	v_mfma_f32_16x16x32_bf16 v[112:115], v[128:131], v[112:115], 0
	v_mfma_f32_16x16x32_bf16 v[116:119], v[132:135], v[108:111], v[116:119]
	s_waitcnt lgkmcnt(12)
	v_mfma_f32_16x16x32_bf16 v[120:123], v[136:139], v[108:111], v[120:123]
	s_waitcnt lgkmcnt(10)
	v_mfma_f32_16x16x32_bf16 v[124:127], v[142:145], v[108:111], v[124:127]
	s_waitcnt lgkmcnt(8)
	v_mfma_f32_16x16x32_bf16 v[108:111], v[146:149], v[108:111], v[112:115]
	s_waitcnt lgkmcnt(6)
	v_mfma_f32_16x16x32_bf16 v[112:115], v[150:153], v[104:107], v[116:119]
	s_waitcnt lgkmcnt(4)
	v_mfma_f32_16x16x32_bf16 v[116:119], v[154:157], v[104:107], v[120:123]
	s_waitcnt lgkmcnt(2)
	v_mfma_f32_16x16x32_bf16 v[120:123], v[158:161], v[104:107], v[124:127]
	s_waitcnt lgkmcnt(0)
	v_mfma_f32_16x16x32_bf16 v[104:107], v[222:225], v[104:107], v[108:111]
	s_nop 1
	ds_read_b64 v[108:109], v60 offset:12288
	ds_read_b64 v[110:111], v60 offset:14336
	ds_read_b64 v[124:125], v60 offset:12544
	ds_read_b64 v[126:127], v60 offset:14592
	ds_read_b64 v[128:129], v60 offset:12800
	ds_read_b64 v[130:131], v60 offset:14848
	ds_read_b64 v[132:133], v60 offset:13056
	ds_read_b64 v[134:135], v60 offset:15104
	ds_read_b64 v[136:137], v60 offset:16384
	ds_read_b64 v[138:139], v60 offset:18432
	ds_read_b64 v[142:143], v60 offset:16640
	ds_read_b64 v[144:145], v60 offset:18688
	ds_read_b64 v[146:147], v60 offset:16896
	ds_read_b64 v[148:149], v60 offset:18944
	ds_read_b64 v[150:151], v60 offset:17152
	ds_read_b64 v[152:153], v60 offset:19200
	ds_read_b64 v[154:155], v60 offset:20480
	ds_read_b64 v[156:157], v60 offset:22528
	ds_read_b64 v[158:159], v60 offset:20736
	ds_read_b64 v[160:161], v60 offset:22784
	ds_read_b64 v[222:223], v60 offset:20992
	ds_read_b64 v[224:225], v60 offset:23040
	ds_read_b64 v[226:227], v60 offset:21248
	ds_read_b64 v[228:229], v60 offset:23296
	s_waitcnt lgkmcnt(14)
	v_mfma_f32_16x16x32_bf16 v[108:111], v[108:111], v[68:71], v[112:115]
	v_mfma_f32_16x16x32_bf16 v[112:115], v[124:127], v[68:71], v[116:119]
	v_mfma_f32_16x16x32_bf16 v[116:119], v[128:131], v[68:71], v[120:123]
	v_mfma_f32_16x16x32_bf16 v[68:71], v[132:135], v[68:71], v[104:107]
	v_mfma_f32_16x16x32_bf16 v[104:107], v[136:139], v[92:95], v[108:111]
	s_waitcnt lgkmcnt(12)
; #define LAS __attribute__((address_space(3)))
; template <bool SWA, bool FAST>
; __device__ __forceinline__ void att_tile(const AttnP& P, LAS unsigned char* lds, int lane, int tb, int qpos0, int hq, int kloc0, int r, int ct, int kr0, int kc0, const AttQZ& qz, float shift) {
;     ...
; #pragma unroll
;     for (int s0 = 0; s0 < NSEG; s0 += GV) {
;         u32x2 vf[GV][4][2];
; #pragma unroll
;         for (int g = 0; g < GV; ++g) { const int s = s0 + g;
;             const int segv = SWA ? s * 4096 : ((kr0 + s) % 9) * 8192;
; #pragma unroll
;             for (int dt = 0; dt < 4; ++dt) {
;                 vf[g][dt][0] = *(const LAS u32x2*)(vb0 + segv + dt * 256); asm volatile("" ::: "memory");
;                 vf[g][dt][1] = *(const LAS u32x2*)(vb0 + segv + dt * 256 + 2048); asm volatile("" ::: "memory"); } }
;         __builtin_amdgcn_sched_barrier(0);
;         __builtin_amdgcn_s_setprio(1);
; #pragma unroll
;         for (int g = 0; g < GV; ++g)
; #pragma unroll
;             for (int dt = 0; dt < 4; ++dt) {
;                 u32x4 w; w.x = vf[g][dt][0].x; w.y = vf[g][dt][0].y; w.z = vf[g][dt][1].x; w.w = vf[g][dt][1].y;
;                 oacc[dt] = __builtin_amdgcn_mfma_f32_16x16x32_bf16(__builtin_bit_cast(bf16x8, w), pb[s0 + g], oacc[dt], 0, 0, 0); }
;         __builtin_amdgcn_s_setprio(0);
;         __builtin_amdgcn_sched_barrier(0);
;     }
	v_mfma_f32_16x16x32_bf16 v[108:111], v[142:145], v[92:95], v[112:115]
	s_waitcnt lgkmcnt(10)
	v_mfma_f32_16x16x32_bf16 v[112:115], v[146:149], v[92:95], v[116:119]
	s_waitcnt lgkmcnt(8)
	v_mfma_f32_16x16x32_bf16 v[68:71], v[150:153], v[92:95], v[68:71]
	s_waitcnt lgkmcnt(6)
	v_mfma_f32_16x16x32_bf16 v[92:95], v[154:157], v[100:103], v[104:107]
	s_waitcnt lgkmcnt(4)
	v_mfma_f32_16x16x32_bf16 v[104:107], v[158:161], v[100:103], v[108:111]
	s_waitcnt lgkmcnt(2)
	v_mfma_f32_16x16x32_bf16 v[108:111], v[222:225], v[100:103], v[112:115]
	s_waitcnt lgkmcnt(0)
	v_mfma_f32_16x16x32_bf16 v[68:71], v[226:229], v[100:103], v[68:71]
	ds_read_b64 v[100:101], v60 offset:24576
	ds_read_b64 v[102:103], v60 offset:26624
	ds_read_b64 v[112:113], v60 offset:24832
	ds_read_b64 v[114:115], v60 offset:26880
	ds_read_b64 v[116:117], v60 offset:25088
	ds_read_b64 v[118:119], v60 offset:27136
	ds_read_b64 v[120:121], v60 offset:25344
	ds_read_b64 v[122:123], v60 offset:27392
	ds_read_b64 v[124:125], v60 offset:28672
	ds_read_b64 v[126:127], v60 offset:30720
	ds_read_b64 v[128:129], v60 offset:28928
	ds_read_b64 v[130:131], v60 offset:30976
	ds_read_b64 v[132:133], v60 offset:29184
	ds_read_b64 v[134:135], v60 offset:31232
	ds_read_b64 v[136:137], v60 offset:29440
	ds_read_b64 v[138:139], v60 offset:31488
	ds_read_b64 v[142:143], v60 offset:32768
	ds_read_b64 v[144:145], v60 offset:34816
	ds_read_b64 v[146:147], v60 offset:33024
	ds_read_b64 v[148:149], v60 offset:35072
	ds_read_b64 v[150:151], v60 offset:33280
	ds_read_b64 v[152:153], v60 offset:35328
	ds_read_b64 v[154:155], v60 offset:33536
	ds_read_b64 v[156:157], v60 offset:35584
	s_waitcnt lgkmcnt(14)
	v_mfma_f32_16x16x32_bf16 v[92:95], v[100:103], v[64:67], v[92:95]
	v_mfma_f32_16x16x32_bf16 v[100:103], v[112:115], v[64:67], v[104:107]
	v_mfma_f32_16x16x32_bf16 v[104:107], v[116:119], v[64:67], v[108:111]
	v_mfma_f32_16x16x32_bf16 v[64:67], v[120:123], v[64:67], v[68:71]
	v_mfma_f32_16x16x32_bf16 v[68:71], v[124:127], v[88:91], v[92:95]
	s_waitcnt lgkmcnt(12)
	v_mfma_f32_16x16x32_bf16 v[92:95], v[128:131], v[88:91], v[100:103]
	s_waitcnt lgkmcnt(10)
	v_mfma_f32_16x16x32_bf16 v[108:111], v[132:135], v[88:91], v[104:107]
	s_waitcnt lgkmcnt(8)
	v_mfma_f32_16x16x32_bf16 v[64:67], v[136:139], v[88:91], v[64:67]
	s_waitcnt lgkmcnt(6)
	v_mfma_f32_16x16x32_bf16 v[104:107], v[142:145], v[96:99], v[68:71]
	s_waitcnt lgkmcnt(4)
	v_mfma_f32_16x16x32_bf16 v[100:103], v[146:149], v[96:99], v[92:95]
	s_waitcnt lgkmcnt(2)
	v_mfma_f32_16x16x32_bf16 v[92:95], v[150:153], v[96:99], v[108:111]
	s_waitcnt lgkmcnt(0)
	v_mfma_f32_16x16x32_bf16 v[88:91], v[154:157], v[96:99], v[64:67]
; template <bool SWA, bool FAST>
; __device__ __forceinline__ void att_tile(const AttnP& P, LAS unsigned char* lds, int lane, int tb, int qpos0, int hq, int kloc0, int r, int ct, int kr0, int kc0, const AttQZ& qz, float shift) {
;     ...
;     const int krow0 = (SWA ? kloc0 : kc0) + li, ksw = (krow0 >> 1) & 7;
;     const LAS unsigned char* kb0 = lds + krow0 * 128 + ((fq ^ ksw) << 4);
;     const LAS unsigned char* kb1 = lds + krow0 * 128 + (((fq + 4) ^ ksw) << 4);
; #pragma unroll
;     for (int s0 = 0; s0 < NSEG; s0 += GS) {
;         bf16x8 kf[GS][2][2];
; #pragma unroll
;         for (int g = 0; g < GS; ++g)
; #pragma unroll
;             for (int kt = 0; kt < 2; ++kt) { const int s = s0 + g;
;                 const int segoff = SWA ? (32 * s + 16 * kt) * 128 : (((kr0 + s) % 9) * 64 + 16 * kt) * 128;
;                 kf[g][kt][0] = *(const LAS bf16x8*)(kb0 + segoff); kf[g][kt][1] = *(const LAS bf16x8*)(kb1 + segoff); }
;         __builtin_amdgcn_sched_barrier(0);
;         __builtin_amdgcn_s_setprio(1);
; #pragma unroll
;         for (int g = 0; g < GS; ++g)
; #pragma unroll
;             for (int kt = 0; kt < 2; ++kt) {
;                 f32x4 z = FAST ? (f32x4){-shift, -shift, -shift, -shift} : (f32x4){0.f, 0.f, 0.f, 0.f};
;                 z = __builtin_amdgcn_mfma_f32_16x16x32_bf16(kf[g][kt][0], bq0, z, 0, 0, 0);
;                 z = __builtin_amdgcn_mfma_f32_16x16x32_bf16(kf[g][kt][1], bq1, z, 0, 0, 0);
;                 sc[s0 + g][kt] = z; }
;         __builtin_amdgcn_s_setprio(0);
;         __builtin_amdgcn_sched_barrier(0);
;     }
;     float mx = -1e30f;
;     if (SWA) {
;         const int qp = qpos0 + li;
; #pragma unroll
;         for (int s = 0; s < NSEG; ++s) {
;             const int kb0 = qpos0 - 128 + 32 * s;
;             if (s >= 1 && s <= 7 && kb0 >= 0 && kb0 + 31 < SEQ) {
; #pragma unroll
;                 for (int kt = 0; kt < 2; ++kt)
; #pragma unroll
;                     for (int j = 0; j < 4; ++j) { if (!FAST) mx = fmaxf(mx, sc[s][kt][j]); }
;             } else {
;                 asm volatile("");
; #pragma unroll
;                 for (int kt = 0; kt < 2; ++kt)
; #pragma unroll
;                     for (int j = 0; j < 4; ++j) { const int kp = kb0 + 16 * kt + 4 * fq + j; const int d = kp - qp;
;                         const bool ok = (kp >= 0) && (kp < SEQ) && (d <= 128) && (d >= -128);
.LBB0_408:
	s_andn2_saveexec_b64 s[84:85], s[84:85]
	s_cbranch_execz .LBB0_418
	s_waitcnt lgkmcnt(11)
	v_mfma_f32_16x16x32_bf16 v[88:91], v[96:99], v[64:67], v[56:59]
	s_waitcnt lgkmcnt(9)
	v_mfma_f32_16x16x32_bf16 v[144:147], v[124:127], v[68:71], v[88:91]
	v_mfma_f32_16x16x32_bf16 v[88:91], v[108:111], v[64:67], v[56:59]
	s_waitcnt lgkmcnt(8)
	v_mfma_f32_16x16x32_bf16 v[148:151], v[112:115], v[68:71], v[88:91]
	s_waitcnt lgkmcnt(7)
	v_mfma_f32_16x16x32_bf16 v[88:91], v[116:119], v[64:67], v[56:59]
	s_waitcnt lgkmcnt(5)
	v_mfma_f32_16x16x32_bf16 v[140:143], v[136:139], v[68:71], v[88:91]
	v_mfma_f32_16x16x32_bf16 v[88:91], v[120:123], v[64:67], v[56:59]
	s_waitcnt lgkmcnt(4)
	v_mfma_f32_16x16x32_bf16 v[136:139], v[128:131], v[68:71], v[88:91]
	s_waitcnt lgkmcnt(3)
	v_mfma_f32_16x16x32_bf16 v[88:91], v[132:135], v[64:67], v[56:59]
	s_waitcnt lgkmcnt(1)
	v_mfma_f32_16x16x32_bf16 v[132:135], v[160:163], v[68:71], v[88:91]
	v_mfma_f32_16x16x32_bf16 v[88:91], v[152:155], v[64:67], v[56:59]
	s_waitcnt lgkmcnt(0)
	v_mfma_f32_16x16x32_bf16 v[124:127], v[156:159], v[68:71], v[88:91]
	s_nop 4
	ds_read_b128 v[88:91], v60 offset:12288
	ds_read_b128 v[92:95], v60 offset:14336
	ds_read_b128 v[96:99], v61 offset:12288
	ds_read_b128 v[100:103], v61 offset:14336
	ds_read_b128 v[104:107], v60 offset:16384
	ds_read_b128 v[108:111], v60 offset:18432
	ds_read_b128 v[112:115], v61 offset:16384
	ds_read_b128 v[152:155], v61 offset:18432
	ds_read_b128 v[156:159], v60 offset:20480
	ds_read_b128 v[160:163], v60 offset:22528
	ds_read_b128 v[222:225], v61 offset:20480
	ds_read_b128 v[226:229], v61 offset:22528
	s_waitcnt lgkmcnt(11)
	v_mfma_f32_16x16x32_bf16 v[88:91], v[88:91], v[64:67], v[56:59]
	s_waitcnt lgkmcnt(9)
	v_mfma_f32_16x16x32_bf16 v[128:131], v[96:99], v[68:71], v[88:91]
	v_mfma_f32_16x16x32_bf16 v[88:91], v[92:95], v[64:67], v[56:59]
	s_waitcnt lgkmcnt(8)
	v_mfma_f32_16x16x32_bf16 v[120:123], v[100:103], v[68:71], v[88:91]
	s_waitcnt lgkmcnt(7)
	v_mfma_f32_16x16x32_bf16 v[88:91], v[104:107], v[64:67], v[56:59]
	s_waitcnt lgkmcnt(5)
	v_mfma_f32_16x16x32_bf16 v[116:119], v[112:115], v[68:71], v[88:91]
	v_mfma_f32_16x16x32_bf16 v[88:91], v[108:111], v[64:67], v[56:59]
	s_waitcnt lgkmcnt(4)
	v_mfma_f32_16x16x32_bf16 v[112:115], v[152:155], v[68:71], v[88:91]
	s_waitcnt lgkmcnt(3)
	v_mfma_f32_16x16x32_bf16 v[88:91], v[156:159], v[64:67], v[56:59]
	s_waitcnt lgkmcnt(1)
	v_mfma_f32_16x16x32_bf16 v[108:111], v[222:225], v[68:71], v[88:91]
	v_mfma_f32_16x16x32_bf16 v[88:91], v[160:163], v[64:67], v[56:59]
	s_waitcnt lgkmcnt(0)
	v_mfma_f32_16x16x32_bf16 v[104:107], v[226:229], v[68:71], v[88:91]
	s_nop 4
	ds_read_b128 v[88:91], v61 offset:24576
	ds_read_b128 v[92:95], v61 offset:26624
	ds_read_b128 v[96:99], v60 offset:26624
	ds_read_b128 v[152:155], v60 offset:28672
	ds_read_b128 v[156:159], v61 offset:28672
	ds_read_b128 v[160:163], v61 offset:30720
	ds_read_b128 v[100:103], v60 offset:24576
	ds_read_b128 v[222:225], v60 offset:32768
	ds_read_b128 v[226:229], v60 offset:30720
	ds_read_b128 v[230:233], v61 offset:32768
	s_waitcnt lgkmcnt(3)
	v_mfma_f32_16x16x32_bf16 v[100:103], v[100:103], v[64:67], v[56:59]
	v_mfma_f32_16x16x32_bf16 v[100:103], v[88:91], v[68:71], v[100:103]
	v_mfma_f32_16x16x32_bf16 v[88:91], v[96:99], v[64:67], v[56:59]
	v_mfma_f32_16x16x32_bf16 v[96:99], v[92:95], v[68:71], v[88:91]
	v_mfma_f32_16x16x32_bf16 v[88:91], v[152:155], v[64:67], v[56:59]
	v_mfma_f32_16x16x32_bf16 v[92:95], v[156:159], v[68:71], v[88:91]
	s_waitcnt lgkmcnt(1)
	v_mfma_f32_16x16x32_bf16 v[88:91], v[226:229], v[64:67], v[56:59]
	v_mfma_f32_16x16x32_bf16 v[64:67], v[222:225], v[64:67], v[56:59]
	v_mfma_f32_16x16x32_bf16 v[88:91], v[160:163], v[68:71], v[88:91]
	s_waitcnt lgkmcnt(0)
	v_mfma_f32_16x16x32_bf16 v[64:67], v[230:233], v[68:71], v[64:67]
	s_and_b64 vcc, exec, s[56:57]
	s_cbranch_vccnz .LBB0_420
	v_readlane_b32 s56, v249, 48
	v_readlane_b32 s57, v249, 49
	s_nop 1
	v_cndmask_b32_e64 v140, v220, v140, s[56:57]
	v_readlane_b32 s56, v249, 50
	v_readlane_b32 s57, v249, 51
	s_nop 1
	v_cndmask_b32_e64 v141, v220, v141, s[56:57]
	v_readlane_b32 s56, v249, 52
	v_readlane_b32 s57, v249, 53
	s_nop 1
	v_cndmask_b32_e64 v142, v220, v142, s[56:57]
	v_readlane_b32 s56, v249, 54
	v_readlane_b32 s57, v249, 55
	s_nop 1
	v_cndmask_b32_e64 v143, v220, v143, s[56:57]
	v_readlane_b32 s56, v249, 56
	v_readlane_b32 s57, v249, 57
	s_nop 1
	v_cndmask_b32_e64 v136, v220, v136, s[56:57]
	v_readlane_b32 s56, v249, 58
	v_readlane_b32 s57, v249, 59
	s_nop 1
	v_cndmask_b32_e64 v137, v220, v137, s[56:57]
	v_readlane_b32 s56, v249, 60
	v_readlane_b32 s57, v249, 61
	s_nop 1
	v_cndmask_b32_e64 v138, v220, v138, s[56:57]
	v_readlane_b32 s56, v249, 62
	v_readlane_b32 s57, v249, 63
	s_nop 1
	v_cndmask_b32_e64 v139, v220, v139, s[56:57]
	s_andn2_b64 vcc, exec, s[70:71]
	s_cbranch_vccz .LBB0_421

; template <bool SWA, bool FAST>
; __device__ __forceinline__ void att_tile(const AttnP& P, LAS unsigned char* lds, int lane, int tb, int qpos0, int hq, int kloc0, int r, int ct, int kr0, int kc0, const AttQZ& qz, float shift) {
;     ...
;                     for (int j = 0; j < 4; ++j) { const int kp = kb0 + 16 * kt + 4 * fq + j; const int d = kp - qp;
;                         const bool ok = (kp >= 0) && (kp < SEQ) && (d <= 128) && (d >= -128);
;                         const float v = ok ? sc[s][kt][j] : -1e30f; sc[s][kt][j] = v; if (!FAST) mx = fmaxf(mx, v); }
;             }
;         }
;     } else if (!FAST) {
;         const int c = 16 * ct + li, cs = min(max(c - 8, 0), 48);
;         const LAS float* rp = (const LAS float*)(lds + ATT_RPB) + (kr0 - r + 7) * 64 + (kc0 + 4 * fq - c + 31);
; #pragma unroll
;         for (int s = 0; s < NSEG; ++s) {
;             float bias[2][4];
; #pragma unroll
;             for (int kt = 0; kt < 2; ++kt)
; #pragma unroll
;                 for (int j = 0; j < 4; ++j) bias[kt][j] = rp[s * 64 + 16 * kt + j];
; #pragma unroll
;             for (int kt = 0; kt < 2; ++kt)
; #pragma unroll
;                 for (int j = 0; j < 4; ++j) { const int kc = kc0 + 16 * kt + 4 * fq + j; const bool ok = (kc >= cs) && (kc < cs + 16);
;                     float t = sc[s][kt][j] + bias[kt][j]; asm volatile("" : "+v"(t));
;                     const float v = ok ? t : -1e30f; sc[s][kt][j] = v; if (!FAST) mx = fmaxf(mx, v); }
;         }
;     }
;     if (!FAST) { mx = fmaxf(mx, __shfl_xor(mx, 16)); mx = fmaxf(mx, __shfl_xor(mx, 32)); }
;     float sk = 0.f;
;     if (SWA) { sk = P.sink[hq] * LOG2E; if (!FAST) mx = fmaxf(mx, sk); }
;     float l = 0.f; f32x2_t l2 = {0.f, 0.f};
;     bf16x8 pb[NSEG];
;     if constexpr (!SWA && FAST) {
;         const int c = 16 * ct + li, cs = min(max(c - 8, 0), 48), w = cs - kc0;
;         const LAS float* rp = (const LAS float*)(lds + ATT_RPB) + (kr0 - r + 7) * 64 + (kc0 + 4 * fq - c + 31);
;         bool hi[4]; const LAS float* rpj[4];
; #pragma unroll
;         for (int j = 0; j < 4; ++j) { hi[j] = (4 * fq + j) < w; rpj[j] = rp + (hi[j] ? 16 : 0) + j; }
;         const unsigned m01 = (hi[0] ? 0u : 0xffffu) | (hi[1] ? 0u : 0xffff0000u), m23 = (hi[2] ? 0u : 0xffffu) | (hi[3] ? 0u : 0xffff0000u);
; #pragma unroll
;         for (int s = 0; s < NSEG; ++s) {
;             float p[4];
; #pragma unroll
.LBB0_417:
	v_cndmask_b32_e64 v153, v220, v66, s[14:15]
	v_cndmask_b32_e64 v66, v220, v148, s[24:25]
	global_load_dword v148, v165, s[2:3]
	v_cndmask_b32_e64 v60, v220, v144, s[16:17]
	v_cndmask_b32_e64 v61, v220, v145, s[18:19]
	v_cndmask_b32_e64 v63, v220, v64, s[10:11]
	v_cndmask_b32_e64 v152, v220, v65, s[12:13]
	v_cndmask_b32_e64 v64, v220, v146, s[20:21]
	v_cndmask_b32_e64 v65, v220, v147, s[22:23]
	v_exp_f32_e32 v60, v60
	v_exp_f32_e32 v61, v61
	v_cndmask_b32_e64 v154, v220, v67, s[34:35]
	v_cndmask_b32_e64 v67, v220, v149, s[26:27]
	v_exp_f32_e32 v64, v64
	v_exp_f32_e32 v65, v65
	v_cndmask_b32_e64 v68, v220, v150, s[28:29]
	v_cndmask_b32_e64 v69, v220, v151, s[30:31]
	v_exp_f32_e32 v66, v66
	v_exp_f32_e32 v67, v67
	v_exp_f32_e32 v68, v68
	v_exp_f32_e32 v69, v69
	v_pk_add_f32 v[70:71], v[60:61], 0 op_sel_hi:[1,0]
	v_cvt_pk_bf16_f32 v144, v60, v61
	v_exp_f32_e32 v60, v140
	v_exp_f32_e32 v61, v141
	v_pk_add_f32 v[70:71], v[64:65], v[70:71]
	v_cvt_pk_bf16_f32 v145, v64, v65
	v_exp_f32_e32 v64, v142
	v_exp_f32_e32 v65, v143
	v_pk_add_f32 v[70:71], v[70:71], v[66:67]
	v_cvt_pk_bf16_f32 v146, v66, v67
	v_exp_f32_e32 v66, v136
	v_exp_f32_e32 v67, v137
	v_pk_add_f32 v[70:71], v[68:69], v[70:71]
	v_cvt_pk_bf16_f32 v147, v68, v69
	v_exp_f32_e32 v68, v138
	v_exp_f32_e32 v69, v139
	v_pk_add_f32 v[70:71], v[70:71], v[60:61]
	v_cvt_pk_bf16_f32 v136, v60, v61
	v_exp_f32_e32 v60, v132
	v_exp_f32_e32 v61, v133
	v_pk_add_f32 v[70:71], v[64:65], v[70:71]
	v_cvt_pk_bf16_f32 v137, v64, v65
	v_exp_f32_e32 v64, v134
	v_exp_f32_e32 v65, v135
	v_pk_add_f32 v[70:71], v[66:67], v[70:71]
	v_cvt_pk_bf16_f32 v138, v66, v67
	v_exp_f32_e32 v66, v124
	v_exp_f32_e32 v67, v125
	v_pk_add_f32 v[70:71], v[68:69], v[70:71]
	v_cvt_pk_bf16_f32 v139, v68, v69
	v_exp_f32_e32 v68, v126
	v_exp_f32_e32 v69, v127
	v_pk_add_f32 v[70:71], v[70:71], v[60:61]
	v_cvt_pk_bf16_f32 v124, v60, v61
	v_exp_f32_e32 v60, v128
	v_exp_f32_e32 v61, v129
	v_pk_add_f32 v[70:71], v[64:65], v[70:71]
	v_cvt_pk_bf16_f32 v125, v64, v65
	v_exp_f32_e32 v64, v130
	v_exp_f32_e32 v65, v131
	v_pk_add_f32 v[70:71], v[66:67], v[70:71]
	v_cvt_pk_bf16_f32 v126, v66, v67
	v_exp_f32_e32 v66, v120
	v_exp_f32_e32 v67, v121
	v_pk_add_f32 v[70:71], v[68:69], v[70:71]
	v_cvt_pk_bf16_f32 v127, v68, v69
	v_exp_f32_e32 v68, v122
	v_exp_f32_e32 v69, v123
	v_pk_add_f32 v[70:71], v[70:71], v[60:61]
	v_cvt_pk_bf16_f32 v120, v60, v61
	v_exp_f32_e32 v60, v116
	v_exp_f32_e32 v61, v117
	v_pk_add_f32 v[70:71], v[64:65], v[70:71]
	v_cvt_pk_bf16_f32 v121, v64, v65
	v_exp_f32_e32 v64, v118
	v_exp_f32_e32 v65, v119
	v_pk_add_f32 v[70:71], v[66:67], v[70:71]
	v_cvt_pk_bf16_f32 v122, v66, v67
	v_exp_f32_e32 v66, v112
	v_exp_f32_e32 v67, v113
	v_pk_add_f32 v[70:71], v[68:69], v[70:71]
	v_cvt_pk_bf16_f32 v123, v68, v69
	v_exp_f32_e32 v68, v114
	v_exp_f32_e32 v69, v115
	v_pk_add_f32 v[70:71], v[70:71], v[60:61]
	v_cvt_pk_bf16_f32 v112, v60, v61
	v_exp_f32_e32 v60, v108
	v_exp_f32_e32 v61, v109
	v_pk_add_f32 v[70:71], v[64:65], v[70:71]
	v_cvt_pk_bf16_f32 v113, v64, v65
	v_exp_f32_e32 v64, v110
	v_exp_f32_e32 v65, v111
	v_pk_add_f32 v[70:71], v[66:67], v[70:71]
	v_cvt_pk_bf16_f32 v114, v66, v67
	v_exp_f32_e32 v66, v104
	v_exp_f32_e32 v67, v105
	v_pk_add_f32 v[70:71], v[68:69], v[70:71]
	v_cvt_pk_bf16_f32 v115, v68, v69
	v_exp_f32_e32 v68, v106
	v_exp_f32_e32 v69, v107
	v_pk_add_f32 v[70:71], v[70:71], v[60:61]
	v_cvt_pk_bf16_f32 v104, v60, v61
	v_pk_add_f32 v[70:71], v[64:65], v[70:71]
	v_exp_f32_e32 v60, v100
	v_exp_f32_e32 v61, v101
	v_pk_add_f32 v[70:71], v[66:67], v[70:71]
	v_cvt_pk_bf16_f32 v106, v66, v67
	v_exp_f32_e32 v66, v102
	v_exp_f32_e32 v67, v103
	v_pk_add_f32 v[70:71], v[68:69], v[70:71]
	v_cvt_pk_bf16_f32 v107, v68, v69
	v_exp_f32_e32 v68, v96
	v_exp_f32_e32 v69, v97
	v_exp_f32_e32 v96, v98
	v_exp_f32_e32 v97, v99
	v_cvt_pk_bf16_f32 v105, v64, v65
	v_pk_add_f32 v[64:65], v[70:71], v[60:61]
	v_exp_f32_e32 v88, v88
	v_pk_add_f32 v[64:65], v[66:67], v[64:65]
	v_exp_f32_e32 v89, v89
	v_pk_add_f32 v[64:65], v[68:69], v[64:65]
	v_exp_f32_e32 v90, v90
	v_pk_add_f32 v[70:71], v[96:97], v[64:65]
	v_cvt_pk_bf16_f32 v64, v60, v61
	v_exp_f32_e32 v60, v92
	v_exp_f32_e32 v61, v93
	v_exp_f32_e32 v92, v94
	v_exp_f32_e32 v93, v95
	v_exp_f32_e32 v91, v91
	v_cvt_pk_bf16_f32 v65, v66, v67
	v_cvt_pk_bf16_f32 v66, v68, v69
	v_pk_add_f32 v[68:69], v[70:71], v[60:61]
	v_exp_f32_e32 v94, v63
	v_exp_f32_e32 v95, v152
	v_cvt_pk_bf16_f32 v67, v96, v97
	v_pk_add_f32 v[68:69], v[92:93], v[68:69]
	v_exp_f32_e32 v96, v153
	v_exp_f32_e32 v97, v154
	v_pk_add_f32 v[68:69], v[88:89], v[68:69]
	s_mov_b32 s56, 0x3fb8aa3b
	v_pk_add_f32 v[70:71], v[90:91], v[68:69]
	v_cvt_pk_bf16_f32 v68, v60, v61
	v_pk_add_f32 v[60:61], v[94:95], v[70:71]
	v_cvt_pk_bf16_f32 v70, v88, v89
	v_pk_add_f32 v[60:61], v[96:97], v[60:61]
	v_cvt_pk_bf16_f32 v71, v90, v91
	v_pk_add_f32 v[60:61], v[168:169], v[60:61]
	v_cvt_pk_bf16_f32 v69, v92, v93
	v_pk_add_f32 v[60:61], v[168:169], v[60:61]
	s_nop 0
	v_add_f32_e32 v60, v60, v61
	v_add_f32_e32 v61, 0, v60
	ds_bpermute_b32 v63, v180, v61
	v_cvt_pk_bf16_f32 v60, v94, v95
	s_waitcnt lgkmcnt(0)
	v_add_f32_e32 v88, v61, v63
	ds_bpermute_b32 v89, v181, v88
	s_waitcnt vmcnt(0)
	v_fma_f32 v61, v148, s56, -v182
	v_exp_f32_e32 v90, v61
	v_cvt_pk_bf16_f32 v61, v96, v97
	v_mov_b32_e32 v63, v62
	s_waitcnt lgkmcnt(0)
; #define LAS __attribute__((address_space(3)))
; template <bool SWA, bool FAST>
; __device__ __forceinline__ void att_tile(const AttnP& P, LAS unsigned char* lds, int lane, int tb, int qpos0, int hq, int kloc0, int r, int ct, int kr0, int kc0, const AttQZ& qz, float shift) {
;     ...
;     l += l2[0] + l2[1];
;     l += __shfl_xor(l, 16); l += __shfl_xor(l, 32);
;     if (SWA) l += __builtin_amdgcn_exp2f(FAST ? sk - shift : sk - mx);
;     const float rl = 1.0f / l;
;     f32x4 oacc[4];
; #pragma unroll
;     for (int dt = 0; dt < 4; ++dt) oacc[dt] = (f32x4){0.f, 0.f, 0.f, 0.f};
;     constexpr int GV = SWA ? 3 : 2;
;     const int g0l = (SWA ? kloc0 : kc0) + 4 * fq;
;     const LAS unsigned char* vb0 = lds + ATT_VOFF + (g0l >> 3) * 1024 + li * 16 + (g0l & 7) * 2;
; #pragma unroll
;     for (int s0 = 0; s0 < NSEG; s0 += GV) {
;         u32x2 vf[GV][4][2];
; #pragma unroll
;         for (int g = 0; g < GV; ++g) { const int s = s0 + g;
;             const int segv = SWA ? s * 4096 : ((kr0 + s) % 9) * 8192;
; #pragma unroll
;             for (int dt = 0; dt < 4; ++dt) {
;                 vf[g][dt][0] = *(const LAS u32x2*)(vb0 + segv + dt * 256); asm volatile("" ::: "memory");
;                 vf[g][dt][1] = *(const LAS u32x2*)(vb0 + segv + dt * 256 + 2048); asm volatile("" ::: "memory"); } }
;         __builtin_amdgcn_sched_barrier(0);
;         __builtin_amdgcn_s_setprio(1);
; #pragma unroll
;         for (int g = 0; g < GV; ++g)
; #pragma unroll
;             for (int dt = 0; dt < 4; ++dt) {
;                 u32x4 w; w.x = vf[g][dt][0].x; w.y = vf[g][dt][0].y; w.z = vf[g][dt][1].x; w.w = vf[g][dt][1].y;
;                 oacc[dt] = __builtin_amdgcn_mfma_f32_16x16x32_bf16(__builtin_bit_cast(bf16x8, w), pb[s0 + g], oacc[dt], 0, 0, 0); }
;         __builtin_amdgcn_s_setprio(0);
;         __builtin_amdgcn_sched_barrier(0);
;     }
	v_add_f32_e32 v88, v88, v89
	v_add_f32_e32 v140, v90, v88
	v_add_u32_e32 v88, v221, v199
	v_lshlrev_b32_e32 v89, 7, v88
	v_lshlrev_b32_e32 v88, 1, v88
	v_and_b32_e32 v89, 0xfffffc00, v89
	v_and_b32_e32 v88, 14, v88
	v_add3_u32 v141, v200, v89, v88
	ds_read_b64 v[88:89], v141
	ds_read_b64 v[90:91], v141 offset:2048
	ds_read_b64 v[92:93], v141 offset:256
	ds_read_b64 v[94:95], v141 offset:2304
	ds_read_b64 v[96:97], v141 offset:512
	ds_read_b64 v[98:99], v141 offset:2560
	ds_read_b64 v[100:101], v141 offset:768
	ds_read_b64 v[102:103], v141 offset:2816
	ds_read_b64 v[108:109], v141 offset:4096
	ds_read_b64 v[110:111], v141 offset:6144
	ds_read_b64 v[116:117], v141 offset:4352
	ds_read_b64 v[118:119], v141 offset:6400
	ds_read_b64 v[128:129], v141 offset:4608
	ds_read_b64 v[130:131], v141 offset:6656
	ds_read_b64 v[132:133], v141 offset:4864
	ds_read_b64 v[134:135], v141 offset:6912
	ds_read_b64 v[148:149], v141 offset:8192
	ds_read_b64 v[150:151], v141 offset:10240
	ds_read_b64 v[152:153], v141 offset:8448
	ds_read_b64 v[154:155], v141 offset:10496
	ds_read_b64 v[156:157], v141 offset:8704
	ds_read_b64 v[158:159], v141 offset:10752
	ds_read_b64 v[160:161], v141 offset:8960
	ds_read_b64 v[162:163], v141 offset:11008
	s_waitcnt lgkmcnt(14)
	v_mfma_f32_16x16x32_bf16 v[88:91], v[88:91], v[144:147], 0
	v_mfma_f32_16x16x32_bf16 v[92:95], v[92:95], v[144:147], 0
	v_mfma_f32_16x16x32_bf16 v[100:103], v[100:103], v[144:147], 0
	v_mfma_f32_16x16x32_bf16 v[96:99], v[96:99], v[144:147], 0
	v_mfma_f32_16x16x32_bf16 v[88:91], v[108:111], v[136:139], v[88:91]
	s_waitcnt lgkmcnt(12)
	v_mfma_f32_16x16x32_bf16 v[92:95], v[116:119], v[136:139], v[92:95]
	s_waitcnt lgkmcnt(8)
	v_mfma_f32_16x16x32_bf16 v[100:103], v[132:135], v[136:139], v[100:103]
	v_mfma_f32_16x16x32_bf16 v[96:99], v[128:131], v[136:139], v[96:99]
	s_waitcnt lgkmcnt(6)
	v_mfma_f32_16x16x32_bf16 v[88:91], v[148:151], v[124:127], v[88:91]
	s_waitcnt lgkmcnt(4)
	v_mfma_f32_16x16x32_bf16 v[92:95], v[152:155], v[124:127], v[92:95]
	s_waitcnt lgkmcnt(0)
	v_mfma_f32_16x16x32_bf16 v[100:103], v[160:163], v[124:127], v[100:103]
	v_mfma_f32_16x16x32_bf16 v[96:99], v[156:159], v[124:127], v[96:99]
	ds_read_b64 v[108:109], v141 offset:12288
	ds_read_b64 v[110:111], v141 offset:14336
	ds_read_b64 v[116:117], v141 offset:12544
	ds_read_b64 v[118:119], v141 offset:14592
	ds_read_b64 v[124:125], v141 offset:12800
	ds_read_b64 v[126:127], v141 offset:14848
	ds_read_b64 v[128:129], v141 offset:13056
	ds_read_b64 v[130:131], v141 offset:15104
	ds_read_b64 v[132:133], v141 offset:16384
	ds_read_b64 v[134:135], v141 offset:18432
	ds_read_b64 v[136:137], v141 offset:16640
	ds_read_b64 v[138:139], v141 offset:18688
	ds_read_b64 v[142:143], v141 offset:16896
	ds_read_b64 v[144:145], v141 offset:18944
	ds_read_b64 v[146:147], v141 offset:17152
	ds_read_b64 v[148:149], v141 offset:19200
	ds_read_b64 v[150:151], v141 offset:20480
	ds_read_b64 v[152:153], v141 offset:22528
	ds_read_b64 v[154:155], v141 offset:20736
	ds_read_b64 v[156:157], v141 offset:22784
	ds_read_b64 v[158:159], v141 offset:20992
	ds_read_b64 v[160:161], v141 offset:23040
	ds_read_b64 v[222:223], v141 offset:21248
	ds_read_b64 v[224:225], v141 offset:23296
	s_waitcnt lgkmcnt(14)
	v_mfma_f32_16x16x32_bf16 v[88:91], v[108:111], v[120:123], v[88:91]
	v_mfma_f32_16x16x32_bf16 v[92:95], v[116:119], v[120:123], v[92:95]
	v_mfma_f32_16x16x32_bf16 v[100:103], v[128:131], v[120:123], v[100:103]
	v_mfma_f32_16x16x32_bf16 v[96:99], v[124:127], v[120:123], v[96:99]
	v_mfma_f32_16x16x32_bf16 v[88:91], v[132:135], v[112:115], v[88:91]
	s_waitcnt lgkmcnt(12)
	v_mfma_f32_16x16x32_bf16 v[92:95], v[136:139], v[112:115], v[92:95]
	s_waitcnt lgkmcnt(8)
	v_mfma_f32_16x16x32_bf16 v[100:103], v[146:149], v[112:115], v[100:103]
	v_mfma_f32_16x16x32_bf16 v[96:99], v[142:145], v[112:115], v[96:99]
	s_waitcnt lgkmcnt(6)
	v_mfma_f32_16x16x32_bf16 v[88:91], v[150:153], v[104:107], v[88:91]
	s_waitcnt lgkmcnt(4)
	v_mfma_f32_16x16x32_bf16 v[92:95], v[154:157], v[104:107], v[92:95]
	s_waitcnt lgkmcnt(0)
	v_mfma_f32_16x16x32_bf16 v[100:103], v[222:225], v[104:107], v[100:103]
	v_mfma_f32_16x16x32_bf16 v[96:99], v[158:161], v[104:107], v[96:99]
	ds_read_b64 v[104:105], v141 offset:24576
	ds_read_b64 v[106:107], v141 offset:26624
	ds_read_b64 v[108:109], v141 offset:24832
	ds_read_b64 v[110:111], v141 offset:26880
	ds_read_b64 v[112:113], v141 offset:25088
	ds_read_b64 v[114:115], v141 offset:27136
	ds_read_b64 v[116:117], v141 offset:25344
	ds_read_b64 v[118:119], v141 offset:27392
	ds_read_b64 v[120:121], v141 offset:28672
	ds_read_b64 v[122:123], v141 offset:30720
	ds_read_b64 v[124:125], v141 offset:28928
	ds_read_b64 v[126:127], v141 offset:30976
	ds_read_b64 v[128:129], v141 offset:29184
	ds_read_b64 v[130:131], v141 offset:31232
	ds_read_b64 v[132:133], v141 offset:29440
	ds_read_b64 v[134:135], v141 offset:31488
	ds_read_b64 v[136:137], v141 offset:32768
	ds_read_b64 v[138:139], v141 offset:34816
	ds_read_b64 v[142:143], v141 offset:33024
	ds_read_b64 v[144:145], v141 offset:35072
	ds_read_b64 v[146:147], v141 offset:33280
	ds_read_b64 v[148:149], v141 offset:35328
	ds_read_b64 v[150:151], v141 offset:33536
	ds_read_b64 v[152:153], v141 offset:35584
	s_waitcnt lgkmcnt(14)
	v_mfma_f32_16x16x32_bf16 v[88:91], v[104:107], v[64:67], v[88:91]
	v_mfma_f32_16x16x32_bf16 v[92:95], v[108:111], v[64:67], v[92:95]
	v_mfma_f32_16x16x32_bf16 v[96:99], v[112:115], v[64:67], v[96:99]
	v_mfma_f32_16x16x32_bf16 v[64:67], v[116:119], v[64:67], v[100:103]
	v_mfma_f32_16x16x32_bf16 v[88:91], v[120:123], v[68:71], v[88:91]
	s_waitcnt lgkmcnt(12)
	v_mfma_f32_16x16x32_bf16 v[92:95], v[124:127], v[68:71], v[92:95]
	s_waitcnt lgkmcnt(10)
	v_mfma_f32_16x16x32_bf16 v[96:99], v[128:131], v[68:71], v[96:99]
	s_waitcnt lgkmcnt(8)
	v_mfma_f32_16x16x32_bf16 v[64:67], v[132:135], v[68:71], v[64:67]
	s_waitcnt lgkmcnt(6)
	v_mfma_f32_16x16x32_bf16 v[104:107], v[136:139], v[60:63], v[88:91]
	s_waitcnt lgkmcnt(4)
	v_mfma_f32_16x16x32_bf16 v[100:103], v[142:145], v[60:63], v[92:95]
	s_waitcnt lgkmcnt(2)
	v_mfma_f32_16x16x32_bf16 v[92:95], v[146:149], v[60:63], v[96:99]
	s_waitcnt lgkmcnt(0)
	v_mfma_f32_16x16x32_bf16 v[88:91], v[150:153], v[60:63], v[64:67]

; __device__ __forceinline__ unsigned xb_ld(unsigned* p)              { return __hip_atomic_load(p, __ATOMIC_RELAXED, __HIP_MEMORY_SCOPE_AGENT); }
; __device__ __forceinline__ void xcd_barrier_complete(unsigned* bar, unsigned x, unsigned& nloc, unsigned& nx) {
;     const unsigned G = gridDim.x * gridDim.y * gridDim.z;
;     unsigned sum, cnt, mine, sp = 0u;
;     for (;;) {
;         sum = 0u; cnt = 0u; mine = 0u;
; #pragma unroll
;         for (unsigned j = 0; j < 16; ++j) { const unsigned c = xb_ld(&bar[XB_XCNT(j)]); sum += c; cnt += (c > 0u) ? 1u : 0u; mine = (j == x) ? c : mine; }
; __device__ __forceinline__ void xcd_barrier(const XcdBarrier& b) {
;     asm volatile("s_waitcnt vmcnt(0)" ::: "memory");
;     __syncthreads();
;     if (threadIdx.x == 0) {
;         unsigned* bar = b.bar;
;         __builtin_amdgcn_s_waitcnt(0);
;         unsigned nloc = b.st[0], nx = b.st[1];
;         if (nloc == 0u) { xcd_barrier_complete(bar, b.x, nloc, nx); b.st[0] = nloc; b.st[1] = nx; }
.LBB0_427:
	s_setprio 0
	s_cmp_gt_i32 s67, 3
	s_cselect_b64 s[0:1], -1, 0
	s_and_b64 s[4:5], s[72:73], s[0:1]
	s_andn2_b64 vcc, exec, s[4:5]
	s_cbranch_vccnz .LBB0_481
	s_getreg_b32 s3, hwreg(HW_REG_XCC_ID, 0, 4)
	s_waitcnt vmcnt(0)
	s_waitcnt vmcnt(0) lgkmcnt(0)
	s_barrier
	s_and_saveexec_b64 s[4:5], s[94:95]
	s_cbranch_execz .LBB0_480
	s_add_i32 s6, 0, 0x25fc0
	v_mov_b32_e32 v0, s6
	s_waitcnt vmcnt(0) expcnt(0) lgkmcnt(0)
	ds_read_b32 v2, v0
	s_add_i32 s6, 0, 0x25fc4
	v_mov_b32_e32 v0, s6
	ds_read_b32 v0, v0
	s_and_b32 s3, s3, 15
	s_waitcnt lgkmcnt(1)
	v_cmp_ne_u32_e32 vcc, 0, v2
	s_cbranch_vccnz .LBB0_444
	s_load_dwordx2 s[10:11], s[74:75], 0x80
	s_load_dword s9, s[74:75], 0x88
	s_add_u32 s6, s64, 0xaf0200
	s_addc_u32 s7, s65, 0
	s_add_u32 s8, s64, 0xaf0400
	s_waitcnt lgkmcnt(0)
	s_mul_i32 s33, s11, s10
	s_mul_i32 s33, s33, s9
	s_addc_u32 s9, s65, 0
	s_add_u32 s10, s64, 0xaf0500
	s_addc_u32 s11, s65, 0
	s_add_u32 s12, s64, 0xaf0600
	s_addc_u32 s13, s65, 0
	s_add_u32 s14, s64, 0xaf0700
	s_addc_u32 s15, s65, 0
	s_add_u32 s16, s64, 0xaf0800
	s_addc_u32 s17, s65, 0
	s_add_u32 s18, s64, 0xaf0900
	s_addc_u32 s19, s65, 0
	s_add_u32 s20, s64, 0xaf0a00
	s_addc_u32 s21, s65, 0
	s_add_u32 s22, s64, 0xaf0b00
	s_addc_u32 s23, s65, 0
	s_add_u32 s24, s64, 0xaf0c00
	s_addc_u32 s25, s65, 0
	s_add_u32 s26, s64, 0xaf0d00
	s_addc_u32 s27, s65, 0
	s_add_u32 s28, s64, 0xaf0e00
	s_addc_u32 s29, s65, 0
	s_add_u32 s30, s64, 0xaf0f00
	s_addc_u32 s31, s65, 0
	s_add_u32 s34, s64, 0xaf1000
	s_addc_u32 s35, s65, 0
	s_add_u32 s36, s64, 0xaf1100
	s_addc_u32 s37, s65, 0
	s_add_u32 s38, s64, 0xaf1200
	s_addc_u32 s39, s65, 0
	s_add_u32 s40, s64, 0xaf1300
	s_addc_u32 s41, s65, 0
	s_mov_b32 s48, 1
	v_mov_b32_e32 v16, 0
	s_branch .LBB0_432
